# FFN-in epilogue: gelu constants merged (g*(c1+c2 g^2) form, 3 fewer VALU per output)
# baseline (speedup 1.0000x reference)
.LBB0_993:
	v_mov_b32_e32 v134, v192
	v_mov_b32_e32 v135, v192
	s_lshl_b32 s6, s30, 7
	v_bfe_i32 v128, v135, 7, 1
	v_and_b32_e32 v128, 0xb00, v128
	v_add_u32_e32 v128, s6, v128
	s_movk_i32 s7, 0x7f
	v_and_or_b32 v128, v135, s7, v128
	v_ashrrev_i32_e32 v129, 31, v128
	v_lshl_add_u64 v[130:131], v[128:129], 2, s[20:21]
	v_ashrrev_i32_e32 v129, 8, v135
	v_mad_i32_i24 v132, v129, s79, v128
	v_ashrrev_i32_e32 v133, 31, v132
	v_lshl_add_u64 v[132:133], v[132:133], 2, s[18:19]
	v_cmp_gt_i32_e32 vcc, 3, v129
	v_add_u32_e32 v129, 0x200, v135
	v_lshl_add_u32 v135, v135, 2, 0
	v_cndmask_b32_e32 v133, v131, v133, vcc
	v_cndmask_b32_e32 v132, v130, v132, vcc
	global_load_dword v132, v[132:133], off
	v_ashrrev_i32_e32 v133, 8, v129
	v_mad_i32_i24 v128, v133, s79, v128
	v_ashrrev_i32_e32 v129, 31, v128
	v_lshl_add_u64 v[128:129], v[128:129], 2, s[18:19]
	v_cmp_gt_i32_e32 vcc, 3, v133
	s_mulk_i32 s0, 0xfc
	v_lshrrev_b32_e32 v136, 1, v134
	v_cndmask_b32_e32 v129, v131, v129, vcc
	v_cndmask_b32_e32 v128, v130, v128, vcc
	global_load_dword v133, v[128:129], off
	v_add_u32_e32 v135, 0x20000, v135
	s_add_i32 s0, s66, s0
	v_and_b32_e32 v219, 15, v134
	v_and_or_b32 v134, v136, 24, s62
	v_add_u32_e32 v218, s0, v219
	v_or_b32_e32 v136, 0x80, v134
	v_or_b32_e32 v137, 4, v134
	v_or_b32_e32 v138, 0x84, v134
	v_cmp_lt_u32_e32 vcc, 1, v219
	v_or_b32_e32 v188, s6, v134
	v_cmp_gt_i32_e64 s[6:7], s58, v218
	v_lshlrev_b32_e32 v172, 2, v134
	v_lshlrev_b32_e32 v210, 2, v137
	v_lshlrev_b32_e32 v206, 2, v136
	v_lshlrev_b32_e32 v212, 2, v138
	v_ashrrev_i32_e32 v189, 31, v188
	s_and_b64 s[6:7], vcc, s[6:7]
	s_waitcnt vmcnt(0)
	ds_write2st64_b32 v135, v132, v133 offset1:8
	s_waitcnt lgkmcnt(0)
	s_barrier
	v_add_u32_e32 v203, 0x20000, v172
	ds_read_b128 v[128:131], v203 offset:0
	ds_read_b128 v[132:135], v203 offset:512
	ds_read_b128 v[136:139], v203 offset:16
	ds_read_b128 v[140:143], v203 offset:528
	ds_read_b128 v[144:147], v203 offset:1024
	ds_read_b128 v[148:151], v203 offset:1536
	ds_read_b128 v[152:155], v203 offset:1040
	ds_read_b128 v[156:159], v203 offset:1552
	s_waitcnt lgkmcnt(0)
	ds_read_b128 v[160:163], v203 offset:2048
	ds_read_b128 v[164:167], v203 offset:2560
	ds_read_b128 v[168:171], v203 offset:2064
	ds_read_b128 v[204:207], v203 offset:2576
	ds_read_b128 v[208:211], v203 offset:3072
	ds_read_b128 v[212:215], v203 offset:3584
	ds_read_b128 v[220:223], v203 offset:3088
	ds_read_b128 v[224:227], v203 offset:3600
	v_lshl_add_u64 v[190:191], v[188:189], 1, s[16:17]
	s_waitcnt lgkmcnt(0)
	s_add_i32 s6, s0, 2079
	s_mul_hi_u32 s7, s6, s59
	s_lshr_b32 s7, s7, 7
	s_mulk_i32 s7, 0x810
	s_sub_i32 s6, s6, s7
	s_cmp_lt_u32 s6, 17
	s_cbranch_scc1 .Lffn1e_slow0
	v_mov_b32_dpp v228, v124 row_shr:1 row_mask:0xf bank_mask:0xf bound_ctrl:1
	v_mov_b32_dpp v229, v124 row_shr:2 row_mask:0xf bank_mask:0xf bound_ctrl:1
	v_mov_b32_dpp v230, v125 row_shr:1 row_mask:0xf bank_mask:0xf bound_ctrl:1
	v_mov_b32_dpp v231, v125 row_shr:2 row_mask:0xf bank_mask:0xf bound_ctrl:1
	v_mov_b32_dpp v232, v126 row_shr:1 row_mask:0xf bank_mask:0xf bound_ctrl:1
	v_mov_b32_dpp v233, v126 row_shr:2 row_mask:0xf bank_mask:0xf bound_ctrl:1
	v_mov_b32_dpp v234, v127 row_shr:1 row_mask:0xf bank_mask:0xf bound_ctrl:1
	v_mov_b32_dpp v235, v127 row_shr:2 row_mask:0xf bank_mask:0xf bound_ctrl:1
	v_fma_f32 v236, v229, v128, v208
	v_fma_f32 v237, v231, v129, v209
	v_fma_f32 v238, v233, v130, v210
	v_fma_f32 v239, v235, v131, v211
	v_fmac_f32_e32 v236, v228, v144
	v_fmac_f32_e32 v237, v230, v145
	v_fmac_f32_e32 v238, v232, v146
	v_fmac_f32_e32 v239, v234, v147
	v_fmac_f32_e32 v236, v124, v160
	v_fmac_f32_e32 v237, v125, v161
	v_fmac_f32_e32 v238, v126, v162
	v_fmac_f32_e32 v239, v127, v163
	v_mov_b32_dpp v228, v116 row_shr:1 row_mask:0xf bank_mask:0xf bound_ctrl:1
	v_mov_b32_dpp v229, v116 row_shr:2 row_mask:0xf bank_mask:0xf bound_ctrl:1
	v_mov_b32_dpp v230, v117 row_shr:1 row_mask:0xf bank_mask:0xf bound_ctrl:1
	v_mov_b32_dpp v231, v117 row_shr:2 row_mask:0xf bank_mask:0xf bound_ctrl:1
	v_mov_b32_dpp v232, v118 row_shr:1 row_mask:0xf bank_mask:0xf bound_ctrl:1
	v_mov_b32_dpp v233, v118 row_shr:2 row_mask:0xf bank_mask:0xf bound_ctrl:1
	v_mov_b32_dpp v234, v119 row_shr:1 row_mask:0xf bank_mask:0xf bound_ctrl:1
	v_mov_b32_dpp v235, v119 row_shr:2 row_mask:0xf bank_mask:0xf bound_ctrl:1
	v_fma_f32 v240, v229, v132, v212
	v_fma_f32 v241, v231, v133, v213
	v_fma_f32 v242, v233, v134, v214
	v_fma_f32 v243, v235, v135, v215
	v_fmac_f32_e32 v240, v228, v148
	v_fmac_f32_e32 v241, v230, v149
	v_fmac_f32_e32 v242, v232, v150
	v_fmac_f32_e32 v243, v234, v151
	v_fmac_f32_e32 v240, v116, v164
	v_fmac_f32_e32 v241, v117, v165
	v_fmac_f32_e32 v242, v118, v166
	v_fmac_f32_e32 v243, v119, v167
	v_mov_b32_e32 v228, 0xbdd2d3e8
	v_mul_f32_e32 v244, v236, v236
	v_mul_f32_e32 v245, v237, v237
	v_mul_f32_e32 v246, v238, v238
	v_mul_f32_e32 v247, v239, v239
	v_fmaak_f32 v244, v244, v228, 0xc0135761
	v_fmaak_f32 v245, v245, v228, 0xc0135761
	v_fmaak_f32 v246, v246, v228, 0xc0135761
	v_fmaak_f32 v247, v247, v228, 0xc0135761
	v_mul_f32_e32 v244, v236, v244
	v_mul_f32_e32 v245, v237, v245
	v_mul_f32_e32 v246, v238, v246
	v_mul_f32_e32 v247, v239, v247
	v_exp_f32_e32 v244, v244
	v_exp_f32_e32 v245, v245
	v_exp_f32_e32 v246, v246
	v_exp_f32_e32 v247, v247
	v_add_f32_e32 v244, 1.0, v244
	v_add_f32_e32 v245, 1.0, v245
	v_add_f32_e32 v246, 1.0, v246
	v_add_f32_e32 v247, 1.0, v247
	v_rcp_f32_e32 v244, v244
	v_rcp_f32_e32 v245, v245
	v_rcp_f32_e32 v246, v246
	v_rcp_f32_e32 v247, v247
	v_mul_f32_e32 v244, v236, v244
	v_mul_f32_e32 v245, v237, v245
	v_mul_f32_e32 v246, v238, v246
	v_mul_f32_e32 v247, v239, v247
	v_mul_f32_e32 v248, v240, v244
	v_mul_f32_e32 v249, v241, v245
	v_mul_f32_e32 v250, v242, v246
	v_mul_f32_e32 v251, v243, v247
	v_mov_b32_dpp v228, v120 row_shr:1 row_mask:0xf bank_mask:0xf bound_ctrl:1
	v_mov_b32_dpp v229, v120 row_shr:2 row_mask:0xf bank_mask:0xf bound_ctrl:1
	v_mov_b32_dpp v230, v121 row_shr:1 row_mask:0xf bank_mask:0xf bound_ctrl:1
	v_mov_b32_dpp v231, v121 row_shr:2 row_mask:0xf bank_mask:0xf bound_ctrl:1
	v_mov_b32_dpp v232, v122 row_shr:1 row_mask:0xf bank_mask:0xf bound_ctrl:1
	v_mov_b32_dpp v233, v122 row_shr:2 row_mask:0xf bank_mask:0xf bound_ctrl:1
	v_mov_b32_dpp v234, v123 row_shr:1 row_mask:0xf bank_mask:0xf bound_ctrl:1
	v_mov_b32_dpp v235, v123 row_shr:2 row_mask:0xf bank_mask:0xf bound_ctrl:1
	v_fma_f32 v236, v229, v136, v220
	v_fma_f32 v237, v231, v137, v221
	v_fma_f32 v238, v233, v138, v222
	v_fma_f32 v239, v235, v139, v223
	v_fmac_f32_e32 v236, v228, v152
	v_fmac_f32_e32 v237, v230, v153
	v_fmac_f32_e32 v238, v232, v154
	v_fmac_f32_e32 v239, v234, v155
	v_fmac_f32_e32 v236, v120, v168
	v_fmac_f32_e32 v237, v121, v169
	v_fmac_f32_e32 v238, v122, v170
	v_fmac_f32_e32 v239, v123, v171
	v_mov_b32_dpp v228, v112 row_shr:1 row_mask:0xf bank_mask:0xf bound_ctrl:1
	v_mov_b32_dpp v229, v112 row_shr:2 row_mask:0xf bank_mask:0xf bound_ctrl:1
	v_mov_b32_dpp v230, v113 row_shr:1 row_mask:0xf bank_mask:0xf bound_ctrl:1
	v_mov_b32_dpp v231, v113 row_shr:2 row_mask:0xf bank_mask:0xf bound_ctrl:1
	v_mov_b32_dpp v232, v114 row_shr:1 row_mask:0xf bank_mask:0xf bound_ctrl:1
	v_mov_b32_dpp v233, v114 row_shr:2 row_mask:0xf bank_mask:0xf bound_ctrl:1
	v_mov_b32_dpp v234, v115 row_shr:1 row_mask:0xf bank_mask:0xf bound_ctrl:1
	v_mov_b32_dpp v235, v115 row_shr:2 row_mask:0xf bank_mask:0xf bound_ctrl:1
	v_fma_f32 v240, v229, v140, v224
	v_fma_f32 v241, v231, v141, v225
	v_fma_f32 v242, v233, v142, v226
	v_fma_f32 v243, v235, v143, v227
	v_fmac_f32_e32 v240, v228, v156
	v_fmac_f32_e32 v241, v230, v157
	v_fmac_f32_e32 v242, v232, v158
	v_fmac_f32_e32 v243, v234, v159
	v_fmac_f32_e32 v240, v112, v204
	v_fmac_f32_e32 v241, v113, v205
	v_fmac_f32_e32 v242, v114, v206
	v_fmac_f32_e32 v243, v115, v207
	v_mov_b32_e32 v228, 0xbdd2d3e8
	v_mul_f32_e32 v244, v236, v236
	v_mul_f32_e32 v245, v237, v237
	v_mul_f32_e32 v246, v238, v238
	v_mul_f32_e32 v247, v239, v239
	v_fmaak_f32 v244, v244, v228, 0xc0135761
	v_fmaak_f32 v245, v245, v228, 0xc0135761
	v_fmaak_f32 v246, v246, v228, 0xc0135761
	v_fmaak_f32 v247, v247, v228, 0xc0135761
	v_mul_f32_e32 v244, v236, v244
	v_mul_f32_e32 v245, v237, v245
	v_mul_f32_e32 v246, v238, v246
	v_mul_f32_e32 v247, v239, v247
	v_exp_f32_e32 v244, v244
	v_exp_f32_e32 v245, v245
	v_exp_f32_e32 v246, v246
	v_exp_f32_e32 v247, v247
	v_add_f32_e32 v244, 1.0, v244
	v_add_f32_e32 v245, 1.0, v245
	v_add_f32_e32 v246, 1.0, v246
	v_add_f32_e32 v247, 1.0, v247
	v_rcp_f32_e32 v244, v244
	v_rcp_f32_e32 v245, v245
	v_rcp_f32_e32 v246, v246
	v_rcp_f32_e32 v247, v247
	v_mul_f32_e32 v244, v236, v244
	v_mul_f32_e32 v245, v237, v245
	v_mul_f32_e32 v246, v238, v246
	v_mul_f32_e32 v247, v239, v247
	v_mul_f32_e32 v174, v240, v244
	v_mul_f32_e32 v175, v241, v245
	v_mul_f32_e32 v176, v242, v246
	v_mul_f32_e32 v177, v243, v247
	v_cvt_pk_bf16_f32 v180, v248, v249
	v_cvt_pk_bf16_f32 v181, v250, v251
	v_cvt_pk_bf16_f32 v182, v174, v175
	v_cvt_pk_bf16_f32 v183, v176, v177
.Lffn1e_store0:
	v_mad_i64_i32 v[216:217], vcc, v218, s79, v[190:191]
	v_cmp_lt_u32_e64 s[8:9], 1, v219
	v_cmp_gt_i32_e32 vcc, s58, v218
	s_nop 1
	s_and_b64 vcc, vcc, s[8:9]
	s_and_saveexec_b64 s[10:11], vcc
	global_store_dwordx4 v[216:217], v[180:183], off sc1
	s_mov_b64 exec, s[10:11]
	s_add_i32 s6, s0, 2095
	s_mul_hi_u32 s7, s6, s59
	s_lshr_b32 s7, s7, 7
	s_mulk_i32 s7, 0x810
	s_sub_i32 s6, s6, s7
	s_cmp_lt_u32 s6, 17
	s_cbranch_scc1 .Lffn1e_slow1
	v_mov_b32_dpp v228, v124 row_ror:1 row_mask:0xf bank_mask:0xf
	v_mov_b32_dpp v229, v124 row_ror:2 row_mask:0xf bank_mask:0xf
	v_mov_b32_dpp v230, v125 row_ror:1 row_mask:0xf bank_mask:0xf
	v_mov_b32_dpp v231, v125 row_ror:2 row_mask:0xf bank_mask:0xf
	v_mov_b32_dpp v232, v126 row_ror:1 row_mask:0xf bank_mask:0xf
	v_mov_b32_dpp v233, v126 row_ror:2 row_mask:0xf bank_mask:0xf
	v_mov_b32_dpp v234, v127 row_ror:1 row_mask:0xf bank_mask:0xf
	v_mov_b32_dpp v235, v127 row_ror:2 row_mask:0xf bank_mask:0xf
	v_mov_b32_dpp v228, v108 row_shr:1 row_mask:0xf bank_mask:0xf
	v_mov_b32_dpp v229, v108 row_shr:2 row_mask:0xf bank_mask:0xf
	v_mov_b32_dpp v230, v109 row_shr:1 row_mask:0xf bank_mask:0xf
	v_mov_b32_dpp v231, v109 row_shr:2 row_mask:0xf bank_mask:0xf
	v_mov_b32_dpp v232, v110 row_shr:1 row_mask:0xf bank_mask:0xf
	v_mov_b32_dpp v233, v110 row_shr:2 row_mask:0xf bank_mask:0xf
	v_mov_b32_dpp v234, v111 row_shr:1 row_mask:0xf bank_mask:0xf
	v_mov_b32_dpp v235, v111 row_shr:2 row_mask:0xf bank_mask:0xf
	v_fma_f32 v236, v229, v128, v208
	v_fma_f32 v237, v231, v129, v209
	v_fma_f32 v238, v233, v130, v210
	v_fma_f32 v239, v235, v131, v211
	v_fmac_f32_e32 v236, v228, v144
	v_fmac_f32_e32 v237, v230, v145
	v_fmac_f32_e32 v238, v232, v146
	v_fmac_f32_e32 v239, v234, v147
	v_fmac_f32_e32 v236, v108, v160
	v_fmac_f32_e32 v237, v109, v161
	v_fmac_f32_e32 v238, v110, v162
	v_fmac_f32_e32 v239, v111, v163
	v_mov_b32_dpp v228, v116 row_ror:1 row_mask:0xf bank_mask:0xf
	v_mov_b32_dpp v229, v116 row_ror:2 row_mask:0xf bank_mask:0xf
	v_mov_b32_dpp v230, v117 row_ror:1 row_mask:0xf bank_mask:0xf
	v_mov_b32_dpp v231, v117 row_ror:2 row_mask:0xf bank_mask:0xf
	v_mov_b32_dpp v232, v118 row_ror:1 row_mask:0xf bank_mask:0xf
	v_mov_b32_dpp v233, v118 row_ror:2 row_mask:0xf bank_mask:0xf
	v_mov_b32_dpp v234, v119 row_ror:1 row_mask:0xf bank_mask:0xf
	v_mov_b32_dpp v235, v119 row_ror:2 row_mask:0xf bank_mask:0xf
	v_mov_b32_dpp v228, v100 row_shr:1 row_mask:0xf bank_mask:0xf
	v_mov_b32_dpp v229, v100 row_shr:2 row_mask:0xf bank_mask:0xf
	v_mov_b32_dpp v230, v101 row_shr:1 row_mask:0xf bank_mask:0xf
	v_mov_b32_dpp v231, v101 row_shr:2 row_mask:0xf bank_mask:0xf
	v_mov_b32_dpp v232, v102 row_shr:1 row_mask:0xf bank_mask:0xf
	v_mov_b32_dpp v233, v102 row_shr:2 row_mask:0xf bank_mask:0xf
	v_mov_b32_dpp v234, v103 row_shr:1 row_mask:0xf bank_mask:0xf
	v_mov_b32_dpp v235, v103 row_shr:2 row_mask:0xf bank_mask:0xf
	v_fma_f32 v240, v229, v132, v212
	v_fma_f32 v241, v231, v133, v213
	v_fma_f32 v242, v233, v134, v214
	v_fma_f32 v243, v235, v135, v215
	v_fmac_f32_e32 v240, v228, v148
	v_fmac_f32_e32 v241, v230, v149
	v_fmac_f32_e32 v242, v232, v150
	v_fmac_f32_e32 v243, v234, v151
	v_fmac_f32_e32 v240, v100, v164
	v_fmac_f32_e32 v241, v101, v165
	v_fmac_f32_e32 v242, v102, v166
	v_fmac_f32_e32 v243, v103, v167
	v_mov_b32_e32 v228, 0xbdd2d3e8
	v_mul_f32_e32 v244, v236, v236
	v_mul_f32_e32 v245, v237, v237
	v_mul_f32_e32 v246, v238, v238
	v_mul_f32_e32 v247, v239, v239
	v_fmaak_f32 v244, v244, v228, 0xc0135761
	v_fmaak_f32 v245, v245, v228, 0xc0135761
	v_fmaak_f32 v246, v246, v228, 0xc0135761
	v_fmaak_f32 v247, v247, v228, 0xc0135761
	v_mul_f32_e32 v244, v236, v244
	v_mul_f32_e32 v245, v237, v245
	v_mul_f32_e32 v246, v238, v246
	v_mul_f32_e32 v247, v239, v247
	v_exp_f32_e32 v244, v244
	v_exp_f32_e32 v245, v245
	v_exp_f32_e32 v246, v246
	v_exp_f32_e32 v247, v247
	v_add_f32_e32 v244, 1.0, v244
	v_add_f32_e32 v245, 1.0, v245
	v_add_f32_e32 v246, 1.0, v246
	v_add_f32_e32 v247, 1.0, v247
	v_rcp_f32_e32 v244, v244
	v_rcp_f32_e32 v245, v245
	v_rcp_f32_e32 v246, v246
	v_rcp_f32_e32 v247, v247
	v_mul_f32_e32 v244, v236, v244
	v_mul_f32_e32 v245, v237, v245
	v_mul_f32_e32 v246, v238, v246
	v_mul_f32_e32 v247, v239, v247
	v_mul_f32_e32 v248, v240, v244
	v_mul_f32_e32 v249, v241, v245
	v_mul_f32_e32 v250, v242, v246
	v_mul_f32_e32 v251, v243, v247
	v_mov_b32_dpp v228, v120 row_ror:1 row_mask:0xf bank_mask:0xf
	v_mov_b32_dpp v229, v120 row_ror:2 row_mask:0xf bank_mask:0xf
	v_mov_b32_dpp v230, v121 row_ror:1 row_mask:0xf bank_mask:0xf
	v_mov_b32_dpp v231, v121 row_ror:2 row_mask:0xf bank_mask:0xf
	v_mov_b32_dpp v232, v122 row_ror:1 row_mask:0xf bank_mask:0xf
	v_mov_b32_dpp v233, v122 row_ror:2 row_mask:0xf bank_mask:0xf
	v_mov_b32_dpp v234, v123 row_ror:1 row_mask:0xf bank_mask:0xf
	v_mov_b32_dpp v235, v123 row_ror:2 row_mask:0xf bank_mask:0xf
	v_mov_b32_dpp v228, v104 row_shr:1 row_mask:0xf bank_mask:0xf
	v_mov_b32_dpp v229, v104 row_shr:2 row_mask:0xf bank_mask:0xf
	v_mov_b32_dpp v230, v105 row_shr:1 row_mask:0xf bank_mask:0xf
	v_mov_b32_dpp v231, v105 row_shr:2 row_mask:0xf bank_mask:0xf
	v_mov_b32_dpp v232, v106 row_shr:1 row_mask:0xf bank_mask:0xf
	v_mov_b32_dpp v233, v106 row_shr:2 row_mask:0xf bank_mask:0xf
	v_mov_b32_dpp v234, v107 row_shr:1 row_mask:0xf bank_mask:0xf
	v_mov_b32_dpp v235, v107 row_shr:2 row_mask:0xf bank_mask:0xf
	v_fma_f32 v236, v229, v136, v220
	v_fma_f32 v237, v231, v137, v221
	v_fma_f32 v238, v233, v138, v222
	v_fma_f32 v239, v235, v139, v223
	v_fmac_f32_e32 v236, v228, v152
	v_fmac_f32_e32 v237, v230, v153
	v_fmac_f32_e32 v238, v232, v154
	v_fmac_f32_e32 v239, v234, v155
	v_fmac_f32_e32 v236, v104, v168
	v_fmac_f32_e32 v237, v105, v169
	v_fmac_f32_e32 v238, v106, v170
	v_fmac_f32_e32 v239, v107, v171
	v_mov_b32_dpp v228, v112 row_ror:1 row_mask:0xf bank_mask:0xf
	v_mov_b32_dpp v229, v112 row_ror:2 row_mask:0xf bank_mask:0xf
	v_mov_b32_dpp v230, v113 row_ror:1 row_mask:0xf bank_mask:0xf
	v_mov_b32_dpp v231, v113 row_ror:2 row_mask:0xf bank_mask:0xf
	v_mov_b32_dpp v232, v114 row_ror:1 row_mask:0xf bank_mask:0xf
	v_mov_b32_dpp v233, v114 row_ror:2 row_mask:0xf bank_mask:0xf
	v_mov_b32_dpp v234, v115 row_ror:1 row_mask:0xf bank_mask:0xf
	v_mov_b32_dpp v235, v115 row_ror:2 row_mask:0xf bank_mask:0xf
	v_mov_b32_dpp v228, v96 row_shr:1 row_mask:0xf bank_mask:0xf
	v_mov_b32_dpp v229, v96 row_shr:2 row_mask:0xf bank_mask:0xf
	v_mov_b32_dpp v230, v97 row_shr:1 row_mask:0xf bank_mask:0xf
	v_mov_b32_dpp v231, v97 row_shr:2 row_mask:0xf bank_mask:0xf
	v_mov_b32_dpp v232, v98 row_shr:1 row_mask:0xf bank_mask:0xf
	v_mov_b32_dpp v233, v98 row_shr:2 row_mask:0xf bank_mask:0xf
	v_mov_b32_dpp v234, v99 row_shr:1 row_mask:0xf bank_mask:0xf
	v_mov_b32_dpp v235, v99 row_shr:2 row_mask:0xf bank_mask:0xf
	v_fma_f32 v240, v229, v140, v224
	v_fma_f32 v241, v231, v141, v225
	v_fma_f32 v242, v233, v142, v226
	v_fma_f32 v243, v235, v143, v227
	v_fmac_f32_e32 v240, v228, v156
	v_fmac_f32_e32 v241, v230, v157
	v_fmac_f32_e32 v242, v232, v158
	v_fmac_f32_e32 v243, v234, v159
	v_fmac_f32_e32 v240, v96, v204
	v_fmac_f32_e32 v241, v97, v205
	v_fmac_f32_e32 v242, v98, v206
	v_fmac_f32_e32 v243, v99, v207
	v_mov_b32_e32 v228, 0xbdd2d3e8
	v_mul_f32_e32 v244, v236, v236
	v_mul_f32_e32 v245, v237, v237
	v_mul_f32_e32 v246, v238, v238
	v_mul_f32_e32 v247, v239, v239
	v_fmaak_f32 v244, v244, v228, 0xc0135761
	v_fmaak_f32 v245, v245, v228, 0xc0135761
	v_fmaak_f32 v246, v246, v228, 0xc0135761
	v_fmaak_f32 v247, v247, v228, 0xc0135761
	v_mul_f32_e32 v244, v236, v244
	v_mul_f32_e32 v245, v237, v245
	v_mul_f32_e32 v246, v238, v246
	v_mul_f32_e32 v247, v239, v247
	v_exp_f32_e32 v244, v244
	v_exp_f32_e32 v245, v245
	v_exp_f32_e32 v246, v246
	v_exp_f32_e32 v247, v247
	v_add_f32_e32 v244, 1.0, v244
	v_add_f32_e32 v245, 1.0, v245
	v_add_f32_e32 v246, 1.0, v246
	v_add_f32_e32 v247, 1.0, v247
	v_rcp_f32_e32 v244, v244
	v_rcp_f32_e32 v245, v245
	v_rcp_f32_e32 v246, v246
	v_rcp_f32_e32 v247, v247
	v_mul_f32_e32 v244, v236, v244
	v_mul_f32_e32 v245, v237, v245
	v_mul_f32_e32 v246, v238, v246
	v_mul_f32_e32 v247, v239, v247
	v_mul_f32_e32 v174, v240, v244
	v_mul_f32_e32 v175, v241, v245
	v_mul_f32_e32 v176, v242, v246
	v_mul_f32_e32 v177, v243, v247
	v_cvt_pk_bf16_f32 v180, v248, v249
	v_cvt_pk_bf16_f32 v181, v250, v251
	v_cvt_pk_bf16_f32 v182, v174, v175
	v_cvt_pk_bf16_f32 v183, v176, v177
.Lffn1e_store1:
	v_add_u32_e32 v252, 16, v218
	v_mad_i64_i32 v[216:217], vcc, v252, s79, v[190:191]
	v_cmp_gt_i32_e32 vcc, s58, v252
	s_nop 1
	s_and_saveexec_b64 s[10:11], vcc
	global_store_dwordx4 v[216:217], v[180:183], off sc1
	s_mov_b64 exec, s[10:11]
	s_add_i32 s6, s0, 2111
	s_mul_hi_u32 s7, s6, s59
	s_lshr_b32 s7, s7, 7
	s_mulk_i32 s7, 0x810
	s_sub_i32 s6, s6, s7
	s_cmp_lt_u32 s6, 17
	s_cbranch_scc1 .Lffn1e_slow2
	v_mov_b32_dpp v228, v108 row_ror:1 row_mask:0xf bank_mask:0xf
	v_mov_b32_dpp v229, v108 row_ror:2 row_mask:0xf bank_mask:0xf
	v_mov_b32_dpp v230, v109 row_ror:1 row_mask:0xf bank_mask:0xf
	v_mov_b32_dpp v231, v109 row_ror:2 row_mask:0xf bank_mask:0xf
	v_mov_b32_dpp v232, v110 row_ror:1 row_mask:0xf bank_mask:0xf
	v_mov_b32_dpp v233, v110 row_ror:2 row_mask:0xf bank_mask:0xf
	v_mov_b32_dpp v234, v111 row_ror:1 row_mask:0xf bank_mask:0xf
	v_mov_b32_dpp v235, v111 row_ror:2 row_mask:0xf bank_mask:0xf
	v_mov_b32_dpp v228, v92 row_shr:1 row_mask:0xf bank_mask:0xf
	v_mov_b32_dpp v229, v92 row_shr:2 row_mask:0xf bank_mask:0xf
	v_mov_b32_dpp v230, v93 row_shr:1 row_mask:0xf bank_mask:0xf
	v_mov_b32_dpp v231, v93 row_shr:2 row_mask:0xf bank_mask:0xf
	v_mov_b32_dpp v232, v94 row_shr:1 row_mask:0xf bank_mask:0xf
	v_mov_b32_dpp v233, v94 row_shr:2 row_mask:0xf bank_mask:0xf
	v_mov_b32_dpp v234, v95 row_shr:1 row_mask:0xf bank_mask:0xf
	v_mov_b32_dpp v235, v95 row_shr:2 row_mask:0xf bank_mask:0xf
	v_fma_f32 v236, v229, v128, v208
	v_fma_f32 v237, v231, v129, v209
	v_fma_f32 v238, v233, v130, v210
	v_fma_f32 v239, v235, v131, v211
	v_fmac_f32_e32 v236, v228, v144
	v_fmac_f32_e32 v237, v230, v145
	v_fmac_f32_e32 v238, v232, v146
	v_fmac_f32_e32 v239, v234, v147
	v_fmac_f32_e32 v236, v92, v160
	v_fmac_f32_e32 v237, v93, v161
	v_fmac_f32_e32 v238, v94, v162
	v_fmac_f32_e32 v239, v95, v163
	v_mov_b32_dpp v228, v100 row_ror:1 row_mask:0xf bank_mask:0xf
	v_mov_b32_dpp v229, v100 row_ror:2 row_mask:0xf bank_mask:0xf
	v_mov_b32_dpp v230, v101 row_ror:1 row_mask:0xf bank_mask:0xf
	v_mov_b32_dpp v231, v101 row_ror:2 row_mask:0xf bank_mask:0xf
	v_mov_b32_dpp v232, v102 row_ror:1 row_mask:0xf bank_mask:0xf
	v_mov_b32_dpp v233, v102 row_ror:2 row_mask:0xf bank_mask:0xf
	v_mov_b32_dpp v234, v103 row_ror:1 row_mask:0xf bank_mask:0xf
	v_mov_b32_dpp v235, v103 row_ror:2 row_mask:0xf bank_mask:0xf
	v_mov_b32_dpp v228, v84 row_shr:1 row_mask:0xf bank_mask:0xf
	v_mov_b32_dpp v229, v84 row_shr:2 row_mask:0xf bank_mask:0xf
	v_mov_b32_dpp v230, v85 row_shr:1 row_mask:0xf bank_mask:0xf
	v_mov_b32_dpp v231, v85 row_shr:2 row_mask:0xf bank_mask:0xf
	v_mov_b32_dpp v232, v86 row_shr:1 row_mask:0xf bank_mask:0xf
	v_mov_b32_dpp v233, v86 row_shr:2 row_mask:0xf bank_mask:0xf
	v_mov_b32_dpp v234, v87 row_shr:1 row_mask:0xf bank_mask:0xf
	v_mov_b32_dpp v235, v87 row_shr:2 row_mask:0xf bank_mask:0xf
	v_fma_f32 v240, v229, v132, v212
	v_fma_f32 v241, v231, v133, v213
	v_fma_f32 v242, v233, v134, v214
	v_fma_f32 v243, v235, v135, v215
	v_fmac_f32_e32 v240, v228, v148
	v_fmac_f32_e32 v241, v230, v149
	v_fmac_f32_e32 v242, v232, v150
	v_fmac_f32_e32 v243, v234, v151
	v_fmac_f32_e32 v240, v84, v164
	v_fmac_f32_e32 v241, v85, v165
	v_fmac_f32_e32 v242, v86, v166
	v_fmac_f32_e32 v243, v87, v167
	v_mov_b32_e32 v228, 0xbdd2d3e8
	v_mul_f32_e32 v244, v236, v236
	v_mul_f32_e32 v245, v237, v237
	v_mul_f32_e32 v246, v238, v238
	v_mul_f32_e32 v247, v239, v239
	v_fmaak_f32 v244, v244, v228, 0xc0135761
	v_fmaak_f32 v245, v245, v228, 0xc0135761
	v_fmaak_f32 v246, v246, v228, 0xc0135761
	v_fmaak_f32 v247, v247, v228, 0xc0135761
	v_mul_f32_e32 v244, v236, v244
	v_mul_f32_e32 v245, v237, v245
	v_mul_f32_e32 v246, v238, v246
	v_mul_f32_e32 v247, v239, v247
	v_exp_f32_e32 v244, v244
	v_exp_f32_e32 v245, v245
	v_exp_f32_e32 v246, v246
	v_exp_f32_e32 v247, v247
	v_add_f32_e32 v244, 1.0, v244
	v_add_f32_e32 v245, 1.0, v245
	v_add_f32_e32 v246, 1.0, v246
	v_add_f32_e32 v247, 1.0, v247
	v_rcp_f32_e32 v244, v244
	v_rcp_f32_e32 v245, v245
	v_rcp_f32_e32 v246, v246
	v_rcp_f32_e32 v247, v247
	v_mul_f32_e32 v244, v236, v244
	v_mul_f32_e32 v245, v237, v245
	v_mul_f32_e32 v246, v238, v246
	v_mul_f32_e32 v247, v239, v247
	v_mul_f32_e32 v248, v240, v244
	v_mul_f32_e32 v249, v241, v245
	v_mul_f32_e32 v250, v242, v246
	v_mul_f32_e32 v251, v243, v247
	v_mov_b32_dpp v228, v104 row_ror:1 row_mask:0xf bank_mask:0xf
	v_mov_b32_dpp v229, v104 row_ror:2 row_mask:0xf bank_mask:0xf
	v_mov_b32_dpp v230, v105 row_ror:1 row_mask:0xf bank_mask:0xf
	v_mov_b32_dpp v231, v105 row_ror:2 row_mask:0xf bank_mask:0xf
	v_mov_b32_dpp v232, v106 row_ror:1 row_mask:0xf bank_mask:0xf
	v_mov_b32_dpp v233, v106 row_ror:2 row_mask:0xf bank_mask:0xf
	v_mov_b32_dpp v234, v107 row_ror:1 row_mask:0xf bank_mask:0xf
	v_mov_b32_dpp v235, v107 row_ror:2 row_mask:0xf bank_mask:0xf
	v_mov_b32_dpp v228, v88 row_shr:1 row_mask:0xf bank_mask:0xf
	v_mov_b32_dpp v229, v88 row_shr:2 row_mask:0xf bank_mask:0xf
	v_mov_b32_dpp v230, v89 row_shr:1 row_mask:0xf bank_mask:0xf
	v_mov_b32_dpp v231, v89 row_shr:2 row_mask:0xf bank_mask:0xf
	v_mov_b32_dpp v232, v90 row_shr:1 row_mask:0xf bank_mask:0xf
	v_mov_b32_dpp v233, v90 row_shr:2 row_mask:0xf bank_mask:0xf
	v_mov_b32_dpp v234, v91 row_shr:1 row_mask:0xf bank_mask:0xf
	v_mov_b32_dpp v235, v91 row_shr:2 row_mask:0xf bank_mask:0xf
	v_fma_f32 v236, v229, v136, v220
	v_fma_f32 v237, v231, v137, v221
	v_fma_f32 v238, v233, v138, v222
	v_fma_f32 v239, v235, v139, v223
	v_fmac_f32_e32 v236, v228, v152
	v_fmac_f32_e32 v237, v230, v153
	v_fmac_f32_e32 v238, v232, v154
	v_fmac_f32_e32 v239, v234, v155
	v_fmac_f32_e32 v236, v88, v168
	v_fmac_f32_e32 v237, v89, v169
	v_fmac_f32_e32 v238, v90, v170
	v_fmac_f32_e32 v239, v91, v171
	v_mov_b32_dpp v228, v96 row_ror:1 row_mask:0xf bank_mask:0xf
	v_mov_b32_dpp v229, v96 row_ror:2 row_mask:0xf bank_mask:0xf
	v_mov_b32_dpp v230, v97 row_ror:1 row_mask:0xf bank_mask:0xf
	v_mov_b32_dpp v231, v97 row_ror:2 row_mask:0xf bank_mask:0xf
	v_mov_b32_dpp v232, v98 row_ror:1 row_mask:0xf bank_mask:0xf
	v_mov_b32_dpp v233, v98 row_ror:2 row_mask:0xf bank_mask:0xf
	v_mov_b32_dpp v234, v99 row_ror:1 row_mask:0xf bank_mask:0xf
	v_mov_b32_dpp v235, v99 row_ror:2 row_mask:0xf bank_mask:0xf
	v_mov_b32_dpp v228, v80 row_shr:1 row_mask:0xf bank_mask:0xf
	v_mov_b32_dpp v229, v80 row_shr:2 row_mask:0xf bank_mask:0xf
	v_mov_b32_dpp v230, v81 row_shr:1 row_mask:0xf bank_mask:0xf
	v_mov_b32_dpp v231, v81 row_shr:2 row_mask:0xf bank_mask:0xf
	v_mov_b32_dpp v232, v82 row_shr:1 row_mask:0xf bank_mask:0xf
	v_mov_b32_dpp v233, v82 row_shr:2 row_mask:0xf bank_mask:0xf
	v_mov_b32_dpp v234, v83 row_shr:1 row_mask:0xf bank_mask:0xf
	v_mov_b32_dpp v235, v83 row_shr:2 row_mask:0xf bank_mask:0xf
	v_fma_f32 v240, v229, v140, v224
	v_fma_f32 v241, v231, v141, v225
	v_fma_f32 v242, v233, v142, v226
	v_fma_f32 v243, v235, v143, v227
	v_fmac_f32_e32 v240, v228, v156
	v_fmac_f32_e32 v241, v230, v157
	v_fmac_f32_e32 v242, v232, v158
	v_fmac_f32_e32 v243, v234, v159
	v_fmac_f32_e32 v240, v80, v204
	v_fmac_f32_e32 v241, v81, v205
	v_fmac_f32_e32 v242, v82, v206
	v_fmac_f32_e32 v243, v83, v207
	v_mov_b32_e32 v228, 0xbdd2d3e8
	v_mul_f32_e32 v244, v236, v236
	v_mul_f32_e32 v245, v237, v237
	v_mul_f32_e32 v246, v238, v238
	v_mul_f32_e32 v247, v239, v239
	v_fmaak_f32 v244, v244, v228, 0xc0135761
	v_fmaak_f32 v245, v245, v228, 0xc0135761
	v_fmaak_f32 v246, v246, v228, 0xc0135761
	v_fmaak_f32 v247, v247, v228, 0xc0135761
	v_mul_f32_e32 v244, v236, v244
	v_mul_f32_e32 v245, v237, v245
	v_mul_f32_e32 v246, v238, v246
	v_mul_f32_e32 v247, v239, v247
	v_exp_f32_e32 v244, v244
	v_exp_f32_e32 v245, v245
	v_exp_f32_e32 v246, v246
	v_exp_f32_e32 v247, v247
	v_add_f32_e32 v244, 1.0, v244
	v_add_f32_e32 v245, 1.0, v245
	v_add_f32_e32 v246, 1.0, v246
	v_add_f32_e32 v247, 1.0, v247
	v_rcp_f32_e32 v244, v244
	v_rcp_f32_e32 v245, v245
	v_rcp_f32_e32 v246, v246
	v_rcp_f32_e32 v247, v247
	v_mul_f32_e32 v244, v236, v244
	v_mul_f32_e32 v245, v237, v245
	v_mul_f32_e32 v246, v238, v246
	v_mul_f32_e32 v247, v239, v247
	v_mul_f32_e32 v174, v240, v244
	v_mul_f32_e32 v175, v241, v245
	v_mul_f32_e32 v176, v242, v246
	v_mul_f32_e32 v177, v243, v247
	v_cvt_pk_bf16_f32 v180, v248, v249
	v_cvt_pk_bf16_f32 v181, v250, v251
	v_cvt_pk_bf16_f32 v182, v174, v175
	v_cvt_pk_bf16_f32 v183, v176, v177
.Lffn1e_store2:
	v_add_u32_e32 v252, 32, v218
	v_mad_i64_i32 v[216:217], vcc, v252, s79, v[190:191]
	v_cmp_gt_i32_e32 vcc, s58, v252
	s_nop 1
	s_and_saveexec_b64 s[10:11], vcc
	global_store_dwordx4 v[216:217], v[180:183], off sc1
	s_mov_b64 exec, s[10:11]
	s_add_i32 s6, s0, 2127
	s_mul_hi_u32 s7, s6, s59
	s_lshr_b32 s7, s7, 7
	s_mulk_i32 s7, 0x810
	s_sub_i32 s6, s6, s7
	s_cmp_lt_u32 s6, 17
	s_cbranch_scc1 .Lffn1e_slow3
	v_mov_b32_dpp v228, v92 row_ror:1 row_mask:0xf bank_mask:0xf
	v_mov_b32_dpp v229, v92 row_ror:2 row_mask:0xf bank_mask:0xf
	v_mov_b32_dpp v230, v93 row_ror:1 row_mask:0xf bank_mask:0xf
	v_mov_b32_dpp v231, v93 row_ror:2 row_mask:0xf bank_mask:0xf
	v_mov_b32_dpp v232, v94 row_ror:1 row_mask:0xf bank_mask:0xf
	v_mov_b32_dpp v233, v94 row_ror:2 row_mask:0xf bank_mask:0xf
	v_mov_b32_dpp v234, v95 row_ror:1 row_mask:0xf bank_mask:0xf
	v_mov_b32_dpp v235, v95 row_ror:2 row_mask:0xf bank_mask:0xf
	v_mov_b32_dpp v228, v76 row_shr:1 row_mask:0xf bank_mask:0xf
	v_mov_b32_dpp v229, v76 row_shr:2 row_mask:0xf bank_mask:0xf
	v_mov_b32_dpp v230, v77 row_shr:1 row_mask:0xf bank_mask:0xf
	v_mov_b32_dpp v231, v77 row_shr:2 row_mask:0xf bank_mask:0xf
	v_mov_b32_dpp v232, v78 row_shr:1 row_mask:0xf bank_mask:0xf
	v_mov_b32_dpp v233, v78 row_shr:2 row_mask:0xf bank_mask:0xf
	v_mov_b32_dpp v234, v79 row_shr:1 row_mask:0xf bank_mask:0xf
	v_mov_b32_dpp v235, v79 row_shr:2 row_mask:0xf bank_mask:0xf
	v_fma_f32 v236, v229, v128, v208
	v_fma_f32 v237, v231, v129, v209
	v_fma_f32 v238, v233, v130, v210
	v_fma_f32 v239, v235, v131, v211
	v_fmac_f32_e32 v236, v228, v144
	v_fmac_f32_e32 v237, v230, v145
	v_fmac_f32_e32 v238, v232, v146
	v_fmac_f32_e32 v239, v234, v147
	v_fmac_f32_e32 v236, v76, v160
	v_fmac_f32_e32 v237, v77, v161
	v_fmac_f32_e32 v238, v78, v162
	v_fmac_f32_e32 v239, v79, v163
	v_mov_b32_dpp v228, v84 row_ror:1 row_mask:0xf bank_mask:0xf
	v_mov_b32_dpp v229, v84 row_ror:2 row_mask:0xf bank_mask:0xf
	v_mov_b32_dpp v230, v85 row_ror:1 row_mask:0xf bank_mask:0xf
	v_mov_b32_dpp v231, v85 row_ror:2 row_mask:0xf bank_mask:0xf
	v_mov_b32_dpp v232, v86 row_ror:1 row_mask:0xf bank_mask:0xf
	v_mov_b32_dpp v233, v86 row_ror:2 row_mask:0xf bank_mask:0xf
	v_mov_b32_dpp v234, v87 row_ror:1 row_mask:0xf bank_mask:0xf
	v_mov_b32_dpp v235, v87 row_ror:2 row_mask:0xf bank_mask:0xf
	v_mov_b32_dpp v228, v68 row_shr:1 row_mask:0xf bank_mask:0xf
	v_mov_b32_dpp v229, v68 row_shr:2 row_mask:0xf bank_mask:0xf
	v_mov_b32_dpp v230, v69 row_shr:1 row_mask:0xf bank_mask:0xf
	v_mov_b32_dpp v231, v69 row_shr:2 row_mask:0xf bank_mask:0xf
	v_mov_b32_dpp v232, v70 row_shr:1 row_mask:0xf bank_mask:0xf
	v_mov_b32_dpp v233, v70 row_shr:2 row_mask:0xf bank_mask:0xf
	v_mov_b32_dpp v234, v71 row_shr:1 row_mask:0xf bank_mask:0xf
	v_mov_b32_dpp v235, v71 row_shr:2 row_mask:0xf bank_mask:0xf
	v_fma_f32 v240, v229, v132, v212
	v_fma_f32 v241, v231, v133, v213
	v_fma_f32 v242, v233, v134, v214
	v_fma_f32 v243, v235, v135, v215
	v_fmac_f32_e32 v240, v228, v148
	v_fmac_f32_e32 v241, v230, v149
	v_fmac_f32_e32 v242, v232, v150
	v_fmac_f32_e32 v243, v234, v151
	v_fmac_f32_e32 v240, v68, v164
	v_fmac_f32_e32 v241, v69, v165
	v_fmac_f32_e32 v242, v70, v166
	v_fmac_f32_e32 v243, v71, v167
	v_mov_b32_e32 v228, 0xbdd2d3e8
	v_mul_f32_e32 v244, v236, v236
	v_mul_f32_e32 v245, v237, v237
	v_mul_f32_e32 v246, v238, v238
	v_mul_f32_e32 v247, v239, v239
	v_fmaak_f32 v244, v244, v228, 0xc0135761
	v_fmaak_f32 v245, v245, v228, 0xc0135761
	v_fmaak_f32 v246, v246, v228, 0xc0135761
	v_fmaak_f32 v247, v247, v228, 0xc0135761
	v_mul_f32_e32 v244, v236, v244
	v_mul_f32_e32 v245, v237, v245
	v_mul_f32_e32 v246, v238, v246
	v_mul_f32_e32 v247, v239, v247
	v_exp_f32_e32 v244, v244
	v_exp_f32_e32 v245, v245
	v_exp_f32_e32 v246, v246
	v_exp_f32_e32 v247, v247
	v_add_f32_e32 v244, 1.0, v244
	v_add_f32_e32 v245, 1.0, v245
	v_add_f32_e32 v246, 1.0, v246
	v_add_f32_e32 v247, 1.0, v247
	v_rcp_f32_e32 v244, v244
	v_rcp_f32_e32 v245, v245
	v_rcp_f32_e32 v246, v246
	v_rcp_f32_e32 v247, v247
	v_mul_f32_e32 v244, v236, v244
	v_mul_f32_e32 v245, v237, v245
	v_mul_f32_e32 v246, v238, v246
	v_mul_f32_e32 v247, v239, v247
	v_mul_f32_e32 v248, v240, v244
	v_mul_f32_e32 v249, v241, v245
	v_mul_f32_e32 v250, v242, v246
	v_mul_f32_e32 v251, v243, v247
	v_mov_b32_dpp v228, v88 row_ror:1 row_mask:0xf bank_mask:0xf
	v_mov_b32_dpp v229, v88 row_ror:2 row_mask:0xf bank_mask:0xf
	v_mov_b32_dpp v230, v89 row_ror:1 row_mask:0xf bank_mask:0xf
	v_mov_b32_dpp v231, v89 row_ror:2 row_mask:0xf bank_mask:0xf
	v_mov_b32_dpp v232, v90 row_ror:1 row_mask:0xf bank_mask:0xf
	v_mov_b32_dpp v233, v90 row_ror:2 row_mask:0xf bank_mask:0xf
	v_mov_b32_dpp v234, v91 row_ror:1 row_mask:0xf bank_mask:0xf
	v_mov_b32_dpp v235, v91 row_ror:2 row_mask:0xf bank_mask:0xf
	v_mov_b32_dpp v228, v72 row_shr:1 row_mask:0xf bank_mask:0xf
	v_mov_b32_dpp v229, v72 row_shr:2 row_mask:0xf bank_mask:0xf
	v_mov_b32_dpp v230, v73 row_shr:1 row_mask:0xf bank_mask:0xf
	v_mov_b32_dpp v231, v73 row_shr:2 row_mask:0xf bank_mask:0xf
	v_mov_b32_dpp v232, v74 row_shr:1 row_mask:0xf bank_mask:0xf
	v_mov_b32_dpp v233, v74 row_shr:2 row_mask:0xf bank_mask:0xf
	v_mov_b32_dpp v234, v75 row_shr:1 row_mask:0xf bank_mask:0xf
	v_mov_b32_dpp v235, v75 row_shr:2 row_mask:0xf bank_mask:0xf
	v_fma_f32 v236, v229, v136, v220
	v_fma_f32 v237, v231, v137, v221
	v_fma_f32 v238, v233, v138, v222
	v_fma_f32 v239, v235, v139, v223
	v_fmac_f32_e32 v236, v228, v152
	v_fmac_f32_e32 v237, v230, v153
	v_fmac_f32_e32 v238, v232, v154
	v_fmac_f32_e32 v239, v234, v155
	v_fmac_f32_e32 v236, v72, v168
	v_fmac_f32_e32 v237, v73, v169
	v_fmac_f32_e32 v238, v74, v170
	v_fmac_f32_e32 v239, v75, v171
	v_mov_b32_dpp v228, v80 row_ror:1 row_mask:0xf bank_mask:0xf
	v_mov_b32_dpp v229, v80 row_ror:2 row_mask:0xf bank_mask:0xf
	v_mov_b32_dpp v230, v81 row_ror:1 row_mask:0xf bank_mask:0xf
	v_mov_b32_dpp v231, v81 row_ror:2 row_mask:0xf bank_mask:0xf
	v_mov_b32_dpp v232, v82 row_ror:1 row_mask:0xf bank_mask:0xf
	v_mov_b32_dpp v233, v82 row_ror:2 row_mask:0xf bank_mask:0xf
	v_mov_b32_dpp v234, v83 row_ror:1 row_mask:0xf bank_mask:0xf
	v_mov_b32_dpp v235, v83 row_ror:2 row_mask:0xf bank_mask:0xf
	v_mov_b32_dpp v228, v64 row_shr:1 row_mask:0xf bank_mask:0xf
	v_mov_b32_dpp v229, v64 row_shr:2 row_mask:0xf bank_mask:0xf
	v_mov_b32_dpp v230, v65 row_shr:1 row_mask:0xf bank_mask:0xf
	v_mov_b32_dpp v231, v65 row_shr:2 row_mask:0xf bank_mask:0xf
	v_mov_b32_dpp v232, v66 row_shr:1 row_mask:0xf bank_mask:0xf
	v_mov_b32_dpp v233, v66 row_shr:2 row_mask:0xf bank_mask:0xf
	v_mov_b32_dpp v234, v67 row_shr:1 row_mask:0xf bank_mask:0xf
	v_mov_b32_dpp v235, v67 row_shr:2 row_mask:0xf bank_mask:0xf
	v_fma_f32 v240, v229, v140, v224
	v_fma_f32 v241, v231, v141, v225
	v_fma_f32 v242, v233, v142, v226
	v_fma_f32 v243, v235, v143, v227
	v_fmac_f32_e32 v240, v228, v156
	v_fmac_f32_e32 v241, v230, v157
	v_fmac_f32_e32 v242, v232, v158
	v_fmac_f32_e32 v243, v234, v159
	v_fmac_f32_e32 v240, v64, v204
	v_fmac_f32_e32 v241, v65, v205
	v_fmac_f32_e32 v242, v66, v206
	v_fmac_f32_e32 v243, v67, v207
	v_mov_b32_e32 v228, 0xbdd2d3e8
	v_mul_f32_e32 v244, v236, v236
	v_mul_f32_e32 v245, v237, v237
	v_mul_f32_e32 v246, v238, v238
	v_mul_f32_e32 v247, v239, v239
	v_fmaak_f32 v244, v244, v228, 0xc0135761
	v_fmaak_f32 v245, v245, v228, 0xc0135761
	v_fmaak_f32 v246, v246, v228, 0xc0135761
	v_fmaak_f32 v247, v247, v228, 0xc0135761
	v_mul_f32_e32 v244, v236, v244
	v_mul_f32_e32 v245, v237, v245
	v_mul_f32_e32 v246, v238, v246
	v_mul_f32_e32 v247, v239, v247
	v_exp_f32_e32 v244, v244
	v_exp_f32_e32 v245, v245
	v_exp_f32_e32 v246, v246
	v_exp_f32_e32 v247, v247
	v_add_f32_e32 v244, 1.0, v244
	v_add_f32_e32 v245, 1.0, v245
	v_add_f32_e32 v246, 1.0, v246
	v_add_f32_e32 v247, 1.0, v247
	v_rcp_f32_e32 v244, v244
	v_rcp_f32_e32 v245, v245
	v_rcp_f32_e32 v246, v246
	v_rcp_f32_e32 v247, v247
	v_mul_f32_e32 v244, v236, v244
	v_mul_f32_e32 v245, v237, v245
	v_mul_f32_e32 v246, v238, v246
	v_mul_f32_e32 v247, v239, v247
	v_mul_f32_e32 v174, v240, v244
	v_mul_f32_e32 v175, v241, v245
	v_mul_f32_e32 v176, v242, v246
	v_mul_f32_e32 v177, v243, v247
	v_cvt_pk_bf16_f32 v180, v248, v249
	v_cvt_pk_bf16_f32 v181, v250, v251
	v_cvt_pk_bf16_f32 v182, v174, v175
	v_cvt_pk_bf16_f32 v183, v176, v177
.Lffn1e_store3:
	v_add_u32_e32 v252, 48, v218
	v_mad_i64_i32 v[216:217], vcc, v252, s79, v[190:191]
	v_cmp_gt_i32_e32 vcc, s58, v252
	s_nop 1
	s_and_saveexec_b64 s[10:11], vcc
	global_store_dwordx4 v[216:217], v[180:183], off sc1
	s_mov_b64 exec, s[10:11]
	s_add_i32 s6, s0, 2143
	s_mul_hi_u32 s7, s6, s59
	s_lshr_b32 s7, s7, 7
	s_mulk_i32 s7, 0x810
	s_sub_i32 s6, s6, s7
	s_cmp_lt_u32 s6, 17
	s_cbranch_scc1 .Lffn1e_slow4
	v_mov_b32_dpp v228, v76 row_ror:1 row_mask:0xf bank_mask:0xf
	v_mov_b32_dpp v229, v76 row_ror:2 row_mask:0xf bank_mask:0xf
	v_mov_b32_dpp v230, v77 row_ror:1 row_mask:0xf bank_mask:0xf
	v_mov_b32_dpp v231, v77 row_ror:2 row_mask:0xf bank_mask:0xf
	v_mov_b32_dpp v232, v78 row_ror:1 row_mask:0xf bank_mask:0xf
	v_mov_b32_dpp v233, v78 row_ror:2 row_mask:0xf bank_mask:0xf
	v_mov_b32_dpp v234, v79 row_ror:1 row_mask:0xf bank_mask:0xf
	v_mov_b32_dpp v235, v79 row_ror:2 row_mask:0xf bank_mask:0xf
	v_mov_b32_dpp v228, v60 row_shr:1 row_mask:0xf bank_mask:0xf
	v_mov_b32_dpp v229, v60 row_shr:2 row_mask:0xf bank_mask:0xf
	v_mov_b32_dpp v230, v61 row_shr:1 row_mask:0xf bank_mask:0xf
	v_mov_b32_dpp v231, v61 row_shr:2 row_mask:0xf bank_mask:0xf
	v_mov_b32_dpp v232, v62 row_shr:1 row_mask:0xf bank_mask:0xf
	v_mov_b32_dpp v233, v62 row_shr:2 row_mask:0xf bank_mask:0xf
	v_mov_b32_dpp v234, v63 row_shr:1 row_mask:0xf bank_mask:0xf
	v_mov_b32_dpp v235, v63 row_shr:2 row_mask:0xf bank_mask:0xf
	v_fma_f32 v236, v229, v128, v208
	v_fma_f32 v237, v231, v129, v209
	v_fma_f32 v238, v233, v130, v210
	v_fma_f32 v239, v235, v131, v211
	v_fmac_f32_e32 v236, v228, v144
	v_fmac_f32_e32 v237, v230, v145
	v_fmac_f32_e32 v238, v232, v146
	v_fmac_f32_e32 v239, v234, v147
	v_fmac_f32_e32 v236, v60, v160
	v_fmac_f32_e32 v237, v61, v161
	v_fmac_f32_e32 v238, v62, v162
	v_fmac_f32_e32 v239, v63, v163
	v_mov_b32_dpp v228, v68 row_ror:1 row_mask:0xf bank_mask:0xf
	v_mov_b32_dpp v229, v68 row_ror:2 row_mask:0xf bank_mask:0xf
	v_mov_b32_dpp v230, v69 row_ror:1 row_mask:0xf bank_mask:0xf
	v_mov_b32_dpp v231, v69 row_ror:2 row_mask:0xf bank_mask:0xf
	v_mov_b32_dpp v232, v70 row_ror:1 row_mask:0xf bank_mask:0xf
	v_mov_b32_dpp v233, v70 row_ror:2 row_mask:0xf bank_mask:0xf
	v_mov_b32_dpp v234, v71 row_ror:1 row_mask:0xf bank_mask:0xf
	v_mov_b32_dpp v235, v71 row_ror:2 row_mask:0xf bank_mask:0xf
	v_mov_b32_dpp v228, v52 row_shr:1 row_mask:0xf bank_mask:0xf
	v_mov_b32_dpp v229, v52 row_shr:2 row_mask:0xf bank_mask:0xf
	v_mov_b32_dpp v230, v53 row_shr:1 row_mask:0xf bank_mask:0xf
	v_mov_b32_dpp v231, v53 row_shr:2 row_mask:0xf bank_mask:0xf
	v_mov_b32_dpp v232, v54 row_shr:1 row_mask:0xf bank_mask:0xf
	v_mov_b32_dpp v233, v54 row_shr:2 row_mask:0xf bank_mask:0xf
	v_mov_b32_dpp v234, v55 row_shr:1 row_mask:0xf bank_mask:0xf
	v_mov_b32_dpp v235, v55 row_shr:2 row_mask:0xf bank_mask:0xf
	v_fma_f32 v240, v229, v132, v212
	v_fma_f32 v241, v231, v133, v213
	v_fma_f32 v242, v233, v134, v214
	v_fma_f32 v243, v235, v135, v215
	v_fmac_f32_e32 v240, v228, v148
	v_fmac_f32_e32 v241, v230, v149
	v_fmac_f32_e32 v242, v232, v150
	v_fmac_f32_e32 v243, v234, v151
	v_fmac_f32_e32 v240, v52, v164
	v_fmac_f32_e32 v241, v53, v165
	v_fmac_f32_e32 v242, v54, v166
	v_fmac_f32_e32 v243, v55, v167
	v_mov_b32_e32 v228, 0xbdd2d3e8
	v_mul_f32_e32 v244, v236, v236
	v_mul_f32_e32 v245, v237, v237
	v_mul_f32_e32 v246, v238, v238
	v_mul_f32_e32 v247, v239, v239
	v_fmaak_f32 v244, v244, v228, 0xc0135761
	v_fmaak_f32 v245, v245, v228, 0xc0135761
	v_fmaak_f32 v246, v246, v228, 0xc0135761
	v_fmaak_f32 v247, v247, v228, 0xc0135761
	v_mul_f32_e32 v244, v236, v244
	v_mul_f32_e32 v245, v237, v245
	v_mul_f32_e32 v246, v238, v246
	v_mul_f32_e32 v247, v239, v247
	v_exp_f32_e32 v244, v244
	v_exp_f32_e32 v245, v245
	v_exp_f32_e32 v246, v246
	v_exp_f32_e32 v247, v247
	v_add_f32_e32 v244, 1.0, v244
	v_add_f32_e32 v245, 1.0, v245
	v_add_f32_e32 v246, 1.0, v246
	v_add_f32_e32 v247, 1.0, v247
	v_rcp_f32_e32 v244, v244
	v_rcp_f32_e32 v245, v245
	v_rcp_f32_e32 v246, v246
	v_rcp_f32_e32 v247, v247
	v_mul_f32_e32 v244, v236, v244
	v_mul_f32_e32 v245, v237, v245
	v_mul_f32_e32 v246, v238, v246
	v_mul_f32_e32 v247, v239, v247
	v_mul_f32_e32 v248, v240, v244
	v_mul_f32_e32 v249, v241, v245
	v_mul_f32_e32 v250, v242, v246
	v_mul_f32_e32 v251, v243, v247
	v_mov_b32_dpp v228, v72 row_ror:1 row_mask:0xf bank_mask:0xf
	v_mov_b32_dpp v229, v72 row_ror:2 row_mask:0xf bank_mask:0xf
	v_mov_b32_dpp v230, v73 row_ror:1 row_mask:0xf bank_mask:0xf
	v_mov_b32_dpp v231, v73 row_ror:2 row_mask:0xf bank_mask:0xf
	v_mov_b32_dpp v232, v74 row_ror:1 row_mask:0xf bank_mask:0xf
	v_mov_b32_dpp v233, v74 row_ror:2 row_mask:0xf bank_mask:0xf
	v_mov_b32_dpp v234, v75 row_ror:1 row_mask:0xf bank_mask:0xf
	v_mov_b32_dpp v235, v75 row_ror:2 row_mask:0xf bank_mask:0xf
	v_mov_b32_dpp v228, v56 row_shr:1 row_mask:0xf bank_mask:0xf
	v_mov_b32_dpp v229, v56 row_shr:2 row_mask:0xf bank_mask:0xf
	v_mov_b32_dpp v230, v57 row_shr:1 row_mask:0xf bank_mask:0xf
	v_mov_b32_dpp v231, v57 row_shr:2 row_mask:0xf bank_mask:0xf
	v_mov_b32_dpp v232, v58 row_shr:1 row_mask:0xf bank_mask:0xf
	v_mov_b32_dpp v233, v58 row_shr:2 row_mask:0xf bank_mask:0xf
	v_mov_b32_dpp v234, v59 row_shr:1 row_mask:0xf bank_mask:0xf
	v_mov_b32_dpp v235, v59 row_shr:2 row_mask:0xf bank_mask:0xf
	v_fma_f32 v236, v229, v136, v220
	v_fma_f32 v237, v231, v137, v221
	v_fma_f32 v238, v233, v138, v222
	v_fma_f32 v239, v235, v139, v223
	v_fmac_f32_e32 v236, v228, v152
	v_fmac_f32_e32 v237, v230, v153
	v_fmac_f32_e32 v238, v232, v154
	v_fmac_f32_e32 v239, v234, v155
	v_fmac_f32_e32 v236, v56, v168
	v_fmac_f32_e32 v237, v57, v169
	v_fmac_f32_e32 v238, v58, v170
	v_fmac_f32_e32 v239, v59, v171
	v_mov_b32_dpp v228, v64 row_ror:1 row_mask:0xf bank_mask:0xf
	v_mov_b32_dpp v229, v64 row_ror:2 row_mask:0xf bank_mask:0xf
	v_mov_b32_dpp v230, v65 row_ror:1 row_mask:0xf bank_mask:0xf
	v_mov_b32_dpp v231, v65 row_ror:2 row_mask:0xf bank_mask:0xf
	v_mov_b32_dpp v232, v66 row_ror:1 row_mask:0xf bank_mask:0xf
	v_mov_b32_dpp v233, v66 row_ror:2 row_mask:0xf bank_mask:0xf
	v_mov_b32_dpp v234, v67 row_ror:1 row_mask:0xf bank_mask:0xf
	v_mov_b32_dpp v235, v67 row_ror:2 row_mask:0xf bank_mask:0xf
	v_mov_b32_dpp v228, v48 row_shr:1 row_mask:0xf bank_mask:0xf
	v_mov_b32_dpp v229, v48 row_shr:2 row_mask:0xf bank_mask:0xf
	v_mov_b32_dpp v230, v49 row_shr:1 row_mask:0xf bank_mask:0xf
	v_mov_b32_dpp v231, v49 row_shr:2 row_mask:0xf bank_mask:0xf
	v_mov_b32_dpp v232, v50 row_shr:1 row_mask:0xf bank_mask:0xf
	v_mov_b32_dpp v233, v50 row_shr:2 row_mask:0xf bank_mask:0xf
	v_mov_b32_dpp v234, v51 row_shr:1 row_mask:0xf bank_mask:0xf
	v_mov_b32_dpp v235, v51 row_shr:2 row_mask:0xf bank_mask:0xf
	v_fma_f32 v240, v229, v140, v224
	v_fma_f32 v241, v231, v141, v225
	v_fma_f32 v242, v233, v142, v226
	v_fma_f32 v243, v235, v143, v227
	v_fmac_f32_e32 v240, v228, v156
	v_fmac_f32_e32 v241, v230, v157
	v_fmac_f32_e32 v242, v232, v158
	v_fmac_f32_e32 v243, v234, v159
	v_fmac_f32_e32 v240, v48, v204
	v_fmac_f32_e32 v241, v49, v205
	v_fmac_f32_e32 v242, v50, v206
	v_fmac_f32_e32 v243, v51, v207
	v_mov_b32_e32 v228, 0xbdd2d3e8
	v_mul_f32_e32 v244, v236, v236
	v_mul_f32_e32 v245, v237, v237
	v_mul_f32_e32 v246, v238, v238
	v_mul_f32_e32 v247, v239, v239
	v_fmaak_f32 v244, v244, v228, 0xc0135761
	v_fmaak_f32 v245, v245, v228, 0xc0135761
	v_fmaak_f32 v246, v246, v228, 0xc0135761
	v_fmaak_f32 v247, v247, v228, 0xc0135761
	v_mul_f32_e32 v244, v236, v244
	v_mul_f32_e32 v245, v237, v245
	v_mul_f32_e32 v246, v238, v246
	v_mul_f32_e32 v247, v239, v247
	v_exp_f32_e32 v244, v244
	v_exp_f32_e32 v245, v245
	v_exp_f32_e32 v246, v246
	v_exp_f32_e32 v247, v247
	v_add_f32_e32 v244, 1.0, v244
	v_add_f32_e32 v245, 1.0, v245
	v_add_f32_e32 v246, 1.0, v246
	v_add_f32_e32 v247, 1.0, v247
	v_rcp_f32_e32 v244, v244
	v_rcp_f32_e32 v245, v245
	v_rcp_f32_e32 v246, v246
	v_rcp_f32_e32 v247, v247
	v_mul_f32_e32 v244, v236, v244
	v_mul_f32_e32 v245, v237, v245
	v_mul_f32_e32 v246, v238, v246
	v_mul_f32_e32 v247, v239, v247
	v_mul_f32_e32 v174, v240, v244
	v_mul_f32_e32 v175, v241, v245
	v_mul_f32_e32 v176, v242, v246
	v_mul_f32_e32 v177, v243, v247
	v_cvt_pk_bf16_f32 v180, v248, v249
	v_cvt_pk_bf16_f32 v181, v250, v251
	v_cvt_pk_bf16_f32 v182, v174, v175
	v_cvt_pk_bf16_f32 v183, v176, v177
.Lffn1e_store4:
	v_add_u32_e32 v252, 64, v218
	v_mad_i64_i32 v[216:217], vcc, v252, s79, v[190:191]
	v_cmp_gt_i32_e32 vcc, s58, v252
	s_nop 1
	s_and_saveexec_b64 s[10:11], vcc
	global_store_dwordx4 v[216:217], v[180:183], off sc1
	s_mov_b64 exec, s[10:11]
	s_add_i32 s6, s0, 2159
	s_mul_hi_u32 s7, s6, s59
	s_lshr_b32 s7, s7, 7
	s_mulk_i32 s7, 0x810
	s_sub_i32 s6, s6, s7
	s_cmp_lt_u32 s6, 17
	s_cbranch_scc1 .Lffn1e_slow5
	v_mov_b32_dpp v228, v60 row_ror:1 row_mask:0xf bank_mask:0xf
	v_mov_b32_dpp v229, v60 row_ror:2 row_mask:0xf bank_mask:0xf
	v_mov_b32_dpp v230, v61 row_ror:1 row_mask:0xf bank_mask:0xf
	v_mov_b32_dpp v231, v61 row_ror:2 row_mask:0xf bank_mask:0xf
	v_mov_b32_dpp v232, v62 row_ror:1 row_mask:0xf bank_mask:0xf
	v_mov_b32_dpp v233, v62 row_ror:2 row_mask:0xf bank_mask:0xf
	v_mov_b32_dpp v234, v63 row_ror:1 row_mask:0xf bank_mask:0xf
	v_mov_b32_dpp v235, v63 row_ror:2 row_mask:0xf bank_mask:0xf
	v_mov_b32_dpp v228, v44 row_shr:1 row_mask:0xf bank_mask:0xf
	v_mov_b32_dpp v229, v44 row_shr:2 row_mask:0xf bank_mask:0xf
	v_mov_b32_dpp v230, v45 row_shr:1 row_mask:0xf bank_mask:0xf
	v_mov_b32_dpp v231, v45 row_shr:2 row_mask:0xf bank_mask:0xf
	v_mov_b32_dpp v232, v46 row_shr:1 row_mask:0xf bank_mask:0xf
	v_mov_b32_dpp v233, v46 row_shr:2 row_mask:0xf bank_mask:0xf
	v_mov_b32_dpp v234, v47 row_shr:1 row_mask:0xf bank_mask:0xf
	v_mov_b32_dpp v235, v47 row_shr:2 row_mask:0xf bank_mask:0xf
	v_fma_f32 v236, v229, v128, v208
	v_fma_f32 v237, v231, v129, v209
	v_fma_f32 v238, v233, v130, v210
	v_fma_f32 v239, v235, v131, v211
	v_fmac_f32_e32 v236, v228, v144
	v_fmac_f32_e32 v237, v230, v145
	v_fmac_f32_e32 v238, v232, v146
	v_fmac_f32_e32 v239, v234, v147
	v_fmac_f32_e32 v236, v44, v160
	v_fmac_f32_e32 v237, v45, v161
	v_fmac_f32_e32 v238, v46, v162
	v_fmac_f32_e32 v239, v47, v163
	v_mov_b32_dpp v228, v52 row_ror:1 row_mask:0xf bank_mask:0xf
	v_mov_b32_dpp v229, v52 row_ror:2 row_mask:0xf bank_mask:0xf
	v_mov_b32_dpp v230, v53 row_ror:1 row_mask:0xf bank_mask:0xf
	v_mov_b32_dpp v231, v53 row_ror:2 row_mask:0xf bank_mask:0xf
	v_mov_b32_dpp v232, v54 row_ror:1 row_mask:0xf bank_mask:0xf
	v_mov_b32_dpp v233, v54 row_ror:2 row_mask:0xf bank_mask:0xf
	v_mov_b32_dpp v234, v55 row_ror:1 row_mask:0xf bank_mask:0xf
	v_mov_b32_dpp v235, v55 row_ror:2 row_mask:0xf bank_mask:0xf
	v_mov_b32_dpp v228, v36 row_shr:1 row_mask:0xf bank_mask:0xf
	v_mov_b32_dpp v229, v36 row_shr:2 row_mask:0xf bank_mask:0xf
	v_mov_b32_dpp v230, v37 row_shr:1 row_mask:0xf bank_mask:0xf
	v_mov_b32_dpp v231, v37 row_shr:2 row_mask:0xf bank_mask:0xf
	v_mov_b32_dpp v232, v38 row_shr:1 row_mask:0xf bank_mask:0xf
	v_mov_b32_dpp v233, v38 row_shr:2 row_mask:0xf bank_mask:0xf
	v_mov_b32_dpp v234, v39 row_shr:1 row_mask:0xf bank_mask:0xf
	v_mov_b32_dpp v235, v39 row_shr:2 row_mask:0xf bank_mask:0xf
	v_fma_f32 v240, v229, v132, v212
	v_fma_f32 v241, v231, v133, v213
	v_fma_f32 v242, v233, v134, v214
	v_fma_f32 v243, v235, v135, v215
	v_fmac_f32_e32 v240, v228, v148
	v_fmac_f32_e32 v241, v230, v149
	v_fmac_f32_e32 v242, v232, v150
	v_fmac_f32_e32 v243, v234, v151
	v_fmac_f32_e32 v240, v36, v164
	v_fmac_f32_e32 v241, v37, v165
	v_fmac_f32_e32 v242, v38, v166
	v_fmac_f32_e32 v243, v39, v167
	v_mov_b32_e32 v228, 0xbdd2d3e8
	v_mul_f32_e32 v244, v236, v236
	v_mul_f32_e32 v245, v237, v237
	v_mul_f32_e32 v246, v238, v238
	v_mul_f32_e32 v247, v239, v239
	v_fmaak_f32 v244, v244, v228, 0xc0135761
	v_fmaak_f32 v245, v245, v228, 0xc0135761
	v_fmaak_f32 v246, v246, v228, 0xc0135761
	v_fmaak_f32 v247, v247, v228, 0xc0135761
	v_mul_f32_e32 v244, v236, v244
	v_mul_f32_e32 v245, v237, v245
	v_mul_f32_e32 v246, v238, v246
	v_mul_f32_e32 v247, v239, v247
	v_exp_f32_e32 v244, v244
	v_exp_f32_e32 v245, v245
	v_exp_f32_e32 v246, v246
	v_exp_f32_e32 v247, v247
	v_add_f32_e32 v244, 1.0, v244
	v_add_f32_e32 v245, 1.0, v245
	v_add_f32_e32 v246, 1.0, v246
	v_add_f32_e32 v247, 1.0, v247
	v_rcp_f32_e32 v244, v244
	v_rcp_f32_e32 v245, v245
	v_rcp_f32_e32 v246, v246
	v_rcp_f32_e32 v247, v247
	v_mul_f32_e32 v244, v236, v244
	v_mul_f32_e32 v245, v237, v245
	v_mul_f32_e32 v246, v238, v246
	v_mul_f32_e32 v247, v239, v247
	v_mul_f32_e32 v248, v240, v244
	v_mul_f32_e32 v249, v241, v245
	v_mul_f32_e32 v250, v242, v246
	v_mul_f32_e32 v251, v243, v247
	v_mov_b32_dpp v228, v56 row_ror:1 row_mask:0xf bank_mask:0xf
	v_mov_b32_dpp v229, v56 row_ror:2 row_mask:0xf bank_mask:0xf
	v_mov_b32_dpp v230, v57 row_ror:1 row_mask:0xf bank_mask:0xf
	v_mov_b32_dpp v231, v57 row_ror:2 row_mask:0xf bank_mask:0xf
	v_mov_b32_dpp v232, v58 row_ror:1 row_mask:0xf bank_mask:0xf
	v_mov_b32_dpp v233, v58 row_ror:2 row_mask:0xf bank_mask:0xf
	v_mov_b32_dpp v234, v59 row_ror:1 row_mask:0xf bank_mask:0xf
	v_mov_b32_dpp v235, v59 row_ror:2 row_mask:0xf bank_mask:0xf
	v_mov_b32_dpp v228, v40 row_shr:1 row_mask:0xf bank_mask:0xf
	v_mov_b32_dpp v229, v40 row_shr:2 row_mask:0xf bank_mask:0xf
	v_mov_b32_dpp v230, v41 row_shr:1 row_mask:0xf bank_mask:0xf
	v_mov_b32_dpp v231, v41 row_shr:2 row_mask:0xf bank_mask:0xf
	v_mov_b32_dpp v232, v42 row_shr:1 row_mask:0xf bank_mask:0xf
	v_mov_b32_dpp v233, v42 row_shr:2 row_mask:0xf bank_mask:0xf
	v_mov_b32_dpp v234, v43 row_shr:1 row_mask:0xf bank_mask:0xf
	v_mov_b32_dpp v235, v43 row_shr:2 row_mask:0xf bank_mask:0xf
	v_fma_f32 v236, v229, v136, v220
	v_fma_f32 v237, v231, v137, v221
	v_fma_f32 v238, v233, v138, v222
	v_fma_f32 v239, v235, v139, v223
	v_fmac_f32_e32 v236, v228, v152
	v_fmac_f32_e32 v237, v230, v153
	v_fmac_f32_e32 v238, v232, v154
	v_fmac_f32_e32 v239, v234, v155
	v_fmac_f32_e32 v236, v40, v168
	v_fmac_f32_e32 v237, v41, v169
	v_fmac_f32_e32 v238, v42, v170
	v_fmac_f32_e32 v239, v43, v171
	v_mov_b32_dpp v228, v48 row_ror:1 row_mask:0xf bank_mask:0xf
	v_mov_b32_dpp v229, v48 row_ror:2 row_mask:0xf bank_mask:0xf
	v_mov_b32_dpp v230, v49 row_ror:1 row_mask:0xf bank_mask:0xf
	v_mov_b32_dpp v231, v49 row_ror:2 row_mask:0xf bank_mask:0xf
	v_mov_b32_dpp v232, v50 row_ror:1 row_mask:0xf bank_mask:0xf
	v_mov_b32_dpp v233, v50 row_ror:2 row_mask:0xf bank_mask:0xf
	v_mov_b32_dpp v234, v51 row_ror:1 row_mask:0xf bank_mask:0xf
	v_mov_b32_dpp v235, v51 row_ror:2 row_mask:0xf bank_mask:0xf
	v_mov_b32_dpp v228, v32 row_shr:1 row_mask:0xf bank_mask:0xf
	v_mov_b32_dpp v229, v32 row_shr:2 row_mask:0xf bank_mask:0xf
	v_mov_b32_dpp v230, v33 row_shr:1 row_mask:0xf bank_mask:0xf
	v_mov_b32_dpp v231, v33 row_shr:2 row_mask:0xf bank_mask:0xf
	v_mov_b32_dpp v232, v34 row_shr:1 row_mask:0xf bank_mask:0xf
	v_mov_b32_dpp v233, v34 row_shr:2 row_mask:0xf bank_mask:0xf
	v_mov_b32_dpp v234, v35 row_shr:1 row_mask:0xf bank_mask:0xf
	v_mov_b32_dpp v235, v35 row_shr:2 row_mask:0xf bank_mask:0xf
	v_fma_f32 v240, v229, v140, v224
	v_fma_f32 v241, v231, v141, v225
	v_fma_f32 v242, v233, v142, v226
	v_fma_f32 v243, v235, v143, v227
	v_fmac_f32_e32 v240, v228, v156
	v_fmac_f32_e32 v241, v230, v157
	v_fmac_f32_e32 v242, v232, v158
	v_fmac_f32_e32 v243, v234, v159
	v_fmac_f32_e32 v240, v32, v204
	v_fmac_f32_e32 v241, v33, v205
	v_fmac_f32_e32 v242, v34, v206
	v_fmac_f32_e32 v243, v35, v207
	v_mov_b32_e32 v228, 0xbdd2d3e8
	v_mul_f32_e32 v244, v236, v236
	v_mul_f32_e32 v245, v237, v237
	v_mul_f32_e32 v246, v238, v238
	v_mul_f32_e32 v247, v239, v239
	v_fmaak_f32 v244, v244, v228, 0xc0135761
	v_fmaak_f32 v245, v245, v228, 0xc0135761
	v_fmaak_f32 v246, v246, v228, 0xc0135761
	v_fmaak_f32 v247, v247, v228, 0xc0135761
	v_mul_f32_e32 v244, v236, v244
	v_mul_f32_e32 v245, v237, v245
	v_mul_f32_e32 v246, v238, v246
	v_mul_f32_e32 v247, v239, v247
	v_exp_f32_e32 v244, v244
	v_exp_f32_e32 v245, v245
	v_exp_f32_e32 v246, v246
	v_exp_f32_e32 v247, v247
	v_add_f32_e32 v244, 1.0, v244
	v_add_f32_e32 v245, 1.0, v245
	v_add_f32_e32 v246, 1.0, v246
	v_add_f32_e32 v247, 1.0, v247
	v_rcp_f32_e32 v244, v244
	v_rcp_f32_e32 v245, v245
	v_rcp_f32_e32 v246, v246
	v_rcp_f32_e32 v247, v247
	v_mul_f32_e32 v244, v236, v244
	v_mul_f32_e32 v245, v237, v245
	v_mul_f32_e32 v246, v238, v246
	v_mul_f32_e32 v247, v239, v247
	v_mul_f32_e32 v174, v240, v244
	v_mul_f32_e32 v175, v241, v245
	v_mul_f32_e32 v176, v242, v246
	v_mul_f32_e32 v177, v243, v247
	v_cvt_pk_bf16_f32 v180, v248, v249
	v_cvt_pk_bf16_f32 v181, v250, v251
	v_cvt_pk_bf16_f32 v182, v174, v175
	v_cvt_pk_bf16_f32 v183, v176, v177
.Lffn1e_store5:
	v_add_u32_e32 v252, 80, v218
	v_mad_i64_i32 v[216:217], vcc, v252, s79, v[190:191]
	v_cmp_gt_i32_e32 vcc, s58, v252
	s_nop 1
	s_and_saveexec_b64 s[10:11], vcc
	global_store_dwordx4 v[216:217], v[180:183], off sc1
	s_mov_b64 exec, s[10:11]
	s_add_i32 s6, s0, 2175
	s_mul_hi_u32 s7, s6, s59
	s_lshr_b32 s7, s7, 7
	s_mulk_i32 s7, 0x810
	s_sub_i32 s6, s6, s7
	s_cmp_lt_u32 s6, 17
	s_cbranch_scc1 .Lffn1e_slow6
	v_mov_b32_dpp v228, v44 row_ror:1 row_mask:0xf bank_mask:0xf
	v_mov_b32_dpp v229, v44 row_ror:2 row_mask:0xf bank_mask:0xf
	v_mov_b32_dpp v230, v45 row_ror:1 row_mask:0xf bank_mask:0xf
	v_mov_b32_dpp v231, v45 row_ror:2 row_mask:0xf bank_mask:0xf
	v_mov_b32_dpp v232, v46 row_ror:1 row_mask:0xf bank_mask:0xf
	v_mov_b32_dpp v233, v46 row_ror:2 row_mask:0xf bank_mask:0xf
	v_mov_b32_dpp v234, v47 row_ror:1 row_mask:0xf bank_mask:0xf
	v_mov_b32_dpp v235, v47 row_ror:2 row_mask:0xf bank_mask:0xf
	v_mov_b32_dpp v228, v28 row_shr:1 row_mask:0xf bank_mask:0xf
	v_mov_b32_dpp v229, v28 row_shr:2 row_mask:0xf bank_mask:0xf
	v_mov_b32_dpp v230, v29 row_shr:1 row_mask:0xf bank_mask:0xf
	v_mov_b32_dpp v231, v29 row_shr:2 row_mask:0xf bank_mask:0xf
	v_mov_b32_dpp v232, v30 row_shr:1 row_mask:0xf bank_mask:0xf
	v_mov_b32_dpp v233, v30 row_shr:2 row_mask:0xf bank_mask:0xf
	v_mov_b32_dpp v234, v31 row_shr:1 row_mask:0xf bank_mask:0xf
	v_mov_b32_dpp v235, v31 row_shr:2 row_mask:0xf bank_mask:0xf
	v_fma_f32 v236, v229, v128, v208
	v_fma_f32 v237, v231, v129, v209
	v_fma_f32 v238, v233, v130, v210
	v_fma_f32 v239, v235, v131, v211
	v_fmac_f32_e32 v236, v228, v144
	v_fmac_f32_e32 v237, v230, v145
	v_fmac_f32_e32 v238, v232, v146
	v_fmac_f32_e32 v239, v234, v147
	v_fmac_f32_e32 v236, v28, v160
	v_fmac_f32_e32 v237, v29, v161
	v_fmac_f32_e32 v238, v30, v162
	v_fmac_f32_e32 v239, v31, v163
	v_mov_b32_dpp v228, v36 row_ror:1 row_mask:0xf bank_mask:0xf
	v_mov_b32_dpp v229, v36 row_ror:2 row_mask:0xf bank_mask:0xf
	v_mov_b32_dpp v230, v37 row_ror:1 row_mask:0xf bank_mask:0xf
	v_mov_b32_dpp v231, v37 row_ror:2 row_mask:0xf bank_mask:0xf
	v_mov_b32_dpp v232, v38 row_ror:1 row_mask:0xf bank_mask:0xf
	v_mov_b32_dpp v233, v38 row_ror:2 row_mask:0xf bank_mask:0xf
	v_mov_b32_dpp v234, v39 row_ror:1 row_mask:0xf bank_mask:0xf
	v_mov_b32_dpp v235, v39 row_ror:2 row_mask:0xf bank_mask:0xf
	v_mov_b32_dpp v228, v20 row_shr:1 row_mask:0xf bank_mask:0xf
	v_mov_b32_dpp v229, v20 row_shr:2 row_mask:0xf bank_mask:0xf
	v_mov_b32_dpp v230, v21 row_shr:1 row_mask:0xf bank_mask:0xf
	v_mov_b32_dpp v231, v21 row_shr:2 row_mask:0xf bank_mask:0xf
	v_mov_b32_dpp v232, v22 row_shr:1 row_mask:0xf bank_mask:0xf
	v_mov_b32_dpp v233, v22 row_shr:2 row_mask:0xf bank_mask:0xf
	v_mov_b32_dpp v234, v23 row_shr:1 row_mask:0xf bank_mask:0xf
	v_mov_b32_dpp v235, v23 row_shr:2 row_mask:0xf bank_mask:0xf
	v_fma_f32 v240, v229, v132, v212
	v_fma_f32 v241, v231, v133, v213
	v_fma_f32 v242, v233, v134, v214
	v_fma_f32 v243, v235, v135, v215
	v_fmac_f32_e32 v240, v228, v148
	v_fmac_f32_e32 v241, v230, v149
	v_fmac_f32_e32 v242, v232, v150
	v_fmac_f32_e32 v243, v234, v151
	v_fmac_f32_e32 v240, v20, v164
	v_fmac_f32_e32 v241, v21, v165
	v_fmac_f32_e32 v242, v22, v166
	v_fmac_f32_e32 v243, v23, v167
	v_mov_b32_e32 v228, 0xbdd2d3e8
	v_mul_f32_e32 v244, v236, v236
	v_mul_f32_e32 v245, v237, v237
	v_mul_f32_e32 v246, v238, v238
	v_mul_f32_e32 v247, v239, v239
	v_fmaak_f32 v244, v244, v228, 0xc0135761
	v_fmaak_f32 v245, v245, v228, 0xc0135761
	v_fmaak_f32 v246, v246, v228, 0xc0135761
	v_fmaak_f32 v247, v247, v228, 0xc0135761
	v_mul_f32_e32 v244, v236, v244
	v_mul_f32_e32 v245, v237, v245
	v_mul_f32_e32 v246, v238, v246
	v_mul_f32_e32 v247, v239, v247
	v_exp_f32_e32 v244, v244
	v_exp_f32_e32 v245, v245
	v_exp_f32_e32 v246, v246
	v_exp_f32_e32 v247, v247
	v_add_f32_e32 v244, 1.0, v244
	v_add_f32_e32 v245, 1.0, v245
	v_add_f32_e32 v246, 1.0, v246
	v_add_f32_e32 v247, 1.0, v247
	v_rcp_f32_e32 v244, v244
	v_rcp_f32_e32 v245, v245
	v_rcp_f32_e32 v246, v246
	v_rcp_f32_e32 v247, v247
	v_mul_f32_e32 v244, v236, v244
	v_mul_f32_e32 v245, v237, v245
	v_mul_f32_e32 v246, v238, v246
	v_mul_f32_e32 v247, v239, v247
	v_mul_f32_e32 v248, v240, v244
	v_mul_f32_e32 v249, v241, v245
	v_mul_f32_e32 v250, v242, v246
	v_mul_f32_e32 v251, v243, v247
	v_mov_b32_dpp v228, v40 row_ror:1 row_mask:0xf bank_mask:0xf
	v_mov_b32_dpp v229, v40 row_ror:2 row_mask:0xf bank_mask:0xf
	v_mov_b32_dpp v230, v41 row_ror:1 row_mask:0xf bank_mask:0xf
	v_mov_b32_dpp v231, v41 row_ror:2 row_mask:0xf bank_mask:0xf
	v_mov_b32_dpp v232, v42 row_ror:1 row_mask:0xf bank_mask:0xf
	v_mov_b32_dpp v233, v42 row_ror:2 row_mask:0xf bank_mask:0xf
	v_mov_b32_dpp v234, v43 row_ror:1 row_mask:0xf bank_mask:0xf
	v_mov_b32_dpp v235, v43 row_ror:2 row_mask:0xf bank_mask:0xf
	v_mov_b32_dpp v228, v24 row_shr:1 row_mask:0xf bank_mask:0xf
	v_mov_b32_dpp v229, v24 row_shr:2 row_mask:0xf bank_mask:0xf
	v_mov_b32_dpp v230, v25 row_shr:1 row_mask:0xf bank_mask:0xf
	v_mov_b32_dpp v231, v25 row_shr:2 row_mask:0xf bank_mask:0xf
	v_mov_b32_dpp v232, v26 row_shr:1 row_mask:0xf bank_mask:0xf
	v_mov_b32_dpp v233, v26 row_shr:2 row_mask:0xf bank_mask:0xf
	v_mov_b32_dpp v234, v27 row_shr:1 row_mask:0xf bank_mask:0xf
	v_mov_b32_dpp v235, v27 row_shr:2 row_mask:0xf bank_mask:0xf
	v_fma_f32 v236, v229, v136, v220
	v_fma_f32 v237, v231, v137, v221
	v_fma_f32 v238, v233, v138, v222
	v_fma_f32 v239, v235, v139, v223
	v_fmac_f32_e32 v236, v228, v152
	v_fmac_f32_e32 v237, v230, v153
	v_fmac_f32_e32 v238, v232, v154
	v_fmac_f32_e32 v239, v234, v155
	v_fmac_f32_e32 v236, v24, v168
	v_fmac_f32_e32 v237, v25, v169
	v_fmac_f32_e32 v238, v26, v170
	v_fmac_f32_e32 v239, v27, v171
	v_mov_b32_dpp v228, v32 row_ror:1 row_mask:0xf bank_mask:0xf
	v_mov_b32_dpp v229, v32 row_ror:2 row_mask:0xf bank_mask:0xf
	v_mov_b32_dpp v230, v33 row_ror:1 row_mask:0xf bank_mask:0xf
	v_mov_b32_dpp v231, v33 row_ror:2 row_mask:0xf bank_mask:0xf
	v_mov_b32_dpp v232, v34 row_ror:1 row_mask:0xf bank_mask:0xf
	v_mov_b32_dpp v233, v34 row_ror:2 row_mask:0xf bank_mask:0xf
	v_mov_b32_dpp v234, v35 row_ror:1 row_mask:0xf bank_mask:0xf
	v_mov_b32_dpp v235, v35 row_ror:2 row_mask:0xf bank_mask:0xf
	v_mov_b32_dpp v228, v16 row_shr:1 row_mask:0xf bank_mask:0xf
	v_mov_b32_dpp v229, v16 row_shr:2 row_mask:0xf bank_mask:0xf
	v_mov_b32_dpp v230, v17 row_shr:1 row_mask:0xf bank_mask:0xf
	v_mov_b32_dpp v231, v17 row_shr:2 row_mask:0xf bank_mask:0xf
	v_mov_b32_dpp v232, v18 row_shr:1 row_mask:0xf bank_mask:0xf
	v_mov_b32_dpp v233, v18 row_shr:2 row_mask:0xf bank_mask:0xf
	v_mov_b32_dpp v234, v19 row_shr:1 row_mask:0xf bank_mask:0xf
	v_mov_b32_dpp v235, v19 row_shr:2 row_mask:0xf bank_mask:0xf
	v_fma_f32 v240, v229, v140, v224
	v_fma_f32 v241, v231, v141, v225
	v_fma_f32 v242, v233, v142, v226
	v_fma_f32 v243, v235, v143, v227
	v_fmac_f32_e32 v240, v228, v156
	v_fmac_f32_e32 v241, v230, v157
	v_fmac_f32_e32 v242, v232, v158
	v_fmac_f32_e32 v243, v234, v159
	v_fmac_f32_e32 v240, v16, v204
	v_fmac_f32_e32 v241, v17, v205
	v_fmac_f32_e32 v242, v18, v206
	v_fmac_f32_e32 v243, v19, v207
	v_mov_b32_e32 v228, 0xbdd2d3e8
	v_mul_f32_e32 v244, v236, v236
	v_mul_f32_e32 v245, v237, v237
	v_mul_f32_e32 v246, v238, v238
	v_mul_f32_e32 v247, v239, v239
	v_fmaak_f32 v244, v244, v228, 0xc0135761
	v_fmaak_f32 v245, v245, v228, 0xc0135761
	v_fmaak_f32 v246, v246, v228, 0xc0135761
	v_fmaak_f32 v247, v247, v228, 0xc0135761
	v_mul_f32_e32 v244, v236, v244
	v_mul_f32_e32 v245, v237, v245
	v_mul_f32_e32 v246, v238, v246
	v_mul_f32_e32 v247, v239, v247
	v_exp_f32_e32 v244, v244
	v_exp_f32_e32 v245, v245
	v_exp_f32_e32 v246, v246
	v_exp_f32_e32 v247, v247
	v_add_f32_e32 v244, 1.0, v244
	v_add_f32_e32 v245, 1.0, v245
	v_add_f32_e32 v246, 1.0, v246
	v_add_f32_e32 v247, 1.0, v247
	v_rcp_f32_e32 v244, v244
	v_rcp_f32_e32 v245, v245
	v_rcp_f32_e32 v246, v246
	v_rcp_f32_e32 v247, v247
	v_mul_f32_e32 v244, v236, v244
	v_mul_f32_e32 v245, v237, v245
	v_mul_f32_e32 v246, v238, v246
	v_mul_f32_e32 v247, v239, v247
	v_mul_f32_e32 v174, v240, v244
	v_mul_f32_e32 v175, v241, v245
	v_mul_f32_e32 v176, v242, v246
	v_mul_f32_e32 v177, v243, v247
	v_cvt_pk_bf16_f32 v180, v248, v249
	v_cvt_pk_bf16_f32 v181, v250, v251
	v_cvt_pk_bf16_f32 v182, v174, v175
	v_cvt_pk_bf16_f32 v183, v176, v177
.Lffn1e_store6:
	v_add_u32_e32 v252, 96, v218
	v_mad_i64_i32 v[216:217], vcc, v252, s79, v[190:191]
	v_cmp_gt_i32_e32 vcc, s58, v252
	s_nop 1
	s_and_saveexec_b64 s[10:11], vcc
	global_store_dwordx4 v[216:217], v[180:183], off sc1
	s_mov_b64 exec, s[10:11]
	s_add_i32 s6, s0, 2191
	s_mul_hi_u32 s7, s6, s59
	s_lshr_b32 s7, s7, 7
	s_mulk_i32 s7, 0x810
	s_sub_i32 s6, s6, s7
	s_cmp_lt_u32 s6, 17
	s_cbranch_scc1 .Lffn1e_slow7
	v_mov_b32_dpp v228, v28 row_ror:1 row_mask:0xf bank_mask:0xf
	v_mov_b32_dpp v229, v28 row_ror:2 row_mask:0xf bank_mask:0xf
	v_mov_b32_dpp v230, v29 row_ror:1 row_mask:0xf bank_mask:0xf
	v_mov_b32_dpp v231, v29 row_ror:2 row_mask:0xf bank_mask:0xf
	v_mov_b32_dpp v232, v30 row_ror:1 row_mask:0xf bank_mask:0xf
	v_mov_b32_dpp v233, v30 row_ror:2 row_mask:0xf bank_mask:0xf
	v_mov_b32_dpp v234, v31 row_ror:1 row_mask:0xf bank_mask:0xf
	v_mov_b32_dpp v235, v31 row_ror:2 row_mask:0xf bank_mask:0xf
	v_mov_b32_dpp v228, v4 row_shr:1 row_mask:0xf bank_mask:0xf
	v_mov_b32_dpp v229, v4 row_shr:2 row_mask:0xf bank_mask:0xf
	v_mov_b32_dpp v230, v5 row_shr:1 row_mask:0xf bank_mask:0xf
	v_mov_b32_dpp v231, v5 row_shr:2 row_mask:0xf bank_mask:0xf
	v_mov_b32_dpp v232, v6 row_shr:1 row_mask:0xf bank_mask:0xf
	v_mov_b32_dpp v233, v6 row_shr:2 row_mask:0xf bank_mask:0xf
	v_mov_b32_dpp v234, v7 row_shr:1 row_mask:0xf bank_mask:0xf
	v_mov_b32_dpp v235, v7 row_shr:2 row_mask:0xf bank_mask:0xf
	v_fma_f32 v236, v229, v128, v208
	v_fma_f32 v237, v231, v129, v209
	v_fma_f32 v238, v233, v130, v210
	v_fma_f32 v239, v235, v131, v211
	v_fmac_f32_e32 v236, v228, v144
	v_fmac_f32_e32 v237, v230, v145
	v_fmac_f32_e32 v238, v232, v146
	v_fmac_f32_e32 v239, v234, v147
	v_fmac_f32_e32 v236, v4, v160
	v_fmac_f32_e32 v237, v5, v161
	v_fmac_f32_e32 v238, v6, v162
	v_fmac_f32_e32 v239, v7, v163
	v_mov_b32_dpp v228, v20 row_ror:1 row_mask:0xf bank_mask:0xf
	v_mov_b32_dpp v229, v20 row_ror:2 row_mask:0xf bank_mask:0xf
	v_mov_b32_dpp v230, v21 row_ror:1 row_mask:0xf bank_mask:0xf
	v_mov_b32_dpp v231, v21 row_ror:2 row_mask:0xf bank_mask:0xf
	v_mov_b32_dpp v232, v22 row_ror:1 row_mask:0xf bank_mask:0xf
	v_mov_b32_dpp v233, v22 row_ror:2 row_mask:0xf bank_mask:0xf
	v_mov_b32_dpp v234, v23 row_ror:1 row_mask:0xf bank_mask:0xf
	v_mov_b32_dpp v235, v23 row_ror:2 row_mask:0xf bank_mask:0xf
	v_mov_b32_dpp v228, v8 row_shr:1 row_mask:0xf bank_mask:0xf
	v_mov_b32_dpp v229, v8 row_shr:2 row_mask:0xf bank_mask:0xf
	v_mov_b32_dpp v230, v9 row_shr:1 row_mask:0xf bank_mask:0xf
	v_mov_b32_dpp v231, v9 row_shr:2 row_mask:0xf bank_mask:0xf
	v_mov_b32_dpp v232, v10 row_shr:1 row_mask:0xf bank_mask:0xf
	v_mov_b32_dpp v233, v10 row_shr:2 row_mask:0xf bank_mask:0xf
	v_mov_b32_dpp v234, v11 row_shr:1 row_mask:0xf bank_mask:0xf
	v_mov_b32_dpp v235, v11 row_shr:2 row_mask:0xf bank_mask:0xf
	v_fma_f32 v240, v229, v132, v212
	v_fma_f32 v241, v231, v133, v213
	v_fma_f32 v242, v233, v134, v214
	v_fma_f32 v243, v235, v135, v215
	v_fmac_f32_e32 v240, v228, v148
	v_fmac_f32_e32 v241, v230, v149
	v_fmac_f32_e32 v242, v232, v150
	v_fmac_f32_e32 v243, v234, v151
	v_fmac_f32_e32 v240, v8, v164
	v_fmac_f32_e32 v241, v9, v165
	v_fmac_f32_e32 v242, v10, v166
	v_fmac_f32_e32 v243, v11, v167
	v_mov_b32_e32 v228, 0xbdd2d3e8
	v_mul_f32_e32 v244, v236, v236
	v_mul_f32_e32 v245, v237, v237
	v_mul_f32_e32 v246, v238, v238
	v_mul_f32_e32 v247, v239, v239
	v_fmaak_f32 v244, v244, v228, 0xc0135761
	v_fmaak_f32 v245, v245, v228, 0xc0135761
	v_fmaak_f32 v246, v246, v228, 0xc0135761
	v_fmaak_f32 v247, v247, v228, 0xc0135761
	v_mul_f32_e32 v244, v236, v244
	v_mul_f32_e32 v245, v237, v245
	v_mul_f32_e32 v246, v238, v246
	v_mul_f32_e32 v247, v239, v247
	v_exp_f32_e32 v244, v244
	v_exp_f32_e32 v245, v245
	v_exp_f32_e32 v246, v246
	v_exp_f32_e32 v247, v247
	v_add_f32_e32 v244, 1.0, v244
	v_add_f32_e32 v245, 1.0, v245
	v_add_f32_e32 v246, 1.0, v246
	v_add_f32_e32 v247, 1.0, v247
	v_rcp_f32_e32 v244, v244
	v_rcp_f32_e32 v245, v245
	v_rcp_f32_e32 v246, v246
	v_rcp_f32_e32 v247, v247
	v_mul_f32_e32 v244, v236, v244
	v_mul_f32_e32 v245, v237, v245
	v_mul_f32_e32 v246, v238, v246
	v_mul_f32_e32 v247, v239, v247
	v_mul_f32_e32 v248, v240, v244
	v_mul_f32_e32 v249, v241, v245
	v_mul_f32_e32 v250, v242, v246
	v_mul_f32_e32 v251, v243, v247
	v_mov_b32_dpp v228, v24 row_ror:1 row_mask:0xf bank_mask:0xf
	v_mov_b32_dpp v229, v24 row_ror:2 row_mask:0xf bank_mask:0xf
	v_mov_b32_dpp v230, v25 row_ror:1 row_mask:0xf bank_mask:0xf
	v_mov_b32_dpp v231, v25 row_ror:2 row_mask:0xf bank_mask:0xf
	v_mov_b32_dpp v232, v26 row_ror:1 row_mask:0xf bank_mask:0xf
	v_mov_b32_dpp v233, v26 row_ror:2 row_mask:0xf bank_mask:0xf
	v_mov_b32_dpp v234, v27 row_ror:1 row_mask:0xf bank_mask:0xf
	v_mov_b32_dpp v235, v27 row_ror:2 row_mask:0xf bank_mask:0xf
	v_mov_b32_dpp v228, v12 row_shr:1 row_mask:0xf bank_mask:0xf
	v_mov_b32_dpp v229, v12 row_shr:2 row_mask:0xf bank_mask:0xf
	v_mov_b32_dpp v230, v13 row_shr:1 row_mask:0xf bank_mask:0xf
	v_mov_b32_dpp v231, v13 row_shr:2 row_mask:0xf bank_mask:0xf
	v_mov_b32_dpp v232, v14 row_shr:1 row_mask:0xf bank_mask:0xf
	v_mov_b32_dpp v233, v14 row_shr:2 row_mask:0xf bank_mask:0xf
	v_mov_b32_dpp v234, v15 row_shr:1 row_mask:0xf bank_mask:0xf
	v_mov_b32_dpp v235, v15 row_shr:2 row_mask:0xf bank_mask:0xf
	v_fma_f32 v236, v229, v136, v220
	v_fma_f32 v237, v231, v137, v221
	v_fma_f32 v238, v233, v138, v222
	v_fma_f32 v239, v235, v139, v223
	v_fmac_f32_e32 v236, v228, v152
	v_fmac_f32_e32 v237, v230, v153
	v_fmac_f32_e32 v238, v232, v154
	v_fmac_f32_e32 v239, v234, v155
	v_fmac_f32_e32 v236, v12, v168
	v_fmac_f32_e32 v237, v13, v169
	v_fmac_f32_e32 v238, v14, v170
	v_fmac_f32_e32 v239, v15, v171
	v_mov_b32_dpp v228, v16 row_ror:1 row_mask:0xf bank_mask:0xf
	v_mov_b32_dpp v229, v16 row_ror:2 row_mask:0xf bank_mask:0xf
	v_mov_b32_dpp v230, v17 row_ror:1 row_mask:0xf bank_mask:0xf
	v_mov_b32_dpp v231, v17 row_ror:2 row_mask:0xf bank_mask:0xf
	v_mov_b32_dpp v232, v18 row_ror:1 row_mask:0xf bank_mask:0xf
	v_mov_b32_dpp v233, v18 row_ror:2 row_mask:0xf bank_mask:0xf
	v_mov_b32_dpp v234, v19 row_ror:1 row_mask:0xf bank_mask:0xf
	v_mov_b32_dpp v235, v19 row_ror:2 row_mask:0xf bank_mask:0xf
	v_mov_b32_dpp v228, v0 row_shr:1 row_mask:0xf bank_mask:0xf
	v_mov_b32_dpp v229, v0 row_shr:2 row_mask:0xf bank_mask:0xf
	v_mov_b32_dpp v230, v1 row_shr:1 row_mask:0xf bank_mask:0xf
	v_mov_b32_dpp v231, v1 row_shr:2 row_mask:0xf bank_mask:0xf
	v_mov_b32_dpp v232, v2 row_shr:1 row_mask:0xf bank_mask:0xf
	v_mov_b32_dpp v233, v2 row_shr:2 row_mask:0xf bank_mask:0xf
	v_mov_b32_dpp v234, v3 row_shr:1 row_mask:0xf bank_mask:0xf
	v_mov_b32_dpp v235, v3 row_shr:2 row_mask:0xf bank_mask:0xf
	v_fma_f32 v240, v229, v140, v224
	v_fma_f32 v241, v231, v141, v225
	v_fma_f32 v242, v233, v142, v226
	v_fma_f32 v243, v235, v143, v227
	v_fmac_f32_e32 v240, v228, v156
	v_fmac_f32_e32 v241, v230, v157
	v_fmac_f32_e32 v242, v232, v158
	v_fmac_f32_e32 v243, v234, v159
	v_fmac_f32_e32 v240, v0, v204
	v_fmac_f32_e32 v241, v1, v205
	v_fmac_f32_e32 v242, v2, v206
	v_fmac_f32_e32 v243, v3, v207
	v_mov_b32_e32 v228, 0xbdd2d3e8
	v_mul_f32_e32 v244, v236, v236
	v_mul_f32_e32 v245, v237, v237
	v_mul_f32_e32 v246, v238, v238
	v_mul_f32_e32 v247, v239, v239
	v_fmaak_f32 v244, v244, v228, 0xc0135761
	v_fmaak_f32 v245, v245, v228, 0xc0135761
	v_fmaak_f32 v246, v246, v228, 0xc0135761
	v_fmaak_f32 v247, v247, v228, 0xc0135761
	v_mul_f32_e32 v244, v236, v244
	v_mul_f32_e32 v245, v237, v245
	v_mul_f32_e32 v246, v238, v246
	v_mul_f32_e32 v247, v239, v247
	v_exp_f32_e32 v244, v244
	v_exp_f32_e32 v245, v245
	v_exp_f32_e32 v246, v246
	v_exp_f32_e32 v247, v247
	v_add_f32_e32 v244, 1.0, v244
	v_add_f32_e32 v245, 1.0, v245
	v_add_f32_e32 v246, 1.0, v246
	v_add_f32_e32 v247, 1.0, v247
	v_rcp_f32_e32 v244, v244
	v_rcp_f32_e32 v245, v245
	v_rcp_f32_e32 v246, v246
	v_rcp_f32_e32 v247, v247
	v_mul_f32_e32 v244, v236, v244
	v_mul_f32_e32 v245, v237, v245
	v_mul_f32_e32 v246, v238, v246
	v_mul_f32_e32 v247, v239, v247
	v_mul_f32_e32 v174, v240, v244
	v_mul_f32_e32 v175, v241, v245
	v_mul_f32_e32 v176, v242, v246
	v_mul_f32_e32 v177, v243, v247
	v_cvt_pk_bf16_f32 v180, v248, v249
	v_cvt_pk_bf16_f32 v181, v250, v251
	v_cvt_pk_bf16_f32 v182, v174, v175
	v_cvt_pk_bf16_f32 v183, v176, v177

.Lffn1e_slow0:
	v_add_u32_e32 v189, 2064, v218
	v_mul_hi_u32 v203, v189, s59
	v_lshrrev_b32_e32 v203, 7, v203
	v_mul_u32_u24_e32 v203, 0x810, v203
	v_sub_u32_e32 v189, v189, v203
	v_cmp_lt_u32_e32 vcc, 0, v189
	v_cmp_lt_u32_e64 s[8:9], 1, v189
	s_nop 1
	v_mov_b32_dpp v228, v124 row_shr:1 row_mask:0xf bank_mask:0xf bound_ctrl:1
	v_mov_b32_dpp v229, v124 row_shr:2 row_mask:0xf bank_mask:0xf bound_ctrl:1
	v_mov_b32_dpp v230, v125 row_shr:1 row_mask:0xf bank_mask:0xf bound_ctrl:1
	v_mov_b32_dpp v231, v125 row_shr:2 row_mask:0xf bank_mask:0xf bound_ctrl:1
	v_mov_b32_dpp v232, v126 row_shr:1 row_mask:0xf bank_mask:0xf bound_ctrl:1
	v_mov_b32_dpp v233, v126 row_shr:2 row_mask:0xf bank_mask:0xf bound_ctrl:1
	v_mov_b32_dpp v234, v127 row_shr:1 row_mask:0xf bank_mask:0xf bound_ctrl:1
	v_mov_b32_dpp v235, v127 row_shr:2 row_mask:0xf bank_mask:0xf bound_ctrl:1
	v_cndmask_b32_e64 v228, 0, v228, vcc
	v_cndmask_b32_e64 v229, 0, v229, s[8:9]
	v_cndmask_b32_e64 v230, 0, v230, vcc
	v_cndmask_b32_e64 v231, 0, v231, s[8:9]
	v_cndmask_b32_e64 v232, 0, v232, vcc
	v_cndmask_b32_e64 v233, 0, v233, s[8:9]
	v_cndmask_b32_e64 v234, 0, v234, vcc
	v_cndmask_b32_e64 v235, 0, v235, s[8:9]
	v_fma_f32 v236, v229, v128, v208
	v_fma_f32 v237, v231, v129, v209
	v_fma_f32 v238, v233, v130, v210
	v_fma_f32 v239, v235, v131, v211
	v_fmac_f32_e32 v236, v228, v144
	v_fmac_f32_e32 v237, v230, v145
	v_fmac_f32_e32 v238, v232, v146
	v_fmac_f32_e32 v239, v234, v147
	v_fmac_f32_e32 v236, v124, v160
	v_fmac_f32_e32 v237, v125, v161
	v_fmac_f32_e32 v238, v126, v162
	v_fmac_f32_e32 v239, v127, v163
	v_mov_b32_dpp v228, v116 row_shr:1 row_mask:0xf bank_mask:0xf bound_ctrl:1
	v_mov_b32_dpp v229, v116 row_shr:2 row_mask:0xf bank_mask:0xf bound_ctrl:1
	v_mov_b32_dpp v230, v117 row_shr:1 row_mask:0xf bank_mask:0xf bound_ctrl:1
	v_mov_b32_dpp v231, v117 row_shr:2 row_mask:0xf bank_mask:0xf bound_ctrl:1
	v_mov_b32_dpp v232, v118 row_shr:1 row_mask:0xf bank_mask:0xf bound_ctrl:1
	v_mov_b32_dpp v233, v118 row_shr:2 row_mask:0xf bank_mask:0xf bound_ctrl:1
	v_mov_b32_dpp v234, v119 row_shr:1 row_mask:0xf bank_mask:0xf bound_ctrl:1
	v_mov_b32_dpp v235, v119 row_shr:2 row_mask:0xf bank_mask:0xf bound_ctrl:1
	v_cndmask_b32_e64 v228, 0, v228, vcc
	v_cndmask_b32_e64 v229, 0, v229, s[8:9]
	v_cndmask_b32_e64 v230, 0, v230, vcc
	v_cndmask_b32_e64 v231, 0, v231, s[8:9]
	v_cndmask_b32_e64 v232, 0, v232, vcc
	v_cndmask_b32_e64 v233, 0, v233, s[8:9]
	v_cndmask_b32_e64 v234, 0, v234, vcc
	v_cndmask_b32_e64 v235, 0, v235, s[8:9]
	v_fma_f32 v240, v229, v132, v212
	v_fma_f32 v241, v231, v133, v213
	v_fma_f32 v242, v233, v134, v214
	v_fma_f32 v243, v235, v135, v215
	v_fmac_f32_e32 v240, v228, v148
	v_fmac_f32_e32 v241, v230, v149
	v_fmac_f32_e32 v242, v232, v150
	v_fmac_f32_e32 v243, v234, v151
	v_fmac_f32_e32 v240, v116, v164
	v_fmac_f32_e32 v241, v117, v165
	v_fmac_f32_e32 v242, v118, v166
	v_fmac_f32_e32 v243, v119, v167
	v_mov_b32_e32 v228, 0xbdd2d3e8
	v_mul_f32_e32 v244, v236, v236
	v_mul_f32_e32 v245, v237, v237
	v_mul_f32_e32 v246, v238, v238
	v_mul_f32_e32 v247, v239, v239
	v_fmaak_f32 v244, v244, v228, 0xc0135761
	v_fmaak_f32 v245, v245, v228, 0xc0135761
	v_fmaak_f32 v246, v246, v228, 0xc0135761
	v_fmaak_f32 v247, v247, v228, 0xc0135761
	v_mul_f32_e32 v244, v236, v244
	v_mul_f32_e32 v245, v237, v245
	v_mul_f32_e32 v246, v238, v246
	v_mul_f32_e32 v247, v239, v247
	v_exp_f32_e32 v244, v244
	v_exp_f32_e32 v245, v245
	v_exp_f32_e32 v246, v246
	v_exp_f32_e32 v247, v247
	v_add_f32_e32 v244, 1.0, v244
	v_add_f32_e32 v245, 1.0, v245
	v_add_f32_e32 v246, 1.0, v246
	v_add_f32_e32 v247, 1.0, v247
	v_rcp_f32_e32 v244, v244
	v_rcp_f32_e32 v245, v245
	v_rcp_f32_e32 v246, v246
	v_rcp_f32_e32 v247, v247
	v_mul_f32_e32 v244, v236, v244
	v_mul_f32_e32 v245, v237, v245
	v_mul_f32_e32 v246, v238, v246
	v_mul_f32_e32 v247, v239, v247
	v_mul_f32_e32 v248, v240, v244
	v_mul_f32_e32 v249, v241, v245
	v_mul_f32_e32 v250, v242, v246
	v_mul_f32_e32 v251, v243, v247
	v_mov_b32_dpp v228, v120 row_shr:1 row_mask:0xf bank_mask:0xf bound_ctrl:1
	v_mov_b32_dpp v229, v120 row_shr:2 row_mask:0xf bank_mask:0xf bound_ctrl:1
	v_mov_b32_dpp v230, v121 row_shr:1 row_mask:0xf bank_mask:0xf bound_ctrl:1
	v_mov_b32_dpp v231, v121 row_shr:2 row_mask:0xf bank_mask:0xf bound_ctrl:1
	v_mov_b32_dpp v232, v122 row_shr:1 row_mask:0xf bank_mask:0xf bound_ctrl:1
	v_mov_b32_dpp v233, v122 row_shr:2 row_mask:0xf bank_mask:0xf bound_ctrl:1
	v_mov_b32_dpp v234, v123 row_shr:1 row_mask:0xf bank_mask:0xf bound_ctrl:1
	v_mov_b32_dpp v235, v123 row_shr:2 row_mask:0xf bank_mask:0xf bound_ctrl:1
	v_cndmask_b32_e64 v228, 0, v228, vcc
	v_cndmask_b32_e64 v229, 0, v229, s[8:9]
	v_cndmask_b32_e64 v230, 0, v230, vcc
	v_cndmask_b32_e64 v231, 0, v231, s[8:9]
	v_cndmask_b32_e64 v232, 0, v232, vcc
	v_cndmask_b32_e64 v233, 0, v233, s[8:9]
	v_cndmask_b32_e64 v234, 0, v234, vcc
	v_cndmask_b32_e64 v235, 0, v235, s[8:9]
	v_fma_f32 v236, v229, v136, v220
	v_fma_f32 v237, v231, v137, v221
	v_fma_f32 v238, v233, v138, v222
	v_fma_f32 v239, v235, v139, v223
	v_fmac_f32_e32 v236, v228, v152
	v_fmac_f32_e32 v237, v230, v153
	v_fmac_f32_e32 v238, v232, v154
	v_fmac_f32_e32 v239, v234, v155
	v_fmac_f32_e32 v236, v120, v168
	v_fmac_f32_e32 v237, v121, v169
	v_fmac_f32_e32 v238, v122, v170
	v_fmac_f32_e32 v239, v123, v171
	v_mov_b32_dpp v228, v112 row_shr:1 row_mask:0xf bank_mask:0xf bound_ctrl:1
	v_mov_b32_dpp v229, v112 row_shr:2 row_mask:0xf bank_mask:0xf bound_ctrl:1
	v_mov_b32_dpp v230, v113 row_shr:1 row_mask:0xf bank_mask:0xf bound_ctrl:1
	v_mov_b32_dpp v231, v113 row_shr:2 row_mask:0xf bank_mask:0xf bound_ctrl:1
	v_mov_b32_dpp v232, v114 row_shr:1 row_mask:0xf bank_mask:0xf bound_ctrl:1
	v_mov_b32_dpp v233, v114 row_shr:2 row_mask:0xf bank_mask:0xf bound_ctrl:1
	v_mov_b32_dpp v234, v115 row_shr:1 row_mask:0xf bank_mask:0xf bound_ctrl:1
	v_mov_b32_dpp v235, v115 row_shr:2 row_mask:0xf bank_mask:0xf bound_ctrl:1
	v_cndmask_b32_e64 v228, 0, v228, vcc
	v_cndmask_b32_e64 v229, 0, v229, s[8:9]
	v_cndmask_b32_e64 v230, 0, v230, vcc
	v_cndmask_b32_e64 v231, 0, v231, s[8:9]
	v_cndmask_b32_e64 v232, 0, v232, vcc
	v_cndmask_b32_e64 v233, 0, v233, s[8:9]
	v_cndmask_b32_e64 v234, 0, v234, vcc
	v_cndmask_b32_e64 v235, 0, v235, s[8:9]
	v_fma_f32 v240, v229, v140, v224
	v_fma_f32 v241, v231, v141, v225
	v_fma_f32 v242, v233, v142, v226
	v_fma_f32 v243, v235, v143, v227
	v_fmac_f32_e32 v240, v228, v156
	v_fmac_f32_e32 v241, v230, v157
	v_fmac_f32_e32 v242, v232, v158
	v_fmac_f32_e32 v243, v234, v159
	v_fmac_f32_e32 v240, v112, v204
	v_fmac_f32_e32 v241, v113, v205
	v_fmac_f32_e32 v242, v114, v206
	v_fmac_f32_e32 v243, v115, v207
	v_mov_b32_e32 v228, 0xbdd2d3e8
	v_mul_f32_e32 v244, v236, v236
	v_mul_f32_e32 v245, v237, v237
	v_mul_f32_e32 v246, v238, v238
	v_mul_f32_e32 v247, v239, v239
	v_fmaak_f32 v244, v244, v228, 0xc0135761
	v_fmaak_f32 v245, v245, v228, 0xc0135761
	v_fmaak_f32 v246, v246, v228, 0xc0135761
	v_fmaak_f32 v247, v247, v228, 0xc0135761
	v_mul_f32_e32 v244, v236, v244
	v_mul_f32_e32 v245, v237, v245
	v_mul_f32_e32 v246, v238, v246
	v_mul_f32_e32 v247, v239, v247
	v_exp_f32_e32 v244, v244
	v_exp_f32_e32 v245, v245
	v_exp_f32_e32 v246, v246
	v_exp_f32_e32 v247, v247
	v_add_f32_e32 v244, 1.0, v244
	v_add_f32_e32 v245, 1.0, v245
	v_add_f32_e32 v246, 1.0, v246
	v_add_f32_e32 v247, 1.0, v247
	v_rcp_f32_e32 v244, v244
	v_rcp_f32_e32 v245, v245
	v_rcp_f32_e32 v246, v246
	v_rcp_f32_e32 v247, v247
	v_mul_f32_e32 v244, v236, v244
	v_mul_f32_e32 v245, v237, v245
	v_mul_f32_e32 v246, v238, v246
	v_mul_f32_e32 v247, v239, v247
	v_mul_f32_e32 v174, v240, v244
	v_mul_f32_e32 v175, v241, v245
	v_mul_f32_e32 v176, v242, v246
	v_mul_f32_e32 v177, v243, v247
	v_cvt_pk_bf16_f32 v180, v248, v249
	v_cvt_pk_bf16_f32 v181, v250, v251
	v_cvt_pk_bf16_f32 v182, v174, v175
	v_cvt_pk_bf16_f32 v183, v176, v177
	s_branch .Lffn1e_store0
.Lffn1e_slow1:
	v_add_u32_e32 v189, 2080, v218
	v_mul_hi_u32 v203, v189, s59
	v_lshrrev_b32_e32 v203, 7, v203
	v_mul_u32_u24_e32 v203, 0x810, v203
	v_sub_u32_e32 v189, v189, v203
	v_cmp_lt_u32_e32 vcc, 0, v189
	v_cmp_lt_u32_e64 s[8:9], 1, v189
	s_nop 1
	v_mov_b32_dpp v228, v124 row_ror:1 row_mask:0xf bank_mask:0xf
	v_mov_b32_dpp v229, v124 row_ror:2 row_mask:0xf bank_mask:0xf
	v_mov_b32_dpp v230, v125 row_ror:1 row_mask:0xf bank_mask:0xf
	v_mov_b32_dpp v231, v125 row_ror:2 row_mask:0xf bank_mask:0xf
	v_mov_b32_dpp v232, v126 row_ror:1 row_mask:0xf bank_mask:0xf
	v_mov_b32_dpp v233, v126 row_ror:2 row_mask:0xf bank_mask:0xf
	v_mov_b32_dpp v234, v127 row_ror:1 row_mask:0xf bank_mask:0xf
	v_mov_b32_dpp v235, v127 row_ror:2 row_mask:0xf bank_mask:0xf
	v_mov_b32_dpp v228, v108 row_shr:1 row_mask:0xf bank_mask:0xf
	v_mov_b32_dpp v229, v108 row_shr:2 row_mask:0xf bank_mask:0xf
	v_mov_b32_dpp v230, v109 row_shr:1 row_mask:0xf bank_mask:0xf
	v_mov_b32_dpp v231, v109 row_shr:2 row_mask:0xf bank_mask:0xf
	v_mov_b32_dpp v232, v110 row_shr:1 row_mask:0xf bank_mask:0xf
	v_mov_b32_dpp v233, v110 row_shr:2 row_mask:0xf bank_mask:0xf
	v_mov_b32_dpp v234, v111 row_shr:1 row_mask:0xf bank_mask:0xf
	v_mov_b32_dpp v235, v111 row_shr:2 row_mask:0xf bank_mask:0xf
	v_cndmask_b32_e64 v228, 0, v228, vcc
	v_cndmask_b32_e64 v229, 0, v229, s[8:9]
	v_cndmask_b32_e64 v230, 0, v230, vcc
	v_cndmask_b32_e64 v231, 0, v231, s[8:9]
	v_cndmask_b32_e64 v232, 0, v232, vcc
	v_cndmask_b32_e64 v233, 0, v233, s[8:9]
	v_cndmask_b32_e64 v234, 0, v234, vcc
	v_cndmask_b32_e64 v235, 0, v235, s[8:9]
	v_fma_f32 v236, v229, v128, v208
	v_fma_f32 v237, v231, v129, v209
	v_fma_f32 v238, v233, v130, v210
	v_fma_f32 v239, v235, v131, v211
	v_fmac_f32_e32 v236, v228, v144
	v_fmac_f32_e32 v237, v230, v145
	v_fmac_f32_e32 v238, v232, v146
	v_fmac_f32_e32 v239, v234, v147
	v_fmac_f32_e32 v236, v108, v160
	v_fmac_f32_e32 v237, v109, v161
	v_fmac_f32_e32 v238, v110, v162
	v_fmac_f32_e32 v239, v111, v163
	v_mov_b32_dpp v228, v116 row_ror:1 row_mask:0xf bank_mask:0xf
	v_mov_b32_dpp v229, v116 row_ror:2 row_mask:0xf bank_mask:0xf
	v_mov_b32_dpp v230, v117 row_ror:1 row_mask:0xf bank_mask:0xf
	v_mov_b32_dpp v231, v117 row_ror:2 row_mask:0xf bank_mask:0xf
	v_mov_b32_dpp v232, v118 row_ror:1 row_mask:0xf bank_mask:0xf
	v_mov_b32_dpp v233, v118 row_ror:2 row_mask:0xf bank_mask:0xf
	v_mov_b32_dpp v234, v119 row_ror:1 row_mask:0xf bank_mask:0xf
	v_mov_b32_dpp v235, v119 row_ror:2 row_mask:0xf bank_mask:0xf
	v_mov_b32_dpp v228, v100 row_shr:1 row_mask:0xf bank_mask:0xf
	v_mov_b32_dpp v229, v100 row_shr:2 row_mask:0xf bank_mask:0xf
	v_mov_b32_dpp v230, v101 row_shr:1 row_mask:0xf bank_mask:0xf
	v_mov_b32_dpp v231, v101 row_shr:2 row_mask:0xf bank_mask:0xf
	v_mov_b32_dpp v232, v102 row_shr:1 row_mask:0xf bank_mask:0xf
	v_mov_b32_dpp v233, v102 row_shr:2 row_mask:0xf bank_mask:0xf
	v_mov_b32_dpp v234, v103 row_shr:1 row_mask:0xf bank_mask:0xf
	v_mov_b32_dpp v235, v103 row_shr:2 row_mask:0xf bank_mask:0xf
	v_cndmask_b32_e64 v228, 0, v228, vcc
	v_cndmask_b32_e64 v229, 0, v229, s[8:9]
	v_cndmask_b32_e64 v230, 0, v230, vcc
	v_cndmask_b32_e64 v231, 0, v231, s[8:9]
	v_cndmask_b32_e64 v232, 0, v232, vcc
	v_cndmask_b32_e64 v233, 0, v233, s[8:9]
	v_cndmask_b32_e64 v234, 0, v234, vcc
	v_cndmask_b32_e64 v235, 0, v235, s[8:9]
	v_fma_f32 v240, v229, v132, v212
	v_fma_f32 v241, v231, v133, v213
	v_fma_f32 v242, v233, v134, v214
	v_fma_f32 v243, v235, v135, v215
	v_fmac_f32_e32 v240, v228, v148
	v_fmac_f32_e32 v241, v230, v149
	v_fmac_f32_e32 v242, v232, v150
	v_fmac_f32_e32 v243, v234, v151
	v_fmac_f32_e32 v240, v100, v164
	v_fmac_f32_e32 v241, v101, v165
	v_fmac_f32_e32 v242, v102, v166
	v_fmac_f32_e32 v243, v103, v167
	v_mov_b32_e32 v228, 0xbdd2d3e8
	v_mul_f32_e32 v244, v236, v236
	v_mul_f32_e32 v245, v237, v237
	v_mul_f32_e32 v246, v238, v238
	v_mul_f32_e32 v247, v239, v239
	v_fmaak_f32 v244, v244, v228, 0xc0135761
	v_fmaak_f32 v245, v245, v228, 0xc0135761
	v_fmaak_f32 v246, v246, v228, 0xc0135761
	v_fmaak_f32 v247, v247, v228, 0xc0135761
	v_mul_f32_e32 v244, v236, v244
	v_mul_f32_e32 v245, v237, v245
	v_mul_f32_e32 v246, v238, v246
	v_mul_f32_e32 v247, v239, v247
	v_exp_f32_e32 v244, v244
	v_exp_f32_e32 v245, v245
	v_exp_f32_e32 v246, v246
	v_exp_f32_e32 v247, v247
	v_add_f32_e32 v244, 1.0, v244
	v_add_f32_e32 v245, 1.0, v245
	v_add_f32_e32 v246, 1.0, v246
	v_add_f32_e32 v247, 1.0, v247
	v_rcp_f32_e32 v244, v244
	v_rcp_f32_e32 v245, v245
	v_rcp_f32_e32 v246, v246
	v_rcp_f32_e32 v247, v247
	v_mul_f32_e32 v244, v236, v244
	v_mul_f32_e32 v245, v237, v245
	v_mul_f32_e32 v246, v238, v246
	v_mul_f32_e32 v247, v239, v247
	v_mul_f32_e32 v248, v240, v244
	v_mul_f32_e32 v249, v241, v245
	v_mul_f32_e32 v250, v242, v246
	v_mul_f32_e32 v251, v243, v247
	v_mov_b32_dpp v228, v120 row_ror:1 row_mask:0xf bank_mask:0xf
	v_mov_b32_dpp v229, v120 row_ror:2 row_mask:0xf bank_mask:0xf
	v_mov_b32_dpp v230, v121 row_ror:1 row_mask:0xf bank_mask:0xf
	v_mov_b32_dpp v231, v121 row_ror:2 row_mask:0xf bank_mask:0xf
	v_mov_b32_dpp v232, v122 row_ror:1 row_mask:0xf bank_mask:0xf
	v_mov_b32_dpp v233, v122 row_ror:2 row_mask:0xf bank_mask:0xf
	v_mov_b32_dpp v234, v123 row_ror:1 row_mask:0xf bank_mask:0xf
	v_mov_b32_dpp v235, v123 row_ror:2 row_mask:0xf bank_mask:0xf
	v_mov_b32_dpp v228, v104 row_shr:1 row_mask:0xf bank_mask:0xf
	v_mov_b32_dpp v229, v104 row_shr:2 row_mask:0xf bank_mask:0xf
	v_mov_b32_dpp v230, v105 row_shr:1 row_mask:0xf bank_mask:0xf
	v_mov_b32_dpp v231, v105 row_shr:2 row_mask:0xf bank_mask:0xf
	v_mov_b32_dpp v232, v106 row_shr:1 row_mask:0xf bank_mask:0xf
	v_mov_b32_dpp v233, v106 row_shr:2 row_mask:0xf bank_mask:0xf
	v_mov_b32_dpp v234, v107 row_shr:1 row_mask:0xf bank_mask:0xf
	v_mov_b32_dpp v235, v107 row_shr:2 row_mask:0xf bank_mask:0xf
	v_cndmask_b32_e64 v228, 0, v228, vcc
	v_cndmask_b32_e64 v229, 0, v229, s[8:9]
	v_cndmask_b32_e64 v230, 0, v230, vcc
	v_cndmask_b32_e64 v231, 0, v231, s[8:9]
	v_cndmask_b32_e64 v232, 0, v232, vcc
	v_cndmask_b32_e64 v233, 0, v233, s[8:9]
	v_cndmask_b32_e64 v234, 0, v234, vcc
	v_cndmask_b32_e64 v235, 0, v235, s[8:9]
	v_fma_f32 v236, v229, v136, v220
	v_fma_f32 v237, v231, v137, v221
	v_fma_f32 v238, v233, v138, v222
	v_fma_f32 v239, v235, v139, v223
	v_fmac_f32_e32 v236, v228, v152
	v_fmac_f32_e32 v237, v230, v153
	v_fmac_f32_e32 v238, v232, v154
	v_fmac_f32_e32 v239, v234, v155
	v_fmac_f32_e32 v236, v104, v168
	v_fmac_f32_e32 v237, v105, v169
	v_fmac_f32_e32 v238, v106, v170
	v_fmac_f32_e32 v239, v107, v171
	v_mov_b32_dpp v228, v112 row_ror:1 row_mask:0xf bank_mask:0xf
	v_mov_b32_dpp v229, v112 row_ror:2 row_mask:0xf bank_mask:0xf
	v_mov_b32_dpp v230, v113 row_ror:1 row_mask:0xf bank_mask:0xf
	v_mov_b32_dpp v231, v113 row_ror:2 row_mask:0xf bank_mask:0xf
	v_mov_b32_dpp v232, v114 row_ror:1 row_mask:0xf bank_mask:0xf
	v_mov_b32_dpp v233, v114 row_ror:2 row_mask:0xf bank_mask:0xf
	v_mov_b32_dpp v234, v115 row_ror:1 row_mask:0xf bank_mask:0xf
	v_mov_b32_dpp v235, v115 row_ror:2 row_mask:0xf bank_mask:0xf
	v_mov_b32_dpp v228, v96 row_shr:1 row_mask:0xf bank_mask:0xf
	v_mov_b32_dpp v229, v96 row_shr:2 row_mask:0xf bank_mask:0xf
	v_mov_b32_dpp v230, v97 row_shr:1 row_mask:0xf bank_mask:0xf
	v_mov_b32_dpp v231, v97 row_shr:2 row_mask:0xf bank_mask:0xf
	v_mov_b32_dpp v232, v98 row_shr:1 row_mask:0xf bank_mask:0xf
	v_mov_b32_dpp v233, v98 row_shr:2 row_mask:0xf bank_mask:0xf
	v_mov_b32_dpp v234, v99 row_shr:1 row_mask:0xf bank_mask:0xf
	v_mov_b32_dpp v235, v99 row_shr:2 row_mask:0xf bank_mask:0xf
	v_cndmask_b32_e64 v228, 0, v228, vcc
	v_cndmask_b32_e64 v229, 0, v229, s[8:9]
	v_cndmask_b32_e64 v230, 0, v230, vcc
	v_cndmask_b32_e64 v231, 0, v231, s[8:9]
	v_cndmask_b32_e64 v232, 0, v232, vcc
	v_cndmask_b32_e64 v233, 0, v233, s[8:9]
	v_cndmask_b32_e64 v234, 0, v234, vcc
	v_cndmask_b32_e64 v235, 0, v235, s[8:9]
	v_fma_f32 v240, v229, v140, v224
	v_fma_f32 v241, v231, v141, v225
	v_fma_f32 v242, v233, v142, v226
	v_fma_f32 v243, v235, v143, v227
	v_fmac_f32_e32 v240, v228, v156
	v_fmac_f32_e32 v241, v230, v157
	v_fmac_f32_e32 v242, v232, v158
	v_fmac_f32_e32 v243, v234, v159
	v_fmac_f32_e32 v240, v96, v204
	v_fmac_f32_e32 v241, v97, v205
	v_fmac_f32_e32 v242, v98, v206
	v_fmac_f32_e32 v243, v99, v207
	v_mov_b32_e32 v228, 0xbdd2d3e8
	v_mul_f32_e32 v244, v236, v236
	v_mul_f32_e32 v245, v237, v237
	v_mul_f32_e32 v246, v238, v238
	v_mul_f32_e32 v247, v239, v239
	v_fmaak_f32 v244, v244, v228, 0xc0135761
	v_fmaak_f32 v245, v245, v228, 0xc0135761
	v_fmaak_f32 v246, v246, v228, 0xc0135761
	v_fmaak_f32 v247, v247, v228, 0xc0135761
	v_mul_f32_e32 v244, v236, v244
	v_mul_f32_e32 v245, v237, v245
	v_mul_f32_e32 v246, v238, v246
	v_mul_f32_e32 v247, v239, v247
	v_exp_f32_e32 v244, v244
	v_exp_f32_e32 v245, v245
	v_exp_f32_e32 v246, v246
	v_exp_f32_e32 v247, v247
	v_add_f32_e32 v244, 1.0, v244
	v_add_f32_e32 v245, 1.0, v245
	v_add_f32_e32 v246, 1.0, v246
	v_add_f32_e32 v247, 1.0, v247
	v_rcp_f32_e32 v244, v244
	v_rcp_f32_e32 v245, v245
	v_rcp_f32_e32 v246, v246
	v_rcp_f32_e32 v247, v247
	v_mul_f32_e32 v244, v236, v244
	v_mul_f32_e32 v245, v237, v245
	v_mul_f32_e32 v246, v238, v246
	v_mul_f32_e32 v247, v239, v247
	v_mul_f32_e32 v174, v240, v244
	v_mul_f32_e32 v175, v241, v245
	v_mul_f32_e32 v176, v242, v246
	v_mul_f32_e32 v177, v243, v247
	v_cvt_pk_bf16_f32 v180, v248, v249
	v_cvt_pk_bf16_f32 v181, v250, v251
	v_cvt_pk_bf16_f32 v182, v174, v175
	v_cvt_pk_bf16_f32 v183, v176, v177
	s_branch .Lffn1e_store1
.Lffn1e_slow2:
	v_add_u32_e32 v189, 2096, v218
	v_mul_hi_u32 v203, v189, s59
	v_lshrrev_b32_e32 v203, 7, v203
	v_mul_u32_u24_e32 v203, 0x810, v203
	v_sub_u32_e32 v189, v189, v203
	v_cmp_lt_u32_e32 vcc, 0, v189
	v_cmp_lt_u32_e64 s[8:9], 1, v189
	s_nop 1
	v_mov_b32_dpp v228, v108 row_ror:1 row_mask:0xf bank_mask:0xf
	v_mov_b32_dpp v229, v108 row_ror:2 row_mask:0xf bank_mask:0xf
	v_mov_b32_dpp v230, v109 row_ror:1 row_mask:0xf bank_mask:0xf
	v_mov_b32_dpp v231, v109 row_ror:2 row_mask:0xf bank_mask:0xf
	v_mov_b32_dpp v232, v110 row_ror:1 row_mask:0xf bank_mask:0xf
	v_mov_b32_dpp v233, v110 row_ror:2 row_mask:0xf bank_mask:0xf
	v_mov_b32_dpp v234, v111 row_ror:1 row_mask:0xf bank_mask:0xf
	v_mov_b32_dpp v235, v111 row_ror:2 row_mask:0xf bank_mask:0xf
	v_mov_b32_dpp v228, v92 row_shr:1 row_mask:0xf bank_mask:0xf
	v_mov_b32_dpp v229, v92 row_shr:2 row_mask:0xf bank_mask:0xf
	v_mov_b32_dpp v230, v93 row_shr:1 row_mask:0xf bank_mask:0xf
	v_mov_b32_dpp v231, v93 row_shr:2 row_mask:0xf bank_mask:0xf
	v_mov_b32_dpp v232, v94 row_shr:1 row_mask:0xf bank_mask:0xf
	v_mov_b32_dpp v233, v94 row_shr:2 row_mask:0xf bank_mask:0xf
	v_mov_b32_dpp v234, v95 row_shr:1 row_mask:0xf bank_mask:0xf
	v_mov_b32_dpp v235, v95 row_shr:2 row_mask:0xf bank_mask:0xf
	v_cndmask_b32_e64 v228, 0, v228, vcc
	v_cndmask_b32_e64 v229, 0, v229, s[8:9]
	v_cndmask_b32_e64 v230, 0, v230, vcc
	v_cndmask_b32_e64 v231, 0, v231, s[8:9]
	v_cndmask_b32_e64 v232, 0, v232, vcc
	v_cndmask_b32_e64 v233, 0, v233, s[8:9]
	v_cndmask_b32_e64 v234, 0, v234, vcc
	v_cndmask_b32_e64 v235, 0, v235, s[8:9]
	v_fma_f32 v236, v229, v128, v208
	v_fma_f32 v237, v231, v129, v209
	v_fma_f32 v238, v233, v130, v210
	v_fma_f32 v239, v235, v131, v211
	v_fmac_f32_e32 v236, v228, v144
	v_fmac_f32_e32 v237, v230, v145
	v_fmac_f32_e32 v238, v232, v146
	v_fmac_f32_e32 v239, v234, v147
	v_fmac_f32_e32 v236, v92, v160
	v_fmac_f32_e32 v237, v93, v161
	v_fmac_f32_e32 v238, v94, v162
	v_fmac_f32_e32 v239, v95, v163
	v_mov_b32_dpp v228, v100 row_ror:1 row_mask:0xf bank_mask:0xf
	v_mov_b32_dpp v229, v100 row_ror:2 row_mask:0xf bank_mask:0xf
	v_mov_b32_dpp v230, v101 row_ror:1 row_mask:0xf bank_mask:0xf
	v_mov_b32_dpp v231, v101 row_ror:2 row_mask:0xf bank_mask:0xf
	v_mov_b32_dpp v232, v102 row_ror:1 row_mask:0xf bank_mask:0xf
	v_mov_b32_dpp v233, v102 row_ror:2 row_mask:0xf bank_mask:0xf
	v_mov_b32_dpp v234, v103 row_ror:1 row_mask:0xf bank_mask:0xf
	v_mov_b32_dpp v235, v103 row_ror:2 row_mask:0xf bank_mask:0xf
	v_mov_b32_dpp v228, v84 row_shr:1 row_mask:0xf bank_mask:0xf
	v_mov_b32_dpp v229, v84 row_shr:2 row_mask:0xf bank_mask:0xf
	v_mov_b32_dpp v230, v85 row_shr:1 row_mask:0xf bank_mask:0xf
	v_mov_b32_dpp v231, v85 row_shr:2 row_mask:0xf bank_mask:0xf
	v_mov_b32_dpp v232, v86 row_shr:1 row_mask:0xf bank_mask:0xf
	v_mov_b32_dpp v233, v86 row_shr:2 row_mask:0xf bank_mask:0xf
	v_mov_b32_dpp v234, v87 row_shr:1 row_mask:0xf bank_mask:0xf
	v_mov_b32_dpp v235, v87 row_shr:2 row_mask:0xf bank_mask:0xf
	v_cndmask_b32_e64 v228, 0, v228, vcc
	v_cndmask_b32_e64 v229, 0, v229, s[8:9]
	v_cndmask_b32_e64 v230, 0, v230, vcc
	v_cndmask_b32_e64 v231, 0, v231, s[8:9]
	v_cndmask_b32_e64 v232, 0, v232, vcc
	v_cndmask_b32_e64 v233, 0, v233, s[8:9]
	v_cndmask_b32_e64 v234, 0, v234, vcc
	v_cndmask_b32_e64 v235, 0, v235, s[8:9]
	v_fma_f32 v240, v229, v132, v212
	v_fma_f32 v241, v231, v133, v213
	v_fma_f32 v242, v233, v134, v214
	v_fma_f32 v243, v235, v135, v215
	v_fmac_f32_e32 v240, v228, v148
	v_fmac_f32_e32 v241, v230, v149
	v_fmac_f32_e32 v242, v232, v150
	v_fmac_f32_e32 v243, v234, v151
	v_fmac_f32_e32 v240, v84, v164
	v_fmac_f32_e32 v241, v85, v165
	v_fmac_f32_e32 v242, v86, v166
	v_fmac_f32_e32 v243, v87, v167
	v_mov_b32_e32 v228, 0xbdd2d3e8
	v_mul_f32_e32 v244, v236, v236
	v_mul_f32_e32 v245, v237, v237
	v_mul_f32_e32 v246, v238, v238
	v_mul_f32_e32 v247, v239, v239
	v_fmaak_f32 v244, v244, v228, 0xc0135761
	v_fmaak_f32 v245, v245, v228, 0xc0135761
	v_fmaak_f32 v246, v246, v228, 0xc0135761
	v_fmaak_f32 v247, v247, v228, 0xc0135761
	v_mul_f32_e32 v244, v236, v244
	v_mul_f32_e32 v245, v237, v245
	v_mul_f32_e32 v246, v238, v246
	v_mul_f32_e32 v247, v239, v247
	v_exp_f32_e32 v244, v244
	v_exp_f32_e32 v245, v245
	v_exp_f32_e32 v246, v246
	v_exp_f32_e32 v247, v247
	v_add_f32_e32 v244, 1.0, v244
	v_add_f32_e32 v245, 1.0, v245
	v_add_f32_e32 v246, 1.0, v246
	v_add_f32_e32 v247, 1.0, v247
	v_rcp_f32_e32 v244, v244
	v_rcp_f32_e32 v245, v245
	v_rcp_f32_e32 v246, v246
	v_rcp_f32_e32 v247, v247
	v_mul_f32_e32 v244, v236, v244
	v_mul_f32_e32 v245, v237, v245
	v_mul_f32_e32 v246, v238, v246
	v_mul_f32_e32 v247, v239, v247
	v_mul_f32_e32 v248, v240, v244
	v_mul_f32_e32 v249, v241, v245
	v_mul_f32_e32 v250, v242, v246
	v_mul_f32_e32 v251, v243, v247
	v_mov_b32_dpp v228, v104 row_ror:1 row_mask:0xf bank_mask:0xf
	v_mov_b32_dpp v229, v104 row_ror:2 row_mask:0xf bank_mask:0xf
	v_mov_b32_dpp v230, v105 row_ror:1 row_mask:0xf bank_mask:0xf
	v_mov_b32_dpp v231, v105 row_ror:2 row_mask:0xf bank_mask:0xf
	v_mov_b32_dpp v232, v106 row_ror:1 row_mask:0xf bank_mask:0xf
	v_mov_b32_dpp v233, v106 row_ror:2 row_mask:0xf bank_mask:0xf
	v_mov_b32_dpp v234, v107 row_ror:1 row_mask:0xf bank_mask:0xf
	v_mov_b32_dpp v235, v107 row_ror:2 row_mask:0xf bank_mask:0xf
	v_mov_b32_dpp v228, v88 row_shr:1 row_mask:0xf bank_mask:0xf
	v_mov_b32_dpp v229, v88 row_shr:2 row_mask:0xf bank_mask:0xf
	v_mov_b32_dpp v230, v89 row_shr:1 row_mask:0xf bank_mask:0xf
	v_mov_b32_dpp v231, v89 row_shr:2 row_mask:0xf bank_mask:0xf
	v_mov_b32_dpp v232, v90 row_shr:1 row_mask:0xf bank_mask:0xf
	v_mov_b32_dpp v233, v90 row_shr:2 row_mask:0xf bank_mask:0xf
	v_mov_b32_dpp v234, v91 row_shr:1 row_mask:0xf bank_mask:0xf
	v_mov_b32_dpp v235, v91 row_shr:2 row_mask:0xf bank_mask:0xf
	v_cndmask_b32_e64 v228, 0, v228, vcc
	v_cndmask_b32_e64 v229, 0, v229, s[8:9]
	v_cndmask_b32_e64 v230, 0, v230, vcc
	v_cndmask_b32_e64 v231, 0, v231, s[8:9]
	v_cndmask_b32_e64 v232, 0, v232, vcc
	v_cndmask_b32_e64 v233, 0, v233, s[8:9]
	v_cndmask_b32_e64 v234, 0, v234, vcc
	v_cndmask_b32_e64 v235, 0, v235, s[8:9]
	v_fma_f32 v236, v229, v136, v220
	v_fma_f32 v237, v231, v137, v221
	v_fma_f32 v238, v233, v138, v222
	v_fma_f32 v239, v235, v139, v223
	v_fmac_f32_e32 v236, v228, v152
	v_fmac_f32_e32 v237, v230, v153
	v_fmac_f32_e32 v238, v232, v154
	v_fmac_f32_e32 v239, v234, v155
	v_fmac_f32_e32 v236, v88, v168
	v_fmac_f32_e32 v237, v89, v169
	v_fmac_f32_e32 v238, v90, v170
	v_fmac_f32_e32 v239, v91, v171
	v_mov_b32_dpp v228, v96 row_ror:1 row_mask:0xf bank_mask:0xf
	v_mov_b32_dpp v229, v96 row_ror:2 row_mask:0xf bank_mask:0xf
	v_mov_b32_dpp v230, v97 row_ror:1 row_mask:0xf bank_mask:0xf
	v_mov_b32_dpp v231, v97 row_ror:2 row_mask:0xf bank_mask:0xf
	v_mov_b32_dpp v232, v98 row_ror:1 row_mask:0xf bank_mask:0xf
	v_mov_b32_dpp v233, v98 row_ror:2 row_mask:0xf bank_mask:0xf
	v_mov_b32_dpp v234, v99 row_ror:1 row_mask:0xf bank_mask:0xf
	v_mov_b32_dpp v235, v99 row_ror:2 row_mask:0xf bank_mask:0xf
	v_mov_b32_dpp v228, v80 row_shr:1 row_mask:0xf bank_mask:0xf
	v_mov_b32_dpp v229, v80 row_shr:2 row_mask:0xf bank_mask:0xf
	v_mov_b32_dpp v230, v81 row_shr:1 row_mask:0xf bank_mask:0xf
	v_mov_b32_dpp v231, v81 row_shr:2 row_mask:0xf bank_mask:0xf
	v_mov_b32_dpp v232, v82 row_shr:1 row_mask:0xf bank_mask:0xf
	v_mov_b32_dpp v233, v82 row_shr:2 row_mask:0xf bank_mask:0xf
	v_mov_b32_dpp v234, v83 row_shr:1 row_mask:0xf bank_mask:0xf
	v_mov_b32_dpp v235, v83 row_shr:2 row_mask:0xf bank_mask:0xf
	v_cndmask_b32_e64 v228, 0, v228, vcc
	v_cndmask_b32_e64 v229, 0, v229, s[8:9]
	v_cndmask_b32_e64 v230, 0, v230, vcc
	v_cndmask_b32_e64 v231, 0, v231, s[8:9]
	v_cndmask_b32_e64 v232, 0, v232, vcc
	v_cndmask_b32_e64 v233, 0, v233, s[8:9]
	v_cndmask_b32_e64 v234, 0, v234, vcc
	v_cndmask_b32_e64 v235, 0, v235, s[8:9]
	v_fma_f32 v240, v229, v140, v224
	v_fma_f32 v241, v231, v141, v225
	v_fma_f32 v242, v233, v142, v226
	v_fma_f32 v243, v235, v143, v227
	v_fmac_f32_e32 v240, v228, v156
	v_fmac_f32_e32 v241, v230, v157
	v_fmac_f32_e32 v242, v232, v158
	v_fmac_f32_e32 v243, v234, v159
	v_fmac_f32_e32 v240, v80, v204
	v_fmac_f32_e32 v241, v81, v205
	v_fmac_f32_e32 v242, v82, v206
	v_fmac_f32_e32 v243, v83, v207
	v_mov_b32_e32 v228, 0xbdd2d3e8
	v_mul_f32_e32 v244, v236, v236
	v_mul_f32_e32 v245, v237, v237
	v_mul_f32_e32 v246, v238, v238
	v_mul_f32_e32 v247, v239, v239
	v_fmaak_f32 v244, v244, v228, 0xc0135761
	v_fmaak_f32 v245, v245, v228, 0xc0135761
	v_fmaak_f32 v246, v246, v228, 0xc0135761
	v_fmaak_f32 v247, v247, v228, 0xc0135761
	v_mul_f32_e32 v244, v236, v244
	v_mul_f32_e32 v245, v237, v245
	v_mul_f32_e32 v246, v238, v246
	v_mul_f32_e32 v247, v239, v247
	v_exp_f32_e32 v244, v244
	v_exp_f32_e32 v245, v245
	v_exp_f32_e32 v246, v246
	v_exp_f32_e32 v247, v247
	v_add_f32_e32 v244, 1.0, v244
	v_add_f32_e32 v245, 1.0, v245
	v_add_f32_e32 v246, 1.0, v246
	v_add_f32_e32 v247, 1.0, v247
	v_rcp_f32_e32 v244, v244
	v_rcp_f32_e32 v245, v245
	v_rcp_f32_e32 v246, v246
	v_rcp_f32_e32 v247, v247
	v_mul_f32_e32 v244, v236, v244
	v_mul_f32_e32 v245, v237, v245
	v_mul_f32_e32 v246, v238, v246
	v_mul_f32_e32 v247, v239, v247
	v_mul_f32_e32 v174, v240, v244
	v_mul_f32_e32 v175, v241, v245
	v_mul_f32_e32 v176, v242, v246
	v_mul_f32_e32 v177, v243, v247
	v_cvt_pk_bf16_f32 v180, v248, v249
	v_cvt_pk_bf16_f32 v181, v250, v251
	v_cvt_pk_bf16_f32 v182, v174, v175
	v_cvt_pk_bf16_f32 v183, v176, v177
	s_branch .Lffn1e_store2
.Lffn1e_slow3:
	v_add_u32_e32 v189, 2112, v218
	v_mul_hi_u32 v203, v189, s59
	v_lshrrev_b32_e32 v203, 7, v203
	v_mul_u32_u24_e32 v203, 0x810, v203
	v_sub_u32_e32 v189, v189, v203
	v_cmp_lt_u32_e32 vcc, 0, v189
	v_cmp_lt_u32_e64 s[8:9], 1, v189
	s_nop 1
	v_mov_b32_dpp v228, v92 row_ror:1 row_mask:0xf bank_mask:0xf
	v_mov_b32_dpp v229, v92 row_ror:2 row_mask:0xf bank_mask:0xf
	v_mov_b32_dpp v230, v93 row_ror:1 row_mask:0xf bank_mask:0xf
	v_mov_b32_dpp v231, v93 row_ror:2 row_mask:0xf bank_mask:0xf
	v_mov_b32_dpp v232, v94 row_ror:1 row_mask:0xf bank_mask:0xf
	v_mov_b32_dpp v233, v94 row_ror:2 row_mask:0xf bank_mask:0xf
	v_mov_b32_dpp v234, v95 row_ror:1 row_mask:0xf bank_mask:0xf
	v_mov_b32_dpp v235, v95 row_ror:2 row_mask:0xf bank_mask:0xf
	v_mov_b32_dpp v228, v76 row_shr:1 row_mask:0xf bank_mask:0xf
	v_mov_b32_dpp v229, v76 row_shr:2 row_mask:0xf bank_mask:0xf
	v_mov_b32_dpp v230, v77 row_shr:1 row_mask:0xf bank_mask:0xf
	v_mov_b32_dpp v231, v77 row_shr:2 row_mask:0xf bank_mask:0xf
	v_mov_b32_dpp v232, v78 row_shr:1 row_mask:0xf bank_mask:0xf
	v_mov_b32_dpp v233, v78 row_shr:2 row_mask:0xf bank_mask:0xf
	v_mov_b32_dpp v234, v79 row_shr:1 row_mask:0xf bank_mask:0xf
	v_mov_b32_dpp v235, v79 row_shr:2 row_mask:0xf bank_mask:0xf
	v_cndmask_b32_e64 v228, 0, v228, vcc
	v_cndmask_b32_e64 v229, 0, v229, s[8:9]
	v_cndmask_b32_e64 v230, 0, v230, vcc
	v_cndmask_b32_e64 v231, 0, v231, s[8:9]
	v_cndmask_b32_e64 v232, 0, v232, vcc
	v_cndmask_b32_e64 v233, 0, v233, s[8:9]
	v_cndmask_b32_e64 v234, 0, v234, vcc
	v_cndmask_b32_e64 v235, 0, v235, s[8:9]
	v_fma_f32 v236, v229, v128, v208
	v_fma_f32 v237, v231, v129, v209
	v_fma_f32 v238, v233, v130, v210
	v_fma_f32 v239, v235, v131, v211
	v_fmac_f32_e32 v236, v228, v144
	v_fmac_f32_e32 v237, v230, v145
	v_fmac_f32_e32 v238, v232, v146
	v_fmac_f32_e32 v239, v234, v147
	v_fmac_f32_e32 v236, v76, v160
	v_fmac_f32_e32 v237, v77, v161
	v_fmac_f32_e32 v238, v78, v162
	v_fmac_f32_e32 v239, v79, v163
	v_mov_b32_dpp v228, v84 row_ror:1 row_mask:0xf bank_mask:0xf
	v_mov_b32_dpp v229, v84 row_ror:2 row_mask:0xf bank_mask:0xf
	v_mov_b32_dpp v230, v85 row_ror:1 row_mask:0xf bank_mask:0xf
	v_mov_b32_dpp v231, v85 row_ror:2 row_mask:0xf bank_mask:0xf
	v_mov_b32_dpp v232, v86 row_ror:1 row_mask:0xf bank_mask:0xf
	v_mov_b32_dpp v233, v86 row_ror:2 row_mask:0xf bank_mask:0xf
	v_mov_b32_dpp v234, v87 row_ror:1 row_mask:0xf bank_mask:0xf
	v_mov_b32_dpp v235, v87 row_ror:2 row_mask:0xf bank_mask:0xf
	v_mov_b32_dpp v228, v68 row_shr:1 row_mask:0xf bank_mask:0xf
	v_mov_b32_dpp v229, v68 row_shr:2 row_mask:0xf bank_mask:0xf
	v_mov_b32_dpp v230, v69 row_shr:1 row_mask:0xf bank_mask:0xf
	v_mov_b32_dpp v231, v69 row_shr:2 row_mask:0xf bank_mask:0xf
	v_mov_b32_dpp v232, v70 row_shr:1 row_mask:0xf bank_mask:0xf
	v_mov_b32_dpp v233, v70 row_shr:2 row_mask:0xf bank_mask:0xf
	v_mov_b32_dpp v234, v71 row_shr:1 row_mask:0xf bank_mask:0xf
	v_mov_b32_dpp v235, v71 row_shr:2 row_mask:0xf bank_mask:0xf
	v_cndmask_b32_e64 v228, 0, v228, vcc
	v_cndmask_b32_e64 v229, 0, v229, s[8:9]
	v_cndmask_b32_e64 v230, 0, v230, vcc
	v_cndmask_b32_e64 v231, 0, v231, s[8:9]
	v_cndmask_b32_e64 v232, 0, v232, vcc
	v_cndmask_b32_e64 v233, 0, v233, s[8:9]
	v_cndmask_b32_e64 v234, 0, v234, vcc
	v_cndmask_b32_e64 v235, 0, v235, s[8:9]
	v_fma_f32 v240, v229, v132, v212
	v_fma_f32 v241, v231, v133, v213
	v_fma_f32 v242, v233, v134, v214
	v_fma_f32 v243, v235, v135, v215
	v_fmac_f32_e32 v240, v228, v148
	v_fmac_f32_e32 v241, v230, v149
	v_fmac_f32_e32 v242, v232, v150
	v_fmac_f32_e32 v243, v234, v151
	v_fmac_f32_e32 v240, v68, v164
	v_fmac_f32_e32 v241, v69, v165
	v_fmac_f32_e32 v242, v70, v166
	v_fmac_f32_e32 v243, v71, v167
	v_mov_b32_e32 v228, 0xbdd2d3e8
	v_mul_f32_e32 v244, v236, v236
	v_mul_f32_e32 v245, v237, v237
	v_mul_f32_e32 v246, v238, v238
	v_mul_f32_e32 v247, v239, v239
	v_fmaak_f32 v244, v244, v228, 0xc0135761
	v_fmaak_f32 v245, v245, v228, 0xc0135761
	v_fmaak_f32 v246, v246, v228, 0xc0135761
	v_fmaak_f32 v247, v247, v228, 0xc0135761
	v_mul_f32_e32 v244, v236, v244
	v_mul_f32_e32 v245, v237, v245
	v_mul_f32_e32 v246, v238, v246
	v_mul_f32_e32 v247, v239, v247
	v_exp_f32_e32 v244, v244
	v_exp_f32_e32 v245, v245
	v_exp_f32_e32 v246, v246
	v_exp_f32_e32 v247, v247
	v_add_f32_e32 v244, 1.0, v244
	v_add_f32_e32 v245, 1.0, v245
	v_add_f32_e32 v246, 1.0, v246
	v_add_f32_e32 v247, 1.0, v247
	v_rcp_f32_e32 v244, v244
	v_rcp_f32_e32 v245, v245
	v_rcp_f32_e32 v246, v246
	v_rcp_f32_e32 v247, v247
	v_mul_f32_e32 v244, v236, v244
	v_mul_f32_e32 v245, v237, v245
	v_mul_f32_e32 v246, v238, v246
	v_mul_f32_e32 v247, v239, v247
	v_mul_f32_e32 v248, v240, v244
	v_mul_f32_e32 v249, v241, v245
	v_mul_f32_e32 v250, v242, v246
	v_mul_f32_e32 v251, v243, v247
	v_mov_b32_dpp v228, v88 row_ror:1 row_mask:0xf bank_mask:0xf
	v_mov_b32_dpp v229, v88 row_ror:2 row_mask:0xf bank_mask:0xf
	v_mov_b32_dpp v230, v89 row_ror:1 row_mask:0xf bank_mask:0xf
	v_mov_b32_dpp v231, v89 row_ror:2 row_mask:0xf bank_mask:0xf
	v_mov_b32_dpp v232, v90 row_ror:1 row_mask:0xf bank_mask:0xf
	v_mov_b32_dpp v233, v90 row_ror:2 row_mask:0xf bank_mask:0xf
	v_mov_b32_dpp v234, v91 row_ror:1 row_mask:0xf bank_mask:0xf
	v_mov_b32_dpp v235, v91 row_ror:2 row_mask:0xf bank_mask:0xf
	v_mov_b32_dpp v228, v72 row_shr:1 row_mask:0xf bank_mask:0xf
	v_mov_b32_dpp v229, v72 row_shr:2 row_mask:0xf bank_mask:0xf
	v_mov_b32_dpp v230, v73 row_shr:1 row_mask:0xf bank_mask:0xf
	v_mov_b32_dpp v231, v73 row_shr:2 row_mask:0xf bank_mask:0xf
	v_mov_b32_dpp v232, v74 row_shr:1 row_mask:0xf bank_mask:0xf
	v_mov_b32_dpp v233, v74 row_shr:2 row_mask:0xf bank_mask:0xf
	v_mov_b32_dpp v234, v75 row_shr:1 row_mask:0xf bank_mask:0xf
	v_mov_b32_dpp v235, v75 row_shr:2 row_mask:0xf bank_mask:0xf
	v_cndmask_b32_e64 v228, 0, v228, vcc
	v_cndmask_b32_e64 v229, 0, v229, s[8:9]
	v_cndmask_b32_e64 v230, 0, v230, vcc
	v_cndmask_b32_e64 v231, 0, v231, s[8:9]
	v_cndmask_b32_e64 v232, 0, v232, vcc
	v_cndmask_b32_e64 v233, 0, v233, s[8:9]
	v_cndmask_b32_e64 v234, 0, v234, vcc
	v_cndmask_b32_e64 v235, 0, v235, s[8:9]
	v_fma_f32 v236, v229, v136, v220
	v_fma_f32 v237, v231, v137, v221
	v_fma_f32 v238, v233, v138, v222
	v_fma_f32 v239, v235, v139, v223
	v_fmac_f32_e32 v236, v228, v152
	v_fmac_f32_e32 v237, v230, v153
	v_fmac_f32_e32 v238, v232, v154
	v_fmac_f32_e32 v239, v234, v155
	v_fmac_f32_e32 v236, v72, v168
	v_fmac_f32_e32 v237, v73, v169
	v_fmac_f32_e32 v238, v74, v170
	v_fmac_f32_e32 v239, v75, v171
	v_mov_b32_dpp v228, v80 row_ror:1 row_mask:0xf bank_mask:0xf
	v_mov_b32_dpp v229, v80 row_ror:2 row_mask:0xf bank_mask:0xf
	v_mov_b32_dpp v230, v81 row_ror:1 row_mask:0xf bank_mask:0xf
	v_mov_b32_dpp v231, v81 row_ror:2 row_mask:0xf bank_mask:0xf
	v_mov_b32_dpp v232, v82 row_ror:1 row_mask:0xf bank_mask:0xf
	v_mov_b32_dpp v233, v82 row_ror:2 row_mask:0xf bank_mask:0xf
	v_mov_b32_dpp v234, v83 row_ror:1 row_mask:0xf bank_mask:0xf
	v_mov_b32_dpp v235, v83 row_ror:2 row_mask:0xf bank_mask:0xf
	v_mov_b32_dpp v228, v64 row_shr:1 row_mask:0xf bank_mask:0xf
	v_mov_b32_dpp v229, v64 row_shr:2 row_mask:0xf bank_mask:0xf
	v_mov_b32_dpp v230, v65 row_shr:1 row_mask:0xf bank_mask:0xf
	v_mov_b32_dpp v231, v65 row_shr:2 row_mask:0xf bank_mask:0xf
	v_mov_b32_dpp v232, v66 row_shr:1 row_mask:0xf bank_mask:0xf
	v_mov_b32_dpp v233, v66 row_shr:2 row_mask:0xf bank_mask:0xf
	v_mov_b32_dpp v234, v67 row_shr:1 row_mask:0xf bank_mask:0xf
	v_mov_b32_dpp v235, v67 row_shr:2 row_mask:0xf bank_mask:0xf
	v_cndmask_b32_e64 v228, 0, v228, vcc
	v_cndmask_b32_e64 v229, 0, v229, s[8:9]
	v_cndmask_b32_e64 v230, 0, v230, vcc
	v_cndmask_b32_e64 v231, 0, v231, s[8:9]
	v_cndmask_b32_e64 v232, 0, v232, vcc
	v_cndmask_b32_e64 v233, 0, v233, s[8:9]
	v_cndmask_b32_e64 v234, 0, v234, vcc
	v_cndmask_b32_e64 v235, 0, v235, s[8:9]
	v_fma_f32 v240, v229, v140, v224
	v_fma_f32 v241, v231, v141, v225
	v_fma_f32 v242, v233, v142, v226
	v_fma_f32 v243, v235, v143, v227
	v_fmac_f32_e32 v240, v228, v156
	v_fmac_f32_e32 v241, v230, v157
	v_fmac_f32_e32 v242, v232, v158
	v_fmac_f32_e32 v243, v234, v159
	v_fmac_f32_e32 v240, v64, v204
	v_fmac_f32_e32 v241, v65, v205
	v_fmac_f32_e32 v242, v66, v206
	v_fmac_f32_e32 v243, v67, v207
	v_mov_b32_e32 v228, 0xbdd2d3e8
	v_mul_f32_e32 v244, v236, v236
	v_mul_f32_e32 v245, v237, v237
	v_mul_f32_e32 v246, v238, v238
	v_mul_f32_e32 v247, v239, v239
	v_fmaak_f32 v244, v244, v228, 0xc0135761
	v_fmaak_f32 v245, v245, v228, 0xc0135761
	v_fmaak_f32 v246, v246, v228, 0xc0135761
	v_fmaak_f32 v247, v247, v228, 0xc0135761
	v_mul_f32_e32 v244, v236, v244
	v_mul_f32_e32 v245, v237, v245
	v_mul_f32_e32 v246, v238, v246
	v_mul_f32_e32 v247, v239, v247
	v_exp_f32_e32 v244, v244
	v_exp_f32_e32 v245, v245
	v_exp_f32_e32 v246, v246
	v_exp_f32_e32 v247, v247
	v_add_f32_e32 v244, 1.0, v244
	v_add_f32_e32 v245, 1.0, v245
	v_add_f32_e32 v246, 1.0, v246
	v_add_f32_e32 v247, 1.0, v247
	v_rcp_f32_e32 v244, v244
	v_rcp_f32_e32 v245, v245
	v_rcp_f32_e32 v246, v246
	v_rcp_f32_e32 v247, v247
	v_mul_f32_e32 v244, v236, v244
	v_mul_f32_e32 v245, v237, v245
	v_mul_f32_e32 v246, v238, v246
	v_mul_f32_e32 v247, v239, v247
	v_mul_f32_e32 v174, v240, v244
	v_mul_f32_e32 v175, v241, v245
	v_mul_f32_e32 v176, v242, v246
	v_mul_f32_e32 v177, v243, v247
	v_cvt_pk_bf16_f32 v180, v248, v249
	v_cvt_pk_bf16_f32 v181, v250, v251
	v_cvt_pk_bf16_f32 v182, v174, v175
	v_cvt_pk_bf16_f32 v183, v176, v177
	s_branch .Lffn1e_store3
.Lffn1e_slow4:
	v_add_u32_e32 v189, 2128, v218
	v_mul_hi_u32 v203, v189, s59
	v_lshrrev_b32_e32 v203, 7, v203
	v_mul_u32_u24_e32 v203, 0x810, v203
	v_sub_u32_e32 v189, v189, v203
	v_cmp_lt_u32_e32 vcc, 0, v189
	v_cmp_lt_u32_e64 s[8:9], 1, v189
	s_nop 1
	v_mov_b32_dpp v228, v76 row_ror:1 row_mask:0xf bank_mask:0xf
	v_mov_b32_dpp v229, v76 row_ror:2 row_mask:0xf bank_mask:0xf
	v_mov_b32_dpp v230, v77 row_ror:1 row_mask:0xf bank_mask:0xf
	v_mov_b32_dpp v231, v77 row_ror:2 row_mask:0xf bank_mask:0xf
	v_mov_b32_dpp v232, v78 row_ror:1 row_mask:0xf bank_mask:0xf
	v_mov_b32_dpp v233, v78 row_ror:2 row_mask:0xf bank_mask:0xf
	v_mov_b32_dpp v234, v79 row_ror:1 row_mask:0xf bank_mask:0xf
	v_mov_b32_dpp v235, v79 row_ror:2 row_mask:0xf bank_mask:0xf
	v_mov_b32_dpp v228, v60 row_shr:1 row_mask:0xf bank_mask:0xf
	v_mov_b32_dpp v229, v60 row_shr:2 row_mask:0xf bank_mask:0xf
	v_mov_b32_dpp v230, v61 row_shr:1 row_mask:0xf bank_mask:0xf
	v_mov_b32_dpp v231, v61 row_shr:2 row_mask:0xf bank_mask:0xf
	v_mov_b32_dpp v232, v62 row_shr:1 row_mask:0xf bank_mask:0xf
	v_mov_b32_dpp v233, v62 row_shr:2 row_mask:0xf bank_mask:0xf
	v_mov_b32_dpp v234, v63 row_shr:1 row_mask:0xf bank_mask:0xf
	v_mov_b32_dpp v235, v63 row_shr:2 row_mask:0xf bank_mask:0xf
	v_cndmask_b32_e64 v228, 0, v228, vcc
	v_cndmask_b32_e64 v229, 0, v229, s[8:9]
	v_cndmask_b32_e64 v230, 0, v230, vcc
	v_cndmask_b32_e64 v231, 0, v231, s[8:9]
	v_cndmask_b32_e64 v232, 0, v232, vcc
	v_cndmask_b32_e64 v233, 0, v233, s[8:9]
	v_cndmask_b32_e64 v234, 0, v234, vcc
	v_cndmask_b32_e64 v235, 0, v235, s[8:9]
	v_fma_f32 v236, v229, v128, v208
	v_fma_f32 v237, v231, v129, v209
	v_fma_f32 v238, v233, v130, v210
	v_fma_f32 v239, v235, v131, v211
	v_fmac_f32_e32 v236, v228, v144
	v_fmac_f32_e32 v237, v230, v145
	v_fmac_f32_e32 v238, v232, v146
	v_fmac_f32_e32 v239, v234, v147
	v_fmac_f32_e32 v236, v60, v160
	v_fmac_f32_e32 v237, v61, v161
	v_fmac_f32_e32 v238, v62, v162
	v_fmac_f32_e32 v239, v63, v163
	v_mov_b32_dpp v228, v68 row_ror:1 row_mask:0xf bank_mask:0xf
	v_mov_b32_dpp v229, v68 row_ror:2 row_mask:0xf bank_mask:0xf
	v_mov_b32_dpp v230, v69 row_ror:1 row_mask:0xf bank_mask:0xf
	v_mov_b32_dpp v231, v69 row_ror:2 row_mask:0xf bank_mask:0xf
	v_mov_b32_dpp v232, v70 row_ror:1 row_mask:0xf bank_mask:0xf
	v_mov_b32_dpp v233, v70 row_ror:2 row_mask:0xf bank_mask:0xf
	v_mov_b32_dpp v234, v71 row_ror:1 row_mask:0xf bank_mask:0xf
	v_mov_b32_dpp v235, v71 row_ror:2 row_mask:0xf bank_mask:0xf
	v_mov_b32_dpp v228, v52 row_shr:1 row_mask:0xf bank_mask:0xf
	v_mov_b32_dpp v229, v52 row_shr:2 row_mask:0xf bank_mask:0xf
	v_mov_b32_dpp v230, v53 row_shr:1 row_mask:0xf bank_mask:0xf
	v_mov_b32_dpp v231, v53 row_shr:2 row_mask:0xf bank_mask:0xf
	v_mov_b32_dpp v232, v54 row_shr:1 row_mask:0xf bank_mask:0xf
	v_mov_b32_dpp v233, v54 row_shr:2 row_mask:0xf bank_mask:0xf
	v_mov_b32_dpp v234, v55 row_shr:1 row_mask:0xf bank_mask:0xf
	v_mov_b32_dpp v235, v55 row_shr:2 row_mask:0xf bank_mask:0xf
	v_cndmask_b32_e64 v228, 0, v228, vcc
	v_cndmask_b32_e64 v229, 0, v229, s[8:9]
	v_cndmask_b32_e64 v230, 0, v230, vcc
	v_cndmask_b32_e64 v231, 0, v231, s[8:9]
	v_cndmask_b32_e64 v232, 0, v232, vcc
	v_cndmask_b32_e64 v233, 0, v233, s[8:9]
	v_cndmask_b32_e64 v234, 0, v234, vcc
	v_cndmask_b32_e64 v235, 0, v235, s[8:9]
	v_fma_f32 v240, v229, v132, v212
	v_fma_f32 v241, v231, v133, v213
	v_fma_f32 v242, v233, v134, v214
	v_fma_f32 v243, v235, v135, v215
	v_fmac_f32_e32 v240, v228, v148
	v_fmac_f32_e32 v241, v230, v149
	v_fmac_f32_e32 v242, v232, v150
	v_fmac_f32_e32 v243, v234, v151
	v_fmac_f32_e32 v240, v52, v164
	v_fmac_f32_e32 v241, v53, v165
	v_fmac_f32_e32 v242, v54, v166
	v_fmac_f32_e32 v243, v55, v167
	v_mov_b32_e32 v228, 0xbdd2d3e8
	v_mul_f32_e32 v244, v236, v236
	v_mul_f32_e32 v245, v237, v237
	v_mul_f32_e32 v246, v238, v238
	v_mul_f32_e32 v247, v239, v239
	v_fmaak_f32 v244, v244, v228, 0xc0135761
	v_fmaak_f32 v245, v245, v228, 0xc0135761
	v_fmaak_f32 v246, v246, v228, 0xc0135761
	v_fmaak_f32 v247, v247, v228, 0xc0135761
	v_mul_f32_e32 v244, v236, v244
	v_mul_f32_e32 v245, v237, v245
	v_mul_f32_e32 v246, v238, v246
	v_mul_f32_e32 v247, v239, v247
	v_exp_f32_e32 v244, v244
	v_exp_f32_e32 v245, v245
	v_exp_f32_e32 v246, v246
	v_exp_f32_e32 v247, v247
	v_add_f32_e32 v244, 1.0, v244
	v_add_f32_e32 v245, 1.0, v245
	v_add_f32_e32 v246, 1.0, v246
	v_add_f32_e32 v247, 1.0, v247
	v_rcp_f32_e32 v244, v244
	v_rcp_f32_e32 v245, v245
	v_rcp_f32_e32 v246, v246
	v_rcp_f32_e32 v247, v247
	v_mul_f32_e32 v244, v236, v244
	v_mul_f32_e32 v245, v237, v245
	v_mul_f32_e32 v246, v238, v246
	v_mul_f32_e32 v247, v239, v247
	v_mul_f32_e32 v248, v240, v244
	v_mul_f32_e32 v249, v241, v245
	v_mul_f32_e32 v250, v242, v246
	v_mul_f32_e32 v251, v243, v247
	v_mov_b32_dpp v228, v72 row_ror:1 row_mask:0xf bank_mask:0xf
	v_mov_b32_dpp v229, v72 row_ror:2 row_mask:0xf bank_mask:0xf
	v_mov_b32_dpp v230, v73 row_ror:1 row_mask:0xf bank_mask:0xf
	v_mov_b32_dpp v231, v73 row_ror:2 row_mask:0xf bank_mask:0xf
	v_mov_b32_dpp v232, v74 row_ror:1 row_mask:0xf bank_mask:0xf
	v_mov_b32_dpp v233, v74 row_ror:2 row_mask:0xf bank_mask:0xf
	v_mov_b32_dpp v234, v75 row_ror:1 row_mask:0xf bank_mask:0xf
	v_mov_b32_dpp v235, v75 row_ror:2 row_mask:0xf bank_mask:0xf
	v_mov_b32_dpp v228, v56 row_shr:1 row_mask:0xf bank_mask:0xf
	v_mov_b32_dpp v229, v56 row_shr:2 row_mask:0xf bank_mask:0xf
	v_mov_b32_dpp v230, v57 row_shr:1 row_mask:0xf bank_mask:0xf
	v_mov_b32_dpp v231, v57 row_shr:2 row_mask:0xf bank_mask:0xf
	v_mov_b32_dpp v232, v58 row_shr:1 row_mask:0xf bank_mask:0xf
	v_mov_b32_dpp v233, v58 row_shr:2 row_mask:0xf bank_mask:0xf
	v_mov_b32_dpp v234, v59 row_shr:1 row_mask:0xf bank_mask:0xf
	v_mov_b32_dpp v235, v59 row_shr:2 row_mask:0xf bank_mask:0xf
	v_cndmask_b32_e64 v228, 0, v228, vcc
	v_cndmask_b32_e64 v229, 0, v229, s[8:9]
	v_cndmask_b32_e64 v230, 0, v230, vcc
	v_cndmask_b32_e64 v231, 0, v231, s[8:9]
	v_cndmask_b32_e64 v232, 0, v232, vcc
	v_cndmask_b32_e64 v233, 0, v233, s[8:9]
	v_cndmask_b32_e64 v234, 0, v234, vcc
	v_cndmask_b32_e64 v235, 0, v235, s[8:9]
	v_fma_f32 v236, v229, v136, v220
	v_fma_f32 v237, v231, v137, v221
	v_fma_f32 v238, v233, v138, v222
	v_fma_f32 v239, v235, v139, v223
	v_fmac_f32_e32 v236, v228, v152
	v_fmac_f32_e32 v237, v230, v153
	v_fmac_f32_e32 v238, v232, v154
	v_fmac_f32_e32 v239, v234, v155
	v_fmac_f32_e32 v236, v56, v168
	v_fmac_f32_e32 v237, v57, v169
	v_fmac_f32_e32 v238, v58, v170
	v_fmac_f32_e32 v239, v59, v171
	v_mov_b32_dpp v228, v64 row_ror:1 row_mask:0xf bank_mask:0xf
	v_mov_b32_dpp v229, v64 row_ror:2 row_mask:0xf bank_mask:0xf
	v_mov_b32_dpp v230, v65 row_ror:1 row_mask:0xf bank_mask:0xf
	v_mov_b32_dpp v231, v65 row_ror:2 row_mask:0xf bank_mask:0xf
	v_mov_b32_dpp v232, v66 row_ror:1 row_mask:0xf bank_mask:0xf
	v_mov_b32_dpp v233, v66 row_ror:2 row_mask:0xf bank_mask:0xf
	v_mov_b32_dpp v234, v67 row_ror:1 row_mask:0xf bank_mask:0xf
	v_mov_b32_dpp v235, v67 row_ror:2 row_mask:0xf bank_mask:0xf
	v_mov_b32_dpp v228, v48 row_shr:1 row_mask:0xf bank_mask:0xf
	v_mov_b32_dpp v229, v48 row_shr:2 row_mask:0xf bank_mask:0xf
	v_mov_b32_dpp v230, v49 row_shr:1 row_mask:0xf bank_mask:0xf
	v_mov_b32_dpp v231, v49 row_shr:2 row_mask:0xf bank_mask:0xf
	v_mov_b32_dpp v232, v50 row_shr:1 row_mask:0xf bank_mask:0xf
	v_mov_b32_dpp v233, v50 row_shr:2 row_mask:0xf bank_mask:0xf
	v_mov_b32_dpp v234, v51 row_shr:1 row_mask:0xf bank_mask:0xf
	v_mov_b32_dpp v235, v51 row_shr:2 row_mask:0xf bank_mask:0xf
	v_cndmask_b32_e64 v228, 0, v228, vcc
	v_cndmask_b32_e64 v229, 0, v229, s[8:9]
	v_cndmask_b32_e64 v230, 0, v230, vcc
	v_cndmask_b32_e64 v231, 0, v231, s[8:9]
	v_cndmask_b32_e64 v232, 0, v232, vcc
	v_cndmask_b32_e64 v233, 0, v233, s[8:9]
	v_cndmask_b32_e64 v234, 0, v234, vcc
	v_cndmask_b32_e64 v235, 0, v235, s[8:9]
	v_fma_f32 v240, v229, v140, v224
	v_fma_f32 v241, v231, v141, v225
	v_fma_f32 v242, v233, v142, v226
	v_fma_f32 v243, v235, v143, v227
	v_fmac_f32_e32 v240, v228, v156
	v_fmac_f32_e32 v241, v230, v157
	v_fmac_f32_e32 v242, v232, v158
	v_fmac_f32_e32 v243, v234, v159
	v_fmac_f32_e32 v240, v48, v204
	v_fmac_f32_e32 v241, v49, v205
	v_fmac_f32_e32 v242, v50, v206
	v_fmac_f32_e32 v243, v51, v207
	v_mov_b32_e32 v228, 0xbdd2d3e8
	v_mul_f32_e32 v244, v236, v236
	v_mul_f32_e32 v245, v237, v237
	v_mul_f32_e32 v246, v238, v238
	v_mul_f32_e32 v247, v239, v239
	v_fmaak_f32 v244, v244, v228, 0xc0135761
	v_fmaak_f32 v245, v245, v228, 0xc0135761
	v_fmaak_f32 v246, v246, v228, 0xc0135761
	v_fmaak_f32 v247, v247, v228, 0xc0135761
	v_mul_f32_e32 v244, v236, v244
	v_mul_f32_e32 v245, v237, v245
	v_mul_f32_e32 v246, v238, v246
	v_mul_f32_e32 v247, v239, v247
	v_exp_f32_e32 v244, v244
	v_exp_f32_e32 v245, v245
	v_exp_f32_e32 v246, v246
	v_exp_f32_e32 v247, v247
	v_add_f32_e32 v244, 1.0, v244
	v_add_f32_e32 v245, 1.0, v245
	v_add_f32_e32 v246, 1.0, v246
	v_add_f32_e32 v247, 1.0, v247
	v_rcp_f32_e32 v244, v244
	v_rcp_f32_e32 v245, v245
	v_rcp_f32_e32 v246, v246
	v_rcp_f32_e32 v247, v247
	v_mul_f32_e32 v244, v236, v244
	v_mul_f32_e32 v245, v237, v245
	v_mul_f32_e32 v246, v238, v246
	v_mul_f32_e32 v247, v239, v247
	v_mul_f32_e32 v174, v240, v244
	v_mul_f32_e32 v175, v241, v245
	v_mul_f32_e32 v176, v242, v246
	v_mul_f32_e32 v177, v243, v247
	v_cvt_pk_bf16_f32 v180, v248, v249
	v_cvt_pk_bf16_f32 v181, v250, v251
	v_cvt_pk_bf16_f32 v182, v174, v175
	v_cvt_pk_bf16_f32 v183, v176, v177
	s_branch .Lffn1e_store4
.Lffn1e_slow5:
	v_add_u32_e32 v189, 2144, v218
	v_mul_hi_u32 v203, v189, s59
	v_lshrrev_b32_e32 v203, 7, v203
	v_mul_u32_u24_e32 v203, 0x810, v203
	v_sub_u32_e32 v189, v189, v203
	v_cmp_lt_u32_e32 vcc, 0, v189
	v_cmp_lt_u32_e64 s[8:9], 1, v189
	s_nop 1
	v_mov_b32_dpp v228, v60 row_ror:1 row_mask:0xf bank_mask:0xf
	v_mov_b32_dpp v229, v60 row_ror:2 row_mask:0xf bank_mask:0xf
	v_mov_b32_dpp v230, v61 row_ror:1 row_mask:0xf bank_mask:0xf
	v_mov_b32_dpp v231, v61 row_ror:2 row_mask:0xf bank_mask:0xf
	v_mov_b32_dpp v232, v62 row_ror:1 row_mask:0xf bank_mask:0xf
	v_mov_b32_dpp v233, v62 row_ror:2 row_mask:0xf bank_mask:0xf
	v_mov_b32_dpp v234, v63 row_ror:1 row_mask:0xf bank_mask:0xf
	v_mov_b32_dpp v235, v63 row_ror:2 row_mask:0xf bank_mask:0xf
	v_mov_b32_dpp v228, v44 row_shr:1 row_mask:0xf bank_mask:0xf
	v_mov_b32_dpp v229, v44 row_shr:2 row_mask:0xf bank_mask:0xf
	v_mov_b32_dpp v230, v45 row_shr:1 row_mask:0xf bank_mask:0xf
	v_mov_b32_dpp v231, v45 row_shr:2 row_mask:0xf bank_mask:0xf
	v_mov_b32_dpp v232, v46 row_shr:1 row_mask:0xf bank_mask:0xf
	v_mov_b32_dpp v233, v46 row_shr:2 row_mask:0xf bank_mask:0xf
	v_mov_b32_dpp v234, v47 row_shr:1 row_mask:0xf bank_mask:0xf
	v_mov_b32_dpp v235, v47 row_shr:2 row_mask:0xf bank_mask:0xf
	v_cndmask_b32_e64 v228, 0, v228, vcc
	v_cndmask_b32_e64 v229, 0, v229, s[8:9]
	v_cndmask_b32_e64 v230, 0, v230, vcc
	v_cndmask_b32_e64 v231, 0, v231, s[8:9]
	v_cndmask_b32_e64 v232, 0, v232, vcc
	v_cndmask_b32_e64 v233, 0, v233, s[8:9]
	v_cndmask_b32_e64 v234, 0, v234, vcc
	v_cndmask_b32_e64 v235, 0, v235, s[8:9]
	v_fma_f32 v236, v229, v128, v208
	v_fma_f32 v237, v231, v129, v209
	v_fma_f32 v238, v233, v130, v210
	v_fma_f32 v239, v235, v131, v211
	v_fmac_f32_e32 v236, v228, v144
	v_fmac_f32_e32 v237, v230, v145
	v_fmac_f32_e32 v238, v232, v146
	v_fmac_f32_e32 v239, v234, v147
	v_fmac_f32_e32 v236, v44, v160
	v_fmac_f32_e32 v237, v45, v161
	v_fmac_f32_e32 v238, v46, v162
	v_fmac_f32_e32 v239, v47, v163
	v_mov_b32_dpp v228, v52 row_ror:1 row_mask:0xf bank_mask:0xf
	v_mov_b32_dpp v229, v52 row_ror:2 row_mask:0xf bank_mask:0xf
	v_mov_b32_dpp v230, v53 row_ror:1 row_mask:0xf bank_mask:0xf
	v_mov_b32_dpp v231, v53 row_ror:2 row_mask:0xf bank_mask:0xf
	v_mov_b32_dpp v232, v54 row_ror:1 row_mask:0xf bank_mask:0xf
	v_mov_b32_dpp v233, v54 row_ror:2 row_mask:0xf bank_mask:0xf
	v_mov_b32_dpp v234, v55 row_ror:1 row_mask:0xf bank_mask:0xf
	v_mov_b32_dpp v235, v55 row_ror:2 row_mask:0xf bank_mask:0xf
	v_mov_b32_dpp v228, v36 row_shr:1 row_mask:0xf bank_mask:0xf
	v_mov_b32_dpp v229, v36 row_shr:2 row_mask:0xf bank_mask:0xf
	v_mov_b32_dpp v230, v37 row_shr:1 row_mask:0xf bank_mask:0xf
	v_mov_b32_dpp v231, v37 row_shr:2 row_mask:0xf bank_mask:0xf
	v_mov_b32_dpp v232, v38 row_shr:1 row_mask:0xf bank_mask:0xf
	v_mov_b32_dpp v233, v38 row_shr:2 row_mask:0xf bank_mask:0xf
	v_mov_b32_dpp v234, v39 row_shr:1 row_mask:0xf bank_mask:0xf
	v_mov_b32_dpp v235, v39 row_shr:2 row_mask:0xf bank_mask:0xf
	v_cndmask_b32_e64 v228, 0, v228, vcc
	v_cndmask_b32_e64 v229, 0, v229, s[8:9]
	v_cndmask_b32_e64 v230, 0, v230, vcc
	v_cndmask_b32_e64 v231, 0, v231, s[8:9]
	v_cndmask_b32_e64 v232, 0, v232, vcc
	v_cndmask_b32_e64 v233, 0, v233, s[8:9]
	v_cndmask_b32_e64 v234, 0, v234, vcc
	v_cndmask_b32_e64 v235, 0, v235, s[8:9]
	v_fma_f32 v240, v229, v132, v212
	v_fma_f32 v241, v231, v133, v213
	v_fma_f32 v242, v233, v134, v214
	v_fma_f32 v243, v235, v135, v215
	v_fmac_f32_e32 v240, v228, v148
	v_fmac_f32_e32 v241, v230, v149
	v_fmac_f32_e32 v242, v232, v150
	v_fmac_f32_e32 v243, v234, v151
	v_fmac_f32_e32 v240, v36, v164
	v_fmac_f32_e32 v241, v37, v165
	v_fmac_f32_e32 v242, v38, v166
	v_fmac_f32_e32 v243, v39, v167
	v_mov_b32_e32 v228, 0xbdd2d3e8
	v_mul_f32_e32 v244, v236, v236
	v_mul_f32_e32 v245, v237, v237
	v_mul_f32_e32 v246, v238, v238
	v_mul_f32_e32 v247, v239, v239
	v_fmaak_f32 v244, v244, v228, 0xc0135761
	v_fmaak_f32 v245, v245, v228, 0xc0135761
	v_fmaak_f32 v246, v246, v228, 0xc0135761
	v_fmaak_f32 v247, v247, v228, 0xc0135761
	v_mul_f32_e32 v244, v236, v244
	v_mul_f32_e32 v245, v237, v245
	v_mul_f32_e32 v246, v238, v246
	v_mul_f32_e32 v247, v239, v247
	v_exp_f32_e32 v244, v244
	v_exp_f32_e32 v245, v245
	v_exp_f32_e32 v246, v246
	v_exp_f32_e32 v247, v247
	v_add_f32_e32 v244, 1.0, v244
	v_add_f32_e32 v245, 1.0, v245
	v_add_f32_e32 v246, 1.0, v246
	v_add_f32_e32 v247, 1.0, v247
	v_rcp_f32_e32 v244, v244
	v_rcp_f32_e32 v245, v245
	v_rcp_f32_e32 v246, v246
	v_rcp_f32_e32 v247, v247
	v_mul_f32_e32 v244, v236, v244
	v_mul_f32_e32 v245, v237, v245
	v_mul_f32_e32 v246, v238, v246
	v_mul_f32_e32 v247, v239, v247
	v_mul_f32_e32 v248, v240, v244
	v_mul_f32_e32 v249, v241, v245
	v_mul_f32_e32 v250, v242, v246
	v_mul_f32_e32 v251, v243, v247
	v_mov_b32_dpp v228, v56 row_ror:1 row_mask:0xf bank_mask:0xf
	v_mov_b32_dpp v229, v56 row_ror:2 row_mask:0xf bank_mask:0xf
	v_mov_b32_dpp v230, v57 row_ror:1 row_mask:0xf bank_mask:0xf
	v_mov_b32_dpp v231, v57 row_ror:2 row_mask:0xf bank_mask:0xf
	v_mov_b32_dpp v232, v58 row_ror:1 row_mask:0xf bank_mask:0xf
	v_mov_b32_dpp v233, v58 row_ror:2 row_mask:0xf bank_mask:0xf
	v_mov_b32_dpp v234, v59 row_ror:1 row_mask:0xf bank_mask:0xf
	v_mov_b32_dpp v235, v59 row_ror:2 row_mask:0xf bank_mask:0xf
	v_mov_b32_dpp v228, v40 row_shr:1 row_mask:0xf bank_mask:0xf
	v_mov_b32_dpp v229, v40 row_shr:2 row_mask:0xf bank_mask:0xf
	v_mov_b32_dpp v230, v41 row_shr:1 row_mask:0xf bank_mask:0xf
	v_mov_b32_dpp v231, v41 row_shr:2 row_mask:0xf bank_mask:0xf
	v_mov_b32_dpp v232, v42 row_shr:1 row_mask:0xf bank_mask:0xf
	v_mov_b32_dpp v233, v42 row_shr:2 row_mask:0xf bank_mask:0xf
	v_mov_b32_dpp v234, v43 row_shr:1 row_mask:0xf bank_mask:0xf
	v_mov_b32_dpp v235, v43 row_shr:2 row_mask:0xf bank_mask:0xf
	v_cndmask_b32_e64 v228, 0, v228, vcc
	v_cndmask_b32_e64 v229, 0, v229, s[8:9]
	v_cndmask_b32_e64 v230, 0, v230, vcc
	v_cndmask_b32_e64 v231, 0, v231, s[8:9]
	v_cndmask_b32_e64 v232, 0, v232, vcc
	v_cndmask_b32_e64 v233, 0, v233, s[8:9]
	v_cndmask_b32_e64 v234, 0, v234, vcc
	v_cndmask_b32_e64 v235, 0, v235, s[8:9]
	v_fma_f32 v236, v229, v136, v220
	v_fma_f32 v237, v231, v137, v221
	v_fma_f32 v238, v233, v138, v222
	v_fma_f32 v239, v235, v139, v223
	v_fmac_f32_e32 v236, v228, v152
	v_fmac_f32_e32 v237, v230, v153
	v_fmac_f32_e32 v238, v232, v154
	v_fmac_f32_e32 v239, v234, v155
	v_fmac_f32_e32 v236, v40, v168
	v_fmac_f32_e32 v237, v41, v169
	v_fmac_f32_e32 v238, v42, v170
	v_fmac_f32_e32 v239, v43, v171
	v_mov_b32_dpp v228, v48 row_ror:1 row_mask:0xf bank_mask:0xf
	v_mov_b32_dpp v229, v48 row_ror:2 row_mask:0xf bank_mask:0xf
	v_mov_b32_dpp v230, v49 row_ror:1 row_mask:0xf bank_mask:0xf
	v_mov_b32_dpp v231, v49 row_ror:2 row_mask:0xf bank_mask:0xf
	v_mov_b32_dpp v232, v50 row_ror:1 row_mask:0xf bank_mask:0xf
	v_mov_b32_dpp v233, v50 row_ror:2 row_mask:0xf bank_mask:0xf
	v_mov_b32_dpp v234, v51 row_ror:1 row_mask:0xf bank_mask:0xf
	v_mov_b32_dpp v235, v51 row_ror:2 row_mask:0xf bank_mask:0xf
	v_mov_b32_dpp v228, v32 row_shr:1 row_mask:0xf bank_mask:0xf
	v_mov_b32_dpp v229, v32 row_shr:2 row_mask:0xf bank_mask:0xf
	v_mov_b32_dpp v230, v33 row_shr:1 row_mask:0xf bank_mask:0xf
	v_mov_b32_dpp v231, v33 row_shr:2 row_mask:0xf bank_mask:0xf
	v_mov_b32_dpp v232, v34 row_shr:1 row_mask:0xf bank_mask:0xf
	v_mov_b32_dpp v233, v34 row_shr:2 row_mask:0xf bank_mask:0xf
	v_mov_b32_dpp v234, v35 row_shr:1 row_mask:0xf bank_mask:0xf
	v_mov_b32_dpp v235, v35 row_shr:2 row_mask:0xf bank_mask:0xf
	v_cndmask_b32_e64 v228, 0, v228, vcc
	v_cndmask_b32_e64 v229, 0, v229, s[8:9]
	v_cndmask_b32_e64 v230, 0, v230, vcc
	v_cndmask_b32_e64 v231, 0, v231, s[8:9]
	v_cndmask_b32_e64 v232, 0, v232, vcc
	v_cndmask_b32_e64 v233, 0, v233, s[8:9]
	v_cndmask_b32_e64 v234, 0, v234, vcc
	v_cndmask_b32_e64 v235, 0, v235, s[8:9]
	v_fma_f32 v240, v229, v140, v224
	v_fma_f32 v241, v231, v141, v225
	v_fma_f32 v242, v233, v142, v226
	v_fma_f32 v243, v235, v143, v227
	v_fmac_f32_e32 v240, v228, v156
	v_fmac_f32_e32 v241, v230, v157
	v_fmac_f32_e32 v242, v232, v158
	v_fmac_f32_e32 v243, v234, v159
	v_fmac_f32_e32 v240, v32, v204
	v_fmac_f32_e32 v241, v33, v205
	v_fmac_f32_e32 v242, v34, v206
	v_fmac_f32_e32 v243, v35, v207
	v_mov_b32_e32 v228, 0xbdd2d3e8
	v_mul_f32_e32 v244, v236, v236
	v_mul_f32_e32 v245, v237, v237
	v_mul_f32_e32 v246, v238, v238
	v_mul_f32_e32 v247, v239, v239
	v_fmaak_f32 v244, v244, v228, 0xc0135761
	v_fmaak_f32 v245, v245, v228, 0xc0135761
	v_fmaak_f32 v246, v246, v228, 0xc0135761
	v_fmaak_f32 v247, v247, v228, 0xc0135761
	v_mul_f32_e32 v244, v236, v244
	v_mul_f32_e32 v245, v237, v245
	v_mul_f32_e32 v246, v238, v246
	v_mul_f32_e32 v247, v239, v247
	v_exp_f32_e32 v244, v244
	v_exp_f32_e32 v245, v245
	v_exp_f32_e32 v246, v246
	v_exp_f32_e32 v247, v247
	v_add_f32_e32 v244, 1.0, v244
	v_add_f32_e32 v245, 1.0, v245
	v_add_f32_e32 v246, 1.0, v246
	v_add_f32_e32 v247, 1.0, v247
	v_rcp_f32_e32 v244, v244
	v_rcp_f32_e32 v245, v245
	v_rcp_f32_e32 v246, v246
	v_rcp_f32_e32 v247, v247
	v_mul_f32_e32 v244, v236, v244
	v_mul_f32_e32 v245, v237, v245
	v_mul_f32_e32 v246, v238, v246
	v_mul_f32_e32 v247, v239, v247
	v_mul_f32_e32 v174, v240, v244
	v_mul_f32_e32 v175, v241, v245
	v_mul_f32_e32 v176, v242, v246
	v_mul_f32_e32 v177, v243, v247
	v_cvt_pk_bf16_f32 v180, v248, v249
	v_cvt_pk_bf16_f32 v181, v250, v251
	v_cvt_pk_bf16_f32 v182, v174, v175
	v_cvt_pk_bf16_f32 v183, v176, v177
	s_branch .Lffn1e_store5
.Lffn1e_slow6:
	v_add_u32_e32 v189, 2160, v218
	v_mul_hi_u32 v203, v189, s59
	v_lshrrev_b32_e32 v203, 7, v203
	v_mul_u32_u24_e32 v203, 0x810, v203
	v_sub_u32_e32 v189, v189, v203
	v_cmp_lt_u32_e32 vcc, 0, v189
	v_cmp_lt_u32_e64 s[8:9], 1, v189
	s_nop 1
	v_mov_b32_dpp v228, v44 row_ror:1 row_mask:0xf bank_mask:0xf
	v_mov_b32_dpp v229, v44 row_ror:2 row_mask:0xf bank_mask:0xf
	v_mov_b32_dpp v230, v45 row_ror:1 row_mask:0xf bank_mask:0xf
	v_mov_b32_dpp v231, v45 row_ror:2 row_mask:0xf bank_mask:0xf
	v_mov_b32_dpp v232, v46 row_ror:1 row_mask:0xf bank_mask:0xf
	v_mov_b32_dpp v233, v46 row_ror:2 row_mask:0xf bank_mask:0xf
	v_mov_b32_dpp v234, v47 row_ror:1 row_mask:0xf bank_mask:0xf
	v_mov_b32_dpp v235, v47 row_ror:2 row_mask:0xf bank_mask:0xf
	v_mov_b32_dpp v228, v28 row_shr:1 row_mask:0xf bank_mask:0xf
	v_mov_b32_dpp v229, v28 row_shr:2 row_mask:0xf bank_mask:0xf
	v_mov_b32_dpp v230, v29 row_shr:1 row_mask:0xf bank_mask:0xf
	v_mov_b32_dpp v231, v29 row_shr:2 row_mask:0xf bank_mask:0xf
	v_mov_b32_dpp v232, v30 row_shr:1 row_mask:0xf bank_mask:0xf
	v_mov_b32_dpp v233, v30 row_shr:2 row_mask:0xf bank_mask:0xf
	v_mov_b32_dpp v234, v31 row_shr:1 row_mask:0xf bank_mask:0xf
	v_mov_b32_dpp v235, v31 row_shr:2 row_mask:0xf bank_mask:0xf
	v_cndmask_b32_e64 v228, 0, v228, vcc
	v_cndmask_b32_e64 v229, 0, v229, s[8:9]
	v_cndmask_b32_e64 v230, 0, v230, vcc
	v_cndmask_b32_e64 v231, 0, v231, s[8:9]
	v_cndmask_b32_e64 v232, 0, v232, vcc
	v_cndmask_b32_e64 v233, 0, v233, s[8:9]
	v_cndmask_b32_e64 v234, 0, v234, vcc
	v_cndmask_b32_e64 v235, 0, v235, s[8:9]
	v_fma_f32 v236, v229, v128, v208
	v_fma_f32 v237, v231, v129, v209
	v_fma_f32 v238, v233, v130, v210
	v_fma_f32 v239, v235, v131, v211
	v_fmac_f32_e32 v236, v228, v144
	v_fmac_f32_e32 v237, v230, v145
	v_fmac_f32_e32 v238, v232, v146
	v_fmac_f32_e32 v239, v234, v147
	v_fmac_f32_e32 v236, v28, v160
	v_fmac_f32_e32 v237, v29, v161
	v_fmac_f32_e32 v238, v30, v162
	v_fmac_f32_e32 v239, v31, v163
	v_mov_b32_dpp v228, v36 row_ror:1 row_mask:0xf bank_mask:0xf
	v_mov_b32_dpp v229, v36 row_ror:2 row_mask:0xf bank_mask:0xf
	v_mov_b32_dpp v230, v37 row_ror:1 row_mask:0xf bank_mask:0xf
	v_mov_b32_dpp v231, v37 row_ror:2 row_mask:0xf bank_mask:0xf
	v_mov_b32_dpp v232, v38 row_ror:1 row_mask:0xf bank_mask:0xf
	v_mov_b32_dpp v233, v38 row_ror:2 row_mask:0xf bank_mask:0xf
	v_mov_b32_dpp v234, v39 row_ror:1 row_mask:0xf bank_mask:0xf
	v_mov_b32_dpp v235, v39 row_ror:2 row_mask:0xf bank_mask:0xf
	v_mov_b32_dpp v228, v20 row_shr:1 row_mask:0xf bank_mask:0xf
	v_mov_b32_dpp v229, v20 row_shr:2 row_mask:0xf bank_mask:0xf
	v_mov_b32_dpp v230, v21 row_shr:1 row_mask:0xf bank_mask:0xf
	v_mov_b32_dpp v231, v21 row_shr:2 row_mask:0xf bank_mask:0xf
	v_mov_b32_dpp v232, v22 row_shr:1 row_mask:0xf bank_mask:0xf
	v_mov_b32_dpp v233, v22 row_shr:2 row_mask:0xf bank_mask:0xf
	v_mov_b32_dpp v234, v23 row_shr:1 row_mask:0xf bank_mask:0xf
	v_mov_b32_dpp v235, v23 row_shr:2 row_mask:0xf bank_mask:0xf
	v_cndmask_b32_e64 v228, 0, v228, vcc
	v_cndmask_b32_e64 v229, 0, v229, s[8:9]
	v_cndmask_b32_e64 v230, 0, v230, vcc
	v_cndmask_b32_e64 v231, 0, v231, s[8:9]
	v_cndmask_b32_e64 v232, 0, v232, vcc
	v_cndmask_b32_e64 v233, 0, v233, s[8:9]
	v_cndmask_b32_e64 v234, 0, v234, vcc
	v_cndmask_b32_e64 v235, 0, v235, s[8:9]
	v_fma_f32 v240, v229, v132, v212
	v_fma_f32 v241, v231, v133, v213
	v_fma_f32 v242, v233, v134, v214
	v_fma_f32 v243, v235, v135, v215
	v_fmac_f32_e32 v240, v228, v148
	v_fmac_f32_e32 v241, v230, v149
	v_fmac_f32_e32 v242, v232, v150
	v_fmac_f32_e32 v243, v234, v151
	v_fmac_f32_e32 v240, v20, v164
	v_fmac_f32_e32 v241, v21, v165
	v_fmac_f32_e32 v242, v22, v166
	v_fmac_f32_e32 v243, v23, v167
	v_mov_b32_e32 v228, 0xbdd2d3e8
	v_mul_f32_e32 v244, v236, v236
	v_mul_f32_e32 v245, v237, v237
	v_mul_f32_e32 v246, v238, v238
	v_mul_f32_e32 v247, v239, v239
	v_fmaak_f32 v244, v244, v228, 0xc0135761
	v_fmaak_f32 v245, v245, v228, 0xc0135761
	v_fmaak_f32 v246, v246, v228, 0xc0135761
	v_fmaak_f32 v247, v247, v228, 0xc0135761
	v_mul_f32_e32 v244, v236, v244
	v_mul_f32_e32 v245, v237, v245
	v_mul_f32_e32 v246, v238, v246
	v_mul_f32_e32 v247, v239, v247
	v_exp_f32_e32 v244, v244
	v_exp_f32_e32 v245, v245
	v_exp_f32_e32 v246, v246
	v_exp_f32_e32 v247, v247
	v_add_f32_e32 v244, 1.0, v244
	v_add_f32_e32 v245, 1.0, v245
	v_add_f32_e32 v246, 1.0, v246
	v_add_f32_e32 v247, 1.0, v247
	v_rcp_f32_e32 v244, v244
	v_rcp_f32_e32 v245, v245
	v_rcp_f32_e32 v246, v246
	v_rcp_f32_e32 v247, v247
	v_mul_f32_e32 v244, v236, v244
	v_mul_f32_e32 v245, v237, v245
	v_mul_f32_e32 v246, v238, v246
	v_mul_f32_e32 v247, v239, v247
	v_mul_f32_e32 v248, v240, v244
	v_mul_f32_e32 v249, v241, v245
	v_mul_f32_e32 v250, v242, v246
	v_mul_f32_e32 v251, v243, v247
	v_mov_b32_dpp v228, v40 row_ror:1 row_mask:0xf bank_mask:0xf
	v_mov_b32_dpp v229, v40 row_ror:2 row_mask:0xf bank_mask:0xf
	v_mov_b32_dpp v230, v41 row_ror:1 row_mask:0xf bank_mask:0xf
	v_mov_b32_dpp v231, v41 row_ror:2 row_mask:0xf bank_mask:0xf
	v_mov_b32_dpp v232, v42 row_ror:1 row_mask:0xf bank_mask:0xf
	v_mov_b32_dpp v233, v42 row_ror:2 row_mask:0xf bank_mask:0xf
	v_mov_b32_dpp v234, v43 row_ror:1 row_mask:0xf bank_mask:0xf
	v_mov_b32_dpp v235, v43 row_ror:2 row_mask:0xf bank_mask:0xf
	v_mov_b32_dpp v228, v24 row_shr:1 row_mask:0xf bank_mask:0xf
	v_mov_b32_dpp v229, v24 row_shr:2 row_mask:0xf bank_mask:0xf
	v_mov_b32_dpp v230, v25 row_shr:1 row_mask:0xf bank_mask:0xf
	v_mov_b32_dpp v231, v25 row_shr:2 row_mask:0xf bank_mask:0xf
	v_mov_b32_dpp v232, v26 row_shr:1 row_mask:0xf bank_mask:0xf
	v_mov_b32_dpp v233, v26 row_shr:2 row_mask:0xf bank_mask:0xf
	v_mov_b32_dpp v234, v27 row_shr:1 row_mask:0xf bank_mask:0xf
	v_mov_b32_dpp v235, v27 row_shr:2 row_mask:0xf bank_mask:0xf
	v_cndmask_b32_e64 v228, 0, v228, vcc
	v_cndmask_b32_e64 v229, 0, v229, s[8:9]
	v_cndmask_b32_e64 v230, 0, v230, vcc
	v_cndmask_b32_e64 v231, 0, v231, s[8:9]
	v_cndmask_b32_e64 v232, 0, v232, vcc
	v_cndmask_b32_e64 v233, 0, v233, s[8:9]
	v_cndmask_b32_e64 v234, 0, v234, vcc
	v_cndmask_b32_e64 v235, 0, v235, s[8:9]
	v_fma_f32 v236, v229, v136, v220
	v_fma_f32 v237, v231, v137, v221
	v_fma_f32 v238, v233, v138, v222
	v_fma_f32 v239, v235, v139, v223
	v_fmac_f32_e32 v236, v228, v152
	v_fmac_f32_e32 v237, v230, v153
	v_fmac_f32_e32 v238, v232, v154
	v_fmac_f32_e32 v239, v234, v155
	v_fmac_f32_e32 v236, v24, v168
	v_fmac_f32_e32 v237, v25, v169
	v_fmac_f32_e32 v238, v26, v170
	v_fmac_f32_e32 v239, v27, v171
	v_mov_b32_dpp v228, v32 row_ror:1 row_mask:0xf bank_mask:0xf
	v_mov_b32_dpp v229, v32 row_ror:2 row_mask:0xf bank_mask:0xf
	v_mov_b32_dpp v230, v33 row_ror:1 row_mask:0xf bank_mask:0xf
	v_mov_b32_dpp v231, v33 row_ror:2 row_mask:0xf bank_mask:0xf
	v_mov_b32_dpp v232, v34 row_ror:1 row_mask:0xf bank_mask:0xf
	v_mov_b32_dpp v233, v34 row_ror:2 row_mask:0xf bank_mask:0xf
	v_mov_b32_dpp v234, v35 row_ror:1 row_mask:0xf bank_mask:0xf
	v_mov_b32_dpp v235, v35 row_ror:2 row_mask:0xf bank_mask:0xf
	v_mov_b32_dpp v228, v16 row_shr:1 row_mask:0xf bank_mask:0xf
	v_mov_b32_dpp v229, v16 row_shr:2 row_mask:0xf bank_mask:0xf
	v_mov_b32_dpp v230, v17 row_shr:1 row_mask:0xf bank_mask:0xf
	v_mov_b32_dpp v231, v17 row_shr:2 row_mask:0xf bank_mask:0xf
	v_mov_b32_dpp v232, v18 row_shr:1 row_mask:0xf bank_mask:0xf
	v_mov_b32_dpp v233, v18 row_shr:2 row_mask:0xf bank_mask:0xf
	v_mov_b32_dpp v234, v19 row_shr:1 row_mask:0xf bank_mask:0xf
	v_mov_b32_dpp v235, v19 row_shr:2 row_mask:0xf bank_mask:0xf
	v_cndmask_b32_e64 v228, 0, v228, vcc
	v_cndmask_b32_e64 v229, 0, v229, s[8:9]
	v_cndmask_b32_e64 v230, 0, v230, vcc
	v_cndmask_b32_e64 v231, 0, v231, s[8:9]
	v_cndmask_b32_e64 v232, 0, v232, vcc
	v_cndmask_b32_e64 v233, 0, v233, s[8:9]
	v_cndmask_b32_e64 v234, 0, v234, vcc
	v_cndmask_b32_e64 v235, 0, v235, s[8:9]
	v_fma_f32 v240, v229, v140, v224
	v_fma_f32 v241, v231, v141, v225
	v_fma_f32 v242, v233, v142, v226
	v_fma_f32 v243, v235, v143, v227
	v_fmac_f32_e32 v240, v228, v156
	v_fmac_f32_e32 v241, v230, v157
	v_fmac_f32_e32 v242, v232, v158
	v_fmac_f32_e32 v243, v234, v159
	v_fmac_f32_e32 v240, v16, v204
	v_fmac_f32_e32 v241, v17, v205
	v_fmac_f32_e32 v242, v18, v206
	v_fmac_f32_e32 v243, v19, v207
	v_mov_b32_e32 v228, 0xbdd2d3e8
	v_mul_f32_e32 v244, v236, v236
	v_mul_f32_e32 v245, v237, v237
	v_mul_f32_e32 v246, v238, v238
	v_mul_f32_e32 v247, v239, v239
	v_fmaak_f32 v244, v244, v228, 0xc0135761
	v_fmaak_f32 v245, v245, v228, 0xc0135761
	v_fmaak_f32 v246, v246, v228, 0xc0135761
	v_fmaak_f32 v247, v247, v228, 0xc0135761
	v_mul_f32_e32 v244, v236, v244
	v_mul_f32_e32 v245, v237, v245
	v_mul_f32_e32 v246, v238, v246
	v_mul_f32_e32 v247, v239, v247
	v_exp_f32_e32 v244, v244
	v_exp_f32_e32 v245, v245
	v_exp_f32_e32 v246, v246
	v_exp_f32_e32 v247, v247
	v_add_f32_e32 v244, 1.0, v244
	v_add_f32_e32 v245, 1.0, v245
	v_add_f32_e32 v246, 1.0, v246
	v_add_f32_e32 v247, 1.0, v247
	v_rcp_f32_e32 v244, v244
	v_rcp_f32_e32 v245, v245
	v_rcp_f32_e32 v246, v246
	v_rcp_f32_e32 v247, v247
	v_mul_f32_e32 v244, v236, v244
	v_mul_f32_e32 v245, v237, v245
	v_mul_f32_e32 v246, v238, v246
	v_mul_f32_e32 v247, v239, v247
	v_mul_f32_e32 v174, v240, v244
	v_mul_f32_e32 v175, v241, v245
	v_mul_f32_e32 v176, v242, v246
	v_mul_f32_e32 v177, v243, v247
	v_cvt_pk_bf16_f32 v180, v248, v249
	v_cvt_pk_bf16_f32 v181, v250, v251
	v_cvt_pk_bf16_f32 v182, v174, v175
	v_cvt_pk_bf16_f32 v183, v176, v177
	s_branch .Lffn1e_store6
.Lffn1e_slow7:
	v_add_u32_e32 v189, 2176, v218
	v_mul_hi_u32 v203, v189, s59
	v_lshrrev_b32_e32 v203, 7, v203
	v_mul_u32_u24_e32 v203, 0x810, v203
	v_sub_u32_e32 v189, v189, v203
	v_cmp_lt_u32_e32 vcc, 0, v189
	v_cmp_lt_u32_e64 s[8:9], 1, v189
	s_nop 1
	v_mov_b32_dpp v228, v28 row_ror:1 row_mask:0xf bank_mask:0xf
	v_mov_b32_dpp v229, v28 row_ror:2 row_mask:0xf bank_mask:0xf
	v_mov_b32_dpp v230, v29 row_ror:1 row_mask:0xf bank_mask:0xf
	v_mov_b32_dpp v231, v29 row_ror:2 row_mask:0xf bank_mask:0xf
	v_mov_b32_dpp v232, v30 row_ror:1 row_mask:0xf bank_mask:0xf
	v_mov_b32_dpp v233, v30 row_ror:2 row_mask:0xf bank_mask:0xf
	v_mov_b32_dpp v234, v31 row_ror:1 row_mask:0xf bank_mask:0xf
	v_mov_b32_dpp v235, v31 row_ror:2 row_mask:0xf bank_mask:0xf
	v_mov_b32_dpp v228, v4 row_shr:1 row_mask:0xf bank_mask:0xf
	v_mov_b32_dpp v229, v4 row_shr:2 row_mask:0xf bank_mask:0xf
	v_mov_b32_dpp v230, v5 row_shr:1 row_mask:0xf bank_mask:0xf
	v_mov_b32_dpp v231, v5 row_shr:2 row_mask:0xf bank_mask:0xf
	v_mov_b32_dpp v232, v6 row_shr:1 row_mask:0xf bank_mask:0xf
	v_mov_b32_dpp v233, v6 row_shr:2 row_mask:0xf bank_mask:0xf
	v_mov_b32_dpp v234, v7 row_shr:1 row_mask:0xf bank_mask:0xf
	v_mov_b32_dpp v235, v7 row_shr:2 row_mask:0xf bank_mask:0xf
	v_cndmask_b32_e64 v228, 0, v228, vcc
	v_cndmask_b32_e64 v229, 0, v229, s[8:9]
	v_cndmask_b32_e64 v230, 0, v230, vcc
	v_cndmask_b32_e64 v231, 0, v231, s[8:9]
	v_cndmask_b32_e64 v232, 0, v232, vcc
	v_cndmask_b32_e64 v233, 0, v233, s[8:9]
	v_cndmask_b32_e64 v234, 0, v234, vcc
	v_cndmask_b32_e64 v235, 0, v235, s[8:9]
	v_fma_f32 v236, v229, v128, v208
	v_fma_f32 v237, v231, v129, v209
	v_fma_f32 v238, v233, v130, v210
	v_fma_f32 v239, v235, v131, v211
	v_fmac_f32_e32 v236, v228, v144
	v_fmac_f32_e32 v237, v230, v145
	v_fmac_f32_e32 v238, v232, v146
	v_fmac_f32_e32 v239, v234, v147
	v_fmac_f32_e32 v236, v4, v160
	v_fmac_f32_e32 v237, v5, v161
	v_fmac_f32_e32 v238, v6, v162
	v_fmac_f32_e32 v239, v7, v163
	v_mov_b32_dpp v228, v20 row_ror:1 row_mask:0xf bank_mask:0xf
	v_mov_b32_dpp v229, v20 row_ror:2 row_mask:0xf bank_mask:0xf
	v_mov_b32_dpp v230, v21 row_ror:1 row_mask:0xf bank_mask:0xf
	v_mov_b32_dpp v231, v21 row_ror:2 row_mask:0xf bank_mask:0xf
	v_mov_b32_dpp v232, v22 row_ror:1 row_mask:0xf bank_mask:0xf
	v_mov_b32_dpp v233, v22 row_ror:2 row_mask:0xf bank_mask:0xf
	v_mov_b32_dpp v234, v23 row_ror:1 row_mask:0xf bank_mask:0xf
	v_mov_b32_dpp v235, v23 row_ror:2 row_mask:0xf bank_mask:0xf
	v_mov_b32_dpp v228, v8 row_shr:1 row_mask:0xf bank_mask:0xf
	v_mov_b32_dpp v229, v8 row_shr:2 row_mask:0xf bank_mask:0xf
	v_mov_b32_dpp v230, v9 row_shr:1 row_mask:0xf bank_mask:0xf
	v_mov_b32_dpp v231, v9 row_shr:2 row_mask:0xf bank_mask:0xf
	v_mov_b32_dpp v232, v10 row_shr:1 row_mask:0xf bank_mask:0xf
	v_mov_b32_dpp v233, v10 row_shr:2 row_mask:0xf bank_mask:0xf
	v_mov_b32_dpp v234, v11 row_shr:1 row_mask:0xf bank_mask:0xf
	v_mov_b32_dpp v235, v11 row_shr:2 row_mask:0xf bank_mask:0xf
	v_cndmask_b32_e64 v228, 0, v228, vcc
	v_cndmask_b32_e64 v229, 0, v229, s[8:9]
	v_cndmask_b32_e64 v230, 0, v230, vcc
	v_cndmask_b32_e64 v231, 0, v231, s[8:9]
	v_cndmask_b32_e64 v232, 0, v232, vcc
	v_cndmask_b32_e64 v233, 0, v233, s[8:9]
	v_cndmask_b32_e64 v234, 0, v234, vcc
	v_cndmask_b32_e64 v235, 0, v235, s[8:9]
	v_fma_f32 v240, v229, v132, v212
	v_fma_f32 v241, v231, v133, v213
	v_fma_f32 v242, v233, v134, v214
	v_fma_f32 v243, v235, v135, v215
	v_fmac_f32_e32 v240, v228, v148
	v_fmac_f32_e32 v241, v230, v149
	v_fmac_f32_e32 v242, v232, v150
	v_fmac_f32_e32 v243, v234, v151
	v_fmac_f32_e32 v240, v8, v164
	v_fmac_f32_e32 v241, v9, v165
	v_fmac_f32_e32 v242, v10, v166
	v_fmac_f32_e32 v243, v11, v167
	v_mov_b32_e32 v228, 0xbdd2d3e8
	v_mul_f32_e32 v244, v236, v236
	v_mul_f32_e32 v245, v237, v237
	v_mul_f32_e32 v246, v238, v238
	v_mul_f32_e32 v247, v239, v239
	v_fmaak_f32 v244, v244, v228, 0xc0135761
	v_fmaak_f32 v245, v245, v228, 0xc0135761
	v_fmaak_f32 v246, v246, v228, 0xc0135761
	v_fmaak_f32 v247, v247, v228, 0xc0135761
	v_mul_f32_e32 v244, v236, v244
	v_mul_f32_e32 v245, v237, v245
	v_mul_f32_e32 v246, v238, v246
	v_mul_f32_e32 v247, v239, v247
	v_exp_f32_e32 v244, v244
	v_exp_f32_e32 v245, v245
	v_exp_f32_e32 v246, v246
	v_exp_f32_e32 v247, v247
	v_add_f32_e32 v244, 1.0, v244
	v_add_f32_e32 v245, 1.0, v245
	v_add_f32_e32 v246, 1.0, v246
	v_add_f32_e32 v247, 1.0, v247
	v_rcp_f32_e32 v244, v244
	v_rcp_f32_e32 v245, v245
	v_rcp_f32_e32 v246, v246
	v_rcp_f32_e32 v247, v247
	v_mul_f32_e32 v244, v236, v244
	v_mul_f32_e32 v245, v237, v245
	v_mul_f32_e32 v246, v238, v246
	v_mul_f32_e32 v247, v239, v247
	v_mul_f32_e32 v248, v240, v244
	v_mul_f32_e32 v249, v241, v245
	v_mul_f32_e32 v250, v242, v246
	v_mul_f32_e32 v251, v243, v247
	v_mov_b32_dpp v228, v24 row_ror:1 row_mask:0xf bank_mask:0xf
	v_mov_b32_dpp v229, v24 row_ror:2 row_mask:0xf bank_mask:0xf
	v_mov_b32_dpp v230, v25 row_ror:1 row_mask:0xf bank_mask:0xf
	v_mov_b32_dpp v231, v25 row_ror:2 row_mask:0xf bank_mask:0xf
	v_mov_b32_dpp v232, v26 row_ror:1 row_mask:0xf bank_mask:0xf
	v_mov_b32_dpp v233, v26 row_ror:2 row_mask:0xf bank_mask:0xf
	v_mov_b32_dpp v234, v27 row_ror:1 row_mask:0xf bank_mask:0xf
	v_mov_b32_dpp v235, v27 row_ror:2 row_mask:0xf bank_mask:0xf
	v_mov_b32_dpp v228, v12 row_shr:1 row_mask:0xf bank_mask:0xf
	v_mov_b32_dpp v229, v12 row_shr:2 row_mask:0xf bank_mask:0xf
	v_mov_b32_dpp v230, v13 row_shr:1 row_mask:0xf bank_mask:0xf
	v_mov_b32_dpp v231, v13 row_shr:2 row_mask:0xf bank_mask:0xf
	v_mov_b32_dpp v232, v14 row_shr:1 row_mask:0xf bank_mask:0xf
	v_mov_b32_dpp v233, v14 row_shr:2 row_mask:0xf bank_mask:0xf
	v_mov_b32_dpp v234, v15 row_shr:1 row_mask:0xf bank_mask:0xf
	v_mov_b32_dpp v235, v15 row_shr:2 row_mask:0xf bank_mask:0xf
	v_cndmask_b32_e64 v228, 0, v228, vcc
	v_cndmask_b32_e64 v229, 0, v229, s[8:9]
	v_cndmask_b32_e64 v230, 0, v230, vcc
	v_cndmask_b32_e64 v231, 0, v231, s[8:9]
	v_cndmask_b32_e64 v232, 0, v232, vcc
	v_cndmask_b32_e64 v233, 0, v233, s[8:9]
	v_cndmask_b32_e64 v234, 0, v234, vcc
	v_cndmask_b32_e64 v235, 0, v235, s[8:9]
	v_fma_f32 v236, v229, v136, v220
	v_fma_f32 v237, v231, v137, v221
	v_fma_f32 v238, v233, v138, v222
	v_fma_f32 v239, v235, v139, v223
	v_fmac_f32_e32 v236, v228, v152
	v_fmac_f32_e32 v237, v230, v153
	v_fmac_f32_e32 v238, v232, v154
	v_fmac_f32_e32 v239, v234, v155
	v_fmac_f32_e32 v236, v12, v168
	v_fmac_f32_e32 v237, v13, v169
	v_fmac_f32_e32 v238, v14, v170
	v_fmac_f32_e32 v239, v15, v171
	v_mov_b32_dpp v228, v16 row_ror:1 row_mask:0xf bank_mask:0xf
	v_mov_b32_dpp v229, v16 row_ror:2 row_mask:0xf bank_mask:0xf
	v_mov_b32_dpp v230, v17 row_ror:1 row_mask:0xf bank_mask:0xf
	v_mov_b32_dpp v231, v17 row_ror:2 row_mask:0xf bank_mask:0xf
	v_mov_b32_dpp v232, v18 row_ror:1 row_mask:0xf bank_mask:0xf
	v_mov_b32_dpp v233, v18 row_ror:2 row_mask:0xf bank_mask:0xf
	v_mov_b32_dpp v234, v19 row_ror:1 row_mask:0xf bank_mask:0xf
	v_mov_b32_dpp v235, v19 row_ror:2 row_mask:0xf bank_mask:0xf
	v_mov_b32_dpp v228, v0 row_shr:1 row_mask:0xf bank_mask:0xf
	v_mov_b32_dpp v229, v0 row_shr:2 row_mask:0xf bank_mask:0xf
	v_mov_b32_dpp v230, v1 row_shr:1 row_mask:0xf bank_mask:0xf
	v_mov_b32_dpp v231, v1 row_shr:2 row_mask:0xf bank_mask:0xf
	v_mov_b32_dpp v232, v2 row_shr:1 row_mask:0xf bank_mask:0xf
	v_mov_b32_dpp v233, v2 row_shr:2 row_mask:0xf bank_mask:0xf
	v_mov_b32_dpp v234, v3 row_shr:1 row_mask:0xf bank_mask:0xf
	v_mov_b32_dpp v235, v3 row_shr:2 row_mask:0xf bank_mask:0xf
	v_cndmask_b32_e64 v228, 0, v228, vcc
	v_cndmask_b32_e64 v229, 0, v229, s[8:9]
	v_cndmask_b32_e64 v230, 0, v230, vcc
	v_cndmask_b32_e64 v231, 0, v231, s[8:9]
	v_cndmask_b32_e64 v232, 0, v232, vcc
	v_cndmask_b32_e64 v233, 0, v233, s[8:9]
	v_cndmask_b32_e64 v234, 0, v234, vcc
	v_cndmask_b32_e64 v235, 0, v235, s[8:9]
	v_fma_f32 v240, v229, v140, v224
	v_fma_f32 v241, v231, v141, v225
	v_fma_f32 v242, v233, v142, v226
	v_fma_f32 v243, v235, v143, v227
	v_fmac_f32_e32 v240, v228, v156
	v_fmac_f32_e32 v241, v230, v157
	v_fmac_f32_e32 v242, v232, v158
	v_fmac_f32_e32 v243, v234, v159
	v_fmac_f32_e32 v240, v0, v204
	v_fmac_f32_e32 v241, v1, v205
	v_fmac_f32_e32 v242, v2, v206
	v_fmac_f32_e32 v243, v3, v207
	v_mov_b32_e32 v228, 0xbdd2d3e8
	v_mul_f32_e32 v244, v236, v236
	v_mul_f32_e32 v245, v237, v237
	v_mul_f32_e32 v246, v238, v238
	v_mul_f32_e32 v247, v239, v239
	v_fmaak_f32 v244, v244, v228, 0xc0135761
	v_fmaak_f32 v245, v245, v228, 0xc0135761
	v_fmaak_f32 v246, v246, v228, 0xc0135761
	v_fmaak_f32 v247, v247, v228, 0xc0135761
	v_mul_f32_e32 v244, v236, v244
	v_mul_f32_e32 v245, v237, v245
	v_mul_f32_e32 v246, v238, v246
	v_mul_f32_e32 v247, v239, v247
	v_exp_f32_e32 v244, v244
	v_exp_f32_e32 v245, v245
	v_exp_f32_e32 v246, v246
	v_exp_f32_e32 v247, v247
	v_add_f32_e32 v244, 1.0, v244
	v_add_f32_e32 v245, 1.0, v245
	v_add_f32_e32 v246, 1.0, v246
	v_add_f32_e32 v247, 1.0, v247
	v_rcp_f32_e32 v244, v244
	v_rcp_f32_e32 v245, v245
	v_rcp_f32_e32 v246, v246
	v_rcp_f32_e32 v247, v247
	v_mul_f32_e32 v244, v236, v244
	v_mul_f32_e32 v245, v237, v245
	v_mul_f32_e32 v246, v238, v246
	v_mul_f32_e32 v247, v239, v247
	v_mul_f32_e32 v174, v240, v244
	v_mul_f32_e32 v175, v241, v245
	v_mul_f32_e32 v176, v242, v246
	v_mul_f32_e32 v177, v243, v247
	v_cvt_pk_bf16_f32 v180, v248, v249
	v_cvt_pk_bf16_f32 v181, v250, v251
	v_cvt_pk_bf16_f32 v182, v174, v175
	v_cvt_pk_bf16_f32 v183, v176, v177
	s_branch .Lffn1e_store7
